# LDS-DMA loads with simple SGPR-base addresses use the saddr form (no 64-bit VALU add in the load segment); missing wait state between m0 write and first LDS-DMA of each unit restored
# speedup vs baseline: 1.0116x; 1.0116x over previous
; #define PG8_STAGE(bufoff, gbase, voff) do { _Pragma("unroll") for (int _i = 0; _i < 2; ++_i) \
;         __builtin_amdgcn_global_load_lds((const unsigned*)((const char*)(gbase) + (voff)[_i]), (PG8_LAS unsigned*)(lds + (bufoff) + ldsw + _i * 8192), 16, 0, 0); } while (0)
; #define PG8_WAIT_V(n) asm volatile("s_waitcnt vmcnt(" #n ")" ::: "memory")
; #define PG8_BAR __builtin_amdgcn_s_barrier()
; template <class Epi, class Sched, bool ALIGN_EPI = false, bool SP2 = false>
; __device__ __forceinline__ void gemm_phase(PG8_LAS unsigned char* lds, const Gemm g, const Sched& S, const Epi& E) {
;     const int tid = threadIdx.x, wid = __builtin_amdgcn_readfirstlane(tid >> 6), lane = tid & 63, wr = wid >> 2, wc = wid & 3, fr = lane & 15, fq = lane >> 4;
;     const int K = g.K, nt = K / BK;
;     unsigned voffA[2], voffB[2];
; #pragma unroll
;     for (int i = 0; i < 2; ++i) { int R, C; stage_rc(tid * 16 + i * 8192, R, C); const int Rb = Epi::PERM ? ((R & ~31) + perm32(R & 31)) : R;
;         voffA[i] = (unsigned)(R * K + C) * 2u; voffB[i] = (unsigned)(Rb * K + C) * 2u; }
;     const size_t kstep = (size_t)(BK * 2);
;     const size_t hstep = (size_t)HALF * K * 2;
;     const size_t tstep = 2 * hstep;
;     const unsigned ldsw = (unsigned)wid * 1024u;
;     const int aoff = lds_byte(wr * 64 + fr, fq * 8), boff = lds_byte(wc * 32 + fr, fq * 8);
;     ...
;         PG8_STAGE(PG8_SB(1, 0), cB + kstep, voffB); PG8_STAGE(PG8_SA(1, 0), cA + kstep, voffA); PG8_STAGE(PG8_SB(1, 1), cB + hstep + kstep, voffB);
;         PG8_WAIT_V(6); PG8_BAR;
.LBB0_331:
	s_add_u32 s6, s90, 0x12500000
	s_addc_u32 s7, s91, 0
	s_lshl_b32 s8, s8, 5
	s_and_b32 s16, s8, 0x60
	s_mov_b64 s[8:9], 0x80
	s_add_i32 m0, s23, 0x18000
	v_lshl_add_u64 v[6:7], v[6:7], 0, s[8:9]
	s_lshl_b32 s13, s1, 13
	s_lshl_b32 s17, s16, 7
	s_waitcnt vmcnt(2)
	s_barrier
	global_load_lds_dwordx4 v[6:7], off
	v_lshl_add_u64 v[4:5], v[4:5], 0, s[8:9]
	s_add_i32 m0, s23, 0x1a000
	s_add_i32 s42, s23, 0x8000
	s_add_i32 s43, s23, 0xa000
	global_load_lds_dwordx4 v[4:5], off
	v_lshl_add_u64 v[0:1], v[0:1], 0, s[8:9]
	s_mov_b32 m0, s42
	s_add_u32 s14, s26, 0x40080
	global_load_lds_dwordx4 v[0:1], off
	v_lshl_add_u64 v[0:1], v[2:3], 0, s[8:9]
	s_mov_b32 m0, s43
	s_addc_u32 s15, s27, 0
	global_load_lds_dwordx4 v[0:1], off
	s_add_i32 m0, s23, 0x1c000
	s_nop 0
	global_load_lds_dwordx4 v132, s[14:15]
	v_lshl_add_u64 v[0:1], s[14:15], 0, v[128:129]
	s_add_i32 m0, s23, 0x1e000
	s_sext_i32_i16 s49, s0
	global_load_lds_dwordx4 v[0:1], off
	v_and_b32_e32 v0, 15, v254
	v_lshlrev_b32_e32 v1, 1, v12
	v_lshl_or_b32 v144, s1, 6, v0
	v_lshl_or_b32 v2, v0, 6, v1
	v_lshlrev_b32_e32 v0, 2, v0
	v_and_b32_e32 v3, 32, v0
	v_bitop3_b32 v2, v2, s13, v3 bitop3:0xde
	v_lshlrev_b32_e32 v3, 6, v254
	s_movk_i32 s0, 0x3c0
	s_cmpk_lt_u32 s12, 0x100
	v_and_or_b32 v1, v3, s0, v1
	s_cselect_b64 s[12:13], -1, 0
	s_lshl_b32 s0, s1, 8
	s_add_i32 s0, s0, 0
	s_add_i32 s0, s0, 0x20000
	v_and_b32_e32 v3, 32, v8
	v_add_u32_e32 v147, s0, v0
	v_lshlrev_b32_e32 v0, 8, v254
	v_bitop3_b32 v145, s17, v1, v3 bitop3:0xf6
	v_and_b32_e32 v0, 0x38000, v0
	v_lshlrev_b32_e32 v1, 11, v13
	v_or3_b32 v0, v10, v0, v1
	v_add_u32_e32 v136, v0, v11
	v_lshlrev_b32_e32 v0, 4, v9
	s_waitcnt vmcnt(6)
	v_and_b32_e32 v0, 0x78000, v0
	v_or3_b32 v0, v10, v0, v1
	s_add_i32 s44, 0, 0x10000
	s_add_i32 s45, 0, 0x14000
	v_or_b32_e32 v146, s16, v12
	v_mov_b32_e32 v137, v133
	v_add_u32_e32 v138, v0, v11
	v_mov_b32_e32 v139, v133
	v_mov_b64_e32 v[140:141], 0xb00
	v_mov_b64_e32 v[142:143], 0xaff
	v_add_u32_e32 v148, s44, v145
	v_add_u32_e32 v149, s45, v145
	v_add_u32_e32 v150, 0, v2
	s_movk_i32 s46, 0x1600
	s_barrier
	s_waitcnt vmcnt(0)
	s_branch .LBB0_334

; #define PG8_STAGE(bufoff, gbase, voff) do { _Pragma("unroll") for (int _i = 0; _i < 2; ++_i) \
;         __builtin_amdgcn_global_load_lds((const unsigned*)((const char*)(gbase) + (voff)[_i]), (PG8_LAS unsigned*)(lds + (bufoff) + ldsw + _i * 8192), 16, 0, 0); } while (0)
; #define PG8_LDA(dst, b, h) do { _Pragma("unroll") for (int m = 0; m < 4; ++m) _Pragma("unroll") for (int k = 0; k < 2; ++k) dst[m][k] = *(const PG8_LAS bf16x8*)(lds + PG8_SA(b, h) + aoff + m * 2048 + k * 1024); } while (0)
; #define PG8_LDB(dst, b, h) do { _Pragma("unroll") for (int n = 0; n < 2; ++n) _Pragma("unroll") for (int k = 0; k < 2; ++k) dst[n][k] = *(const PG8_LAS bf16x8*)(lds + PG8_SB(b, h) + boff + n * 2048 + k * 1024); } while (0)
; #define PG8_MMA(ai, bj, At, Bt) do { __builtin_amdgcn_s_setprio(1); _Pragma("unroll") for (int m = 0; m < 4; ++m) _Pragma("unroll") for (int n = 0; n < 2; ++n) _Pragma("unroll") for (int k = 0; k < 2; ++k) \
;         acc[ai][bj][m][n] = __builtin_amdgcn_mfma_f32_16x16x32_bf16(Bt[n][k], At[m][k], acc[ai][bj][m][n], 0, 0, 0); __builtin_amdgcn_s_setprio(0); } while (0)
; #define PG8_WAIT_V(n) asm volatile("s_waitcnt vmcnt(" #n ")" ::: "memory")
; #define PG8_WAIT_L(n) asm volatile("s_waitcnt lgkmcnt(" #n ")" ::: "memory")
; #define PG8_BAR __builtin_amdgcn_s_barrier()
; #define PG8_SCHED __builtin_amdgcn_sched_barrier(0)
; template <class Epi, class Sched, bool ALIGN_EPI = false, bool SP2 = false>
; __device__ __forceinline__ void gemm_phase(PG8_LAS unsigned char* lds, const Gemm g, const Sched& S, const Epi& E) {
;     ...
;             PG8_LDB(B0, 0, 0); PG8_LDB(B1, 0, 1); PG8_SCHED; PG8_LDA(At, 0, 0); PG8_STAGE(PG8_SA(1, 1), a1 + hstep, voffA);
;             PG8_WAIT_V(8); PG8_WAIT_L(0); PG8_BAR; PG8_MMA(0, 0, At, B0); PG8_MMA(0, 1, At, B1); PG8_BAR; PG8_SCHED;
;             PG8_LDA(At, 0, 1); PG8_STAGE(PG8_SB(0, 0), b2, voffB); PG8_STAGE(PG8_SB(0, 1), b2 + hstep, voffB); PG8_STAGE(PG8_SA(0, 0), a2, voffA);
;             PG8_WAIT_V(8); PG8_WAIT_L(0); PG8_BAR; PG8_MMA(1, 0, At, B0); PG8_MMA(1, 1, At, B1); PG8_BAR; PG8_SCHED;
.LBB0_336:
	s_ashr_i32 s17, s16, 31
	s_lshl_b64 s[18:19], s[16:17], 19
	s_add_u32 s18, s36, s18
	s_addc_u32 s19, s37, s19
	s_and_b64 s[20:21], s[0:1], exec
	s_cselect_b32 s17, s19, s25
	s_cselect_b32 s50, s18, s24
	s_ashr_i32 s15, s14, 31
	s_lshl_b64 s[20:21], s[14:15], 19
	s_add_u32 s20, s34, s20
	s_addc_u32 s21, s35, s21
	s_and_b64 s[28:29], s[0:1], exec
	s_cselect_b32 s15, s21, s27
	s_cselect_b32 s51, s20, s26
	s_add_u32 s24, s24, 0x40080
	s_addc_u32 s25, s25, 0
	s_add_u32 s52, s26, 0x100
	s_addc_u32 s53, s27, 0
	s_mov_b32 s54, -2
	s_add_u32 s26, s24, 0xfffc0080
	s_addc_u32 s27, s25, -1
	s_cmp_eq_u32 s54, 12
	s_cselect_b32 s29, s17, s27
	s_cselect_b32 s28, s50, s26
	s_cselect_b32 s27, s15, s53
	s_cselect_b32 s26, s51, s52
	s_add_i32 m0, s23, 0xc000
	s_nop 0
	global_load_lds_dwordx4 v136, s[24:25]
	s_add_i32 m0, s23, 0xe000
	s_nop 0
	global_load_lds_dwordx4 v138, s[24:25]
	s_waitcnt vmcnt(8)
	s_waitcnt lgkmcnt(0)
	s_setprio 1
	s_barrier
	v_mfma_f32_16x16x32_bf16 v[124:127], v[152:155], v[184:187], 0
	v_mfma_f32_16x16x32_bf16 v[120:123], v[160:163], v[184:187], 0
	v_mfma_f32_16x16x32_bf16 v[108:111], v[152:155], v[192:195], 0
	v_mfma_f32_16x16x32_bf16 v[104:107], v[160:163], v[192:195], 0
	v_mfma_f32_16x16x32_bf16 v[92:95], v[152:155], v[200:203], 0
	v_mfma_f32_16x16x32_bf16 v[88:91], v[160:163], v[200:203], 0
	v_mfma_f32_16x16x32_bf16 v[76:79], v[152:155], v[208:211], 0
	v_mfma_f32_16x16x32_bf16 v[72:75], v[160:163], v[208:211], 0
	v_mfma_f32_16x16x32_bf16 v[124:127], v[156:159], v[188:191], v[124:127]
	v_mfma_f32_16x16x32_bf16 v[120:123], v[164:167], v[188:191], v[120:123]
	v_mfma_f32_16x16x32_bf16 v[108:111], v[156:159], v[196:199], v[108:111]
	v_mfma_f32_16x16x32_bf16 v[104:107], v[164:167], v[196:199], v[104:107]
	v_mfma_f32_16x16x32_bf16 v[92:95], v[156:159], v[204:207], v[92:95]
	v_mfma_f32_16x16x32_bf16 v[88:91], v[164:167], v[204:207], v[88:91]
	v_mfma_f32_16x16x32_bf16 v[76:79], v[156:159], v[212:215], v[76:79]
	v_mfma_f32_16x16x32_bf16 v[72:75], v[164:167], v[212:215], v[72:75]
	v_mfma_f32_16x16x32_bf16 v[116:119], v[168:171], v[184:187], 0
	v_mfma_f32_16x16x32_bf16 v[112:115], v[176:179], v[184:187], 0
	v_mfma_f32_16x16x32_bf16 v[100:103], v[168:171], v[192:195], 0
	v_mfma_f32_16x16x32_bf16 v[96:99], v[176:179], v[192:195], 0
	v_mfma_f32_16x16x32_bf16 v[84:87], v[168:171], v[200:203], 0
	v_mfma_f32_16x16x32_bf16 v[80:83], v[176:179], v[200:203], 0
	v_mfma_f32_16x16x32_bf16 v[68:71], v[168:171], v[208:211], 0
	v_mfma_f32_16x16x32_bf16 v[64:67], v[176:179], v[208:211], 0
	v_mfma_f32_16x16x32_bf16 v[116:119], v[172:175], v[188:191], v[116:119]
	v_mfma_f32_16x16x32_bf16 v[112:115], v[180:183], v[188:191], v[112:115]
	v_mfma_f32_16x16x32_bf16 v[100:103], v[172:175], v[196:199], v[100:103]
	v_mfma_f32_16x16x32_bf16 v[96:99], v[180:183], v[196:199], v[96:99]
	v_mfma_f32_16x16x32_bf16 v[84:87], v[172:175], v[204:207], v[84:87]
	v_mfma_f32_16x16x32_bf16 v[80:83], v[180:183], v[204:207], v[80:83]
	v_mfma_f32_16x16x32_bf16 v[68:71], v[172:175], v[212:215], v[68:71]
	v_mfma_f32_16x16x32_bf16 v[64:67], v[180:183], v[212:215], v[64:67]
	s_barrier
	s_setprio 0
	s_add_i32 s55, s44, s33
	v_lshl_add_u64 v[216:217], s[26:27], 0, v[132:133]
	s_mov_b32 m0, s55
	ds_read_b128 v[184:187], v150 offset:16384
	ds_read_b128 v[188:191], v150 offset:17408
	ds_read_b128 v[192:195], v150 offset:18432
	ds_read_b128 v[196:199], v150 offset:19456
	ds_read_b128 v[200:203], v150 offset:20480
	ds_read_b128 v[204:207], v150 offset:21504
	ds_read_b128 v[208:211], v150 offset:22528
	ds_read_b128 v[212:215], v150 offset:23552
	global_load_lds_dwordx4 v[216:217], off
	s_add_i32 m0, s55, 0x2000
	s_add_u32 s56, s26, 0x40000
	v_lshl_add_u64 v[218:219], s[26:27], 0, v[128:129]
	s_addc_u32 s57, s27, 0
	s_add_i32 s55, s45, s33
	global_load_lds_dwordx4 v[218:219], off
	s_mov_b32 m0, s55
	v_lshl_add_u64 v[222:223], s[28:29], 0, v[130:131]
	global_load_lds_dwordx4 v132, s[56:57]
	s_add_i32 m0, s55, 0x2000
	s_nop 0
	global_load_lds_dwordx4 v128, s[56:57]
	v_lshl_add_u64 v[220:221], s[28:29], 0, v[134:135]
	s_mov_b32 m0, s23
	s_nop 0
	global_load_lds_dwordx4 v[220:221], off
	s_mov_b32 m0, s39
	s_nop 0
	global_load_lds_dwordx4 v[222:223], off
	s_waitcnt vmcnt(8)
	s_waitcnt lgkmcnt(0)
	s_setprio 1
	s_barrier
	v_mfma_f32_16x16x32_bf16 v[60:63], v[152:155], v[184:187], 0
	v_mfma_f32_16x16x32_bf16 v[56:59], v[160:163], v[184:187], 0
	v_mfma_f32_16x16x32_bf16 v[44:47], v[152:155], v[192:195], 0
	v_mfma_f32_16x16x32_bf16 v[40:43], v[160:163], v[192:195], 0
	v_mfma_f32_16x16x32_bf16 v[28:31], v[152:155], v[200:203], 0
	v_mfma_f32_16x16x32_bf16 v[24:27], v[160:163], v[200:203], 0
	v_mfma_f32_16x16x32_bf16 v[12:15], v[152:155], v[208:211], 0
	v_mfma_f32_16x16x32_bf16 v[8:11], v[160:163], v[208:211], 0
	v_mfma_f32_16x16x32_bf16 v[60:63], v[156:159], v[188:191], v[60:63]
	v_mfma_f32_16x16x32_bf16 v[56:59], v[164:167], v[188:191], v[56:59]
	v_mfma_f32_16x16x32_bf16 v[44:47], v[156:159], v[196:199], v[44:47]
	v_mfma_f32_16x16x32_bf16 v[40:43], v[164:167], v[196:199], v[40:43]
	v_mfma_f32_16x16x32_bf16 v[28:31], v[156:159], v[204:207], v[28:31]
	v_mfma_f32_16x16x32_bf16 v[24:27], v[164:167], v[204:207], v[24:27]
	v_mfma_f32_16x16x32_bf16 v[12:15], v[156:159], v[212:215], v[12:15]
	v_mfma_f32_16x16x32_bf16 v[8:11], v[164:167], v[212:215], v[8:11]
	v_mfma_f32_16x16x32_bf16 v[52:55], v[168:171], v[184:187], 0
	v_mfma_f32_16x16x32_bf16 v[48:51], v[176:179], v[184:187], 0
	v_mfma_f32_16x16x32_bf16 v[36:39], v[168:171], v[192:195], 0
	v_mfma_f32_16x16x32_bf16 v[32:35], v[176:179], v[192:195], 0
	v_mfma_f32_16x16x32_bf16 v[20:23], v[168:171], v[200:203], 0
	v_mfma_f32_16x16x32_bf16 v[16:19], v[176:179], v[200:203], 0
	v_mfma_f32_16x16x32_bf16 v[4:7], v[168:171], v[208:211], 0
	v_mfma_f32_16x16x32_bf16 v[0:3], v[176:179], v[208:211], 0
	v_mfma_f32_16x16x32_bf16 v[52:55], v[172:175], v[188:191], v[52:55]
	v_mfma_f32_16x16x32_bf16 v[48:51], v[180:183], v[188:191], v[48:51]
	v_mfma_f32_16x16x32_bf16 v[36:39], v[172:175], v[196:199], v[36:39]
	v_mfma_f32_16x16x32_bf16 v[32:35], v[180:183], v[196:199], v[32:35]
	v_mfma_f32_16x16x32_bf16 v[20:23], v[172:175], v[204:207], v[20:23]
	v_mfma_f32_16x16x32_bf16 v[16:19], v[180:183], v[204:207], v[16:19]
	v_mfma_f32_16x16x32_bf16 v[4:7], v[172:175], v[212:215], v[4:7]
	v_mfma_f32_16x16x32_bf16 v[0:3], v[180:183], v[212:215], v[0:3]
	s_barrier
; #define PG8_STAGE(bufoff, gbase, voff) do { _Pragma("unroll") for (int _i = 0; _i < 2; ++_i) \
;         __builtin_amdgcn_global_load_lds((const unsigned*)((const char*)(gbase) + (voff)[_i]), (PG8_LAS unsigned*)(lds + (bufoff) + ldsw + _i * 8192), 16, 0, 0); } while (0)
; #define PG8_LDA(dst, b, h) do { _Pragma("unroll") for (int m = 0; m < 4; ++m) _Pragma("unroll") for (int k = 0; k < 2; ++k) dst[m][k] = *(const PG8_LAS bf16x8*)(lds + PG8_SA(b, h) + aoff + m * 2048 + k * 1024); } while (0)
; #define PG8_LDB(dst, b, h) do { _Pragma("unroll") for (int n = 0; n < 2; ++n) _Pragma("unroll") for (int k = 0; k < 2; ++k) dst[n][k] = *(const PG8_LAS bf16x8*)(lds + PG8_SB(b, h) + boff + n * 2048 + k * 1024); } while (0)
; #define PG8_MMA(ai, bj, At, Bt) do { __builtin_amdgcn_s_setprio(1); _Pragma("unroll") for (int m = 0; m < 4; ++m) _Pragma("unroll") for (int n = 0; n < 2; ++n) _Pragma("unroll") for (int k = 0; k < 2; ++k) \
;         acc[ai][bj][m][n] = __builtin_amdgcn_mfma_f32_16x16x32_bf16(Bt[n][k], At[m][k], acc[ai][bj][m][n], 0, 0, 0); __builtin_amdgcn_s_setprio(0); } while (0)
; #define PG8_WAIT_V(n) asm volatile("s_waitcnt vmcnt(" #n ")" ::: "memory")
; #define PG8_WAIT_L(n) asm volatile("s_waitcnt lgkmcnt(" #n ")" ::: "memory")
; #define PG8_BAR __builtin_amdgcn_s_barrier()
; #define PG8_SCHED __builtin_amdgcn_sched_barrier(0)
; template <class Epi, class Sched, bool ALIGN_EPI = false, bool SP2 = false>
; __device__ __forceinline__ void gemm_phase(PG8_LAS unsigned char* lds, const Gemm g, const Sched& S, const Epi& E) {
;     ...
;             PG8_LDB(B0, 1, 0); PG8_LDB(B1, 1, 1); PG8_SCHED; PG8_LDA(At, 1, 0); PG8_STAGE(PG8_SA(0, 1), a2 + hstep, voffA);
;             PG8_WAIT_V(8); PG8_WAIT_L(0); PG8_BAR; PG8_MMA(0, 0, At, B0); PG8_MMA(0, 1, At, B1); PG8_BAR; PG8_SCHED;
;             PG8_LDA(At, 1, 1); PG8_STAGE(PG8_SB(1, 0), b3, voffB); PG8_STAGE(PG8_SB(1, 1), b3 + hstep, voffB); PG8_STAGE(PG8_SA(1, 0), a3, voffA);
;             PG8_WAIT_V(8); PG8_WAIT_L(0); PG8_BAR; PG8_MMA(1, 0, At, B0); PG8_MMA(1, 1, At, B1); PG8_BAR; PG8_SCHED;
	s_setprio 0
	s_add_i32 s55, 0, 0x18000
	v_add_u32_e32 v151, s55, v145
	s_add_i32 s56, 0, 0x1c000
	ds_read_b128 v[152:155], v151
	ds_read_b128 v[156:159], v151 offset:1024
	ds_read_b128 v[160:163], v151 offset:2048
	ds_read_b128 v[164:167], v151 offset:3072
	v_add_u32_e32 v151, s56, v145
	ds_read_b128 v[168:171], v151
	ds_read_b128 v[172:175], v151 offset:1024
	ds_read_b128 v[176:179], v151 offset:2048
	ds_read_b128 v[180:183], v151 offset:3072
	s_add_u32 s28, s28, 0x40000
	s_addc_u32 s29, s29, 0
	s_mov_b32 m0, s40
	ds_read_b128 v[184:187], v150 offset:32768
	ds_read_b128 v[188:191], v150 offset:33792
	ds_read_b128 v[192:195], v150 offset:34816
	ds_read_b128 v[196:199], v150 offset:35840
	ds_read_b128 v[200:203], v150 offset:36864
	ds_read_b128 v[204:207], v150 offset:37888
	ds_read_b128 v[208:211], v150 offset:38912
	ds_read_b128 v[212:215], v150 offset:39936
	global_load_lds_dwordx4 v134, s[28:29]
	s_mov_b32 m0, s41
	s_nop 0
	global_load_lds_dwordx4 v130, s[28:29]
	s_waitcnt vmcnt(8)
	s_waitcnt lgkmcnt(0)
	s_setprio 1
	s_barrier
	v_mfma_f32_16x16x32_bf16 v[124:127], v[152:155], v[184:187], v[124:127]
	v_mfma_f32_16x16x32_bf16 v[120:123], v[160:163], v[184:187], v[120:123]
	v_mfma_f32_16x16x32_bf16 v[108:111], v[152:155], v[192:195], v[108:111]
	v_mfma_f32_16x16x32_bf16 v[104:107], v[160:163], v[192:195], v[104:107]
	v_mfma_f32_16x16x32_bf16 v[92:95], v[152:155], v[200:203], v[92:95]
	v_mfma_f32_16x16x32_bf16 v[88:91], v[160:163], v[200:203], v[88:91]
	v_mfma_f32_16x16x32_bf16 v[76:79], v[152:155], v[208:211], v[76:79]
	v_mfma_f32_16x16x32_bf16 v[72:75], v[160:163], v[208:211], v[72:75]
	v_mfma_f32_16x16x32_bf16 v[124:127], v[156:159], v[188:191], v[124:127]
	v_mfma_f32_16x16x32_bf16 v[120:123], v[164:167], v[188:191], v[120:123]
	v_mfma_f32_16x16x32_bf16 v[108:111], v[156:159], v[196:199], v[108:111]
	v_mfma_f32_16x16x32_bf16 v[104:107], v[164:167], v[196:199], v[104:107]
	v_mfma_f32_16x16x32_bf16 v[92:95], v[156:159], v[204:207], v[92:95]
	v_mfma_f32_16x16x32_bf16 v[88:91], v[164:167], v[204:207], v[88:91]
	v_mfma_f32_16x16x32_bf16 v[76:79], v[156:159], v[212:215], v[76:79]
	v_mfma_f32_16x16x32_bf16 v[72:75], v[164:167], v[212:215], v[72:75]
	v_mfma_f32_16x16x32_bf16 v[116:119], v[168:171], v[184:187], v[116:119]
	v_mfma_f32_16x16x32_bf16 v[112:115], v[176:179], v[184:187], v[112:115]
	v_mfma_f32_16x16x32_bf16 v[100:103], v[168:171], v[192:195], v[100:103]
	v_mfma_f32_16x16x32_bf16 v[96:99], v[176:179], v[192:195], v[96:99]
	v_mfma_f32_16x16x32_bf16 v[84:87], v[168:171], v[200:203], v[84:87]
	v_mfma_f32_16x16x32_bf16 v[80:83], v[176:179], v[200:203], v[80:83]
	v_mfma_f32_16x16x32_bf16 v[68:71], v[168:171], v[208:211], v[68:71]
	v_mfma_f32_16x16x32_bf16 v[64:67], v[176:179], v[208:211], v[64:67]
	v_mfma_f32_16x16x32_bf16 v[116:119], v[172:175], v[188:191], v[116:119]
	v_mfma_f32_16x16x32_bf16 v[112:115], v[180:183], v[188:191], v[112:115]
	v_mfma_f32_16x16x32_bf16 v[100:103], v[172:175], v[196:199], v[100:103]
	v_mfma_f32_16x16x32_bf16 v[96:99], v[180:183], v[196:199], v[96:99]
	v_mfma_f32_16x16x32_bf16 v[84:87], v[172:175], v[204:207], v[84:87]
	v_mfma_f32_16x16x32_bf16 v[80:83], v[180:183], v[204:207], v[80:83]
	v_mfma_f32_16x16x32_bf16 v[68:71], v[172:175], v[212:215], v[68:71]
	v_mfma_f32_16x16x32_bf16 v[64:67], v[180:183], v[212:215], v[64:67]
	s_barrier
	s_setprio 0
	s_add_i32 s28, s55, s33
	v_lshl_add_u64 v[216:217], v[216:217], 0, s[8:9]
	s_mov_b32 m0, s28
	ds_read_b128 v[184:187], v150 offset:49152
	ds_read_b128 v[188:191], v150 offset:50176
	ds_read_b128 v[192:195], v150 offset:51200
	ds_read_b128 v[196:199], v150 offset:52224
	ds_read_b128 v[200:203], v150 offset:53248
	ds_read_b128 v[204:207], v150 offset:54272
	ds_read_b128 v[208:211], v150 offset:55296
	ds_read_b128 v[212:215], v150 offset:56320
	global_load_lds_dwordx4 v[216:217], off
	s_add_i32 m0, s28, 0x2000
	s_add_u32 s26, s26, 0x40080
	v_lshl_add_u64 v[216:217], v[218:219], 0, s[8:9]
	s_addc_u32 s27, s27, 0
	s_add_i32 s28, s56, s33
	global_load_lds_dwordx4 v[216:217], off
	s_mov_b32 m0, s28
	s_nop 0
	global_load_lds_dwordx4 v132, s[26:27]
	s_add_i32 m0, s28, 0x2000
	s_nop 0
	global_load_lds_dwordx4 v128, s[26:27]
	v_lshl_add_u64 v[216:217], v[220:221], 0, s[8:9]
	s_mov_b32 m0, s42
	s_nop 0
	global_load_lds_dwordx4 v[216:217], off
	v_lshl_add_u64 v[216:217], v[222:223], 0, s[8:9]
	s_mov_b32 m0, s43
	s_nop 0
	global_load_lds_dwordx4 v[216:217], off
	s_waitcnt vmcnt(8)
	s_waitcnt lgkmcnt(0)
	s_setprio 1
	s_barrier
	v_mfma_f32_16x16x32_bf16 v[60:63], v[152:155], v[184:187], v[60:63]
	v_mfma_f32_16x16x32_bf16 v[56:59], v[160:163], v[184:187], v[56:59]
	v_mfma_f32_16x16x32_bf16 v[44:47], v[152:155], v[192:195], v[44:47]
	v_mfma_f32_16x16x32_bf16 v[40:43], v[160:163], v[192:195], v[40:43]
	v_mfma_f32_16x16x32_bf16 v[28:31], v[152:155], v[200:203], v[28:31]
	v_mfma_f32_16x16x32_bf16 v[24:27], v[160:163], v[200:203], v[24:27]
	v_mfma_f32_16x16x32_bf16 v[12:15], v[152:155], v[208:211], v[12:15]
	v_mfma_f32_16x16x32_bf16 v[8:11], v[160:163], v[208:211], v[8:11]
	v_mfma_f32_16x16x32_bf16 v[60:63], v[156:159], v[188:191], v[60:63]
	v_mfma_f32_16x16x32_bf16 v[56:59], v[164:167], v[188:191], v[56:59]
	v_mfma_f32_16x16x32_bf16 v[44:47], v[156:159], v[196:199], v[44:47]
	v_mfma_f32_16x16x32_bf16 v[40:43], v[164:167], v[196:199], v[40:43]
	v_mfma_f32_16x16x32_bf16 v[28:31], v[156:159], v[204:207], v[28:31]
	v_mfma_f32_16x16x32_bf16 v[24:27], v[164:167], v[204:207], v[24:27]
	v_mfma_f32_16x16x32_bf16 v[12:15], v[156:159], v[212:215], v[12:15]
	v_mfma_f32_16x16x32_bf16 v[8:11], v[164:167], v[212:215], v[8:11]
	v_mfma_f32_16x16x32_bf16 v[52:55], v[168:171], v[184:187], v[52:55]
	v_mfma_f32_16x16x32_bf16 v[48:51], v[176:179], v[184:187], v[48:51]
	v_mfma_f32_16x16x32_bf16 v[36:39], v[168:171], v[192:195], v[36:39]
	v_mfma_f32_16x16x32_bf16 v[32:35], v[176:179], v[192:195], v[32:35]
	v_mfma_f32_16x16x32_bf16 v[20:23], v[168:171], v[200:203], v[20:23]
	v_mfma_f32_16x16x32_bf16 v[16:19], v[176:179], v[200:203], v[16:19]
	v_mfma_f32_16x16x32_bf16 v[4:7], v[168:171], v[208:211], v[4:7]
	v_mfma_f32_16x16x32_bf16 v[0:3], v[176:179], v[208:211], v[0:3]
	v_mfma_f32_16x16x32_bf16 v[52:55], v[172:175], v[188:191], v[52:55]
	v_mfma_f32_16x16x32_bf16 v[48:51], v[180:183], v[188:191], v[48:51]
	v_mfma_f32_16x16x32_bf16 v[36:39], v[172:175], v[196:199], v[36:39]
	v_mfma_f32_16x16x32_bf16 v[32:35], v[180:183], v[196:199], v[32:35]
	v_mfma_f32_16x16x32_bf16 v[20:23], v[172:175], v[204:207], v[20:23]
	v_mfma_f32_16x16x32_bf16 v[16:19], v[180:183], v[204:207], v[16:19]
	v_mfma_f32_16x16x32_bf16 v[4:7], v[172:175], v[212:215], v[4:7]
	v_mfma_f32_16x16x32_bf16 v[0:3], v[180:183], v[212:215], v[0:3]
	s_barrier
	s_setprio 0
	s_add_i32 s54, s54, 2
	s_add_u32 s24, s24, 0x100
	s_addc_u32 s25, s25, 0
	s_add_u32 s52, s52, 0x100
	s_addc_u32 s53, s53, 0
	s_cmp_gt_u32 s54, 13
; #define PG8_STAGE(bufoff, gbase, voff) do { _Pragma("unroll") for (int _i = 0; _i < 2; ++_i) \
;         __builtin_amdgcn_global_load_lds((const unsigned*)((const char*)(gbase) + (voff)[_i]), (PG8_LAS unsigned*)(lds + (bufoff) + ldsw + _i * 8192), 16, 0, 0); } while (0)
; #define PG8_LDA(dst, b, h) do { _Pragma("unroll") for (int m = 0; m < 4; ++m) _Pragma("unroll") for (int k = 0; k < 2; ++k) dst[m][k] = *(const PG8_LAS bf16x8*)(lds + PG8_SA(b, h) + aoff + m * 2048 + k * 1024); } while (0)
; #define PG8_LDB(dst, b, h) do { _Pragma("unroll") for (int n = 0; n < 2; ++n) _Pragma("unroll") for (int k = 0; k < 2; ++k) dst[n][k] = *(const PG8_LAS bf16x8*)(lds + PG8_SB(b, h) + boff + n * 2048 + k * 1024); } while (0)
; #define PG8_MMA(ai, bj, At, Bt) do { __builtin_amdgcn_s_setprio(1); _Pragma("unroll") for (int m = 0; m < 4; ++m) _Pragma("unroll") for (int n = 0; n < 2; ++n) _Pragma("unroll") for (int k = 0; k < 2; ++k) \
;         acc[ai][bj][m][n] = __builtin_amdgcn_mfma_f32_16x16x32_bf16(Bt[n][k], At[m][k], acc[ai][bj][m][n], 0, 0, 0); __builtin_amdgcn_s_setprio(0); } while (0)
; #define PG8_WAIT_V(n) asm volatile("s_waitcnt vmcnt(" #n ")" ::: "memory")
; #define PG8_WAIT_L(n) asm volatile("s_waitcnt lgkmcnt(" #n ")" ::: "memory")
; #define PG8_BAR __builtin_amdgcn_s_barrier()
; #define PG8_SCHED __builtin_amdgcn_sched_barrier(0)
; template <class Epi, class Sched, bool ALIGN_EPI = false, bool SP2 = false>
; __device__ __forceinline__ void gemm_phase(PG8_LAS unsigned char* lds, const Gemm g, const Sched& S, const Epi& E) {
;     ...
;             PG8_LDB(B0, 0, 0); PG8_LDB(B1, 0, 1); PG8_SCHED; PG8_LDA(At, 0, 0); PG8_STAGE(PG8_SA(1, 1), a1 + hstep, voffA);
;             PG8_WAIT_V(8); PG8_WAIT_L(0); PG8_BAR; PG8_MMA(0, 0, At, B0); PG8_MMA(0, 1, At, B1); PG8_BAR; PG8_SCHED;
;             PG8_LDA(At, 0, 1); PG8_STAGE(PG8_SB(0, 0), b2, voffB); PG8_STAGE(PG8_SB(0, 1), b2 + hstep, voffB); PG8_STAGE(PG8_SA(0, 0), a2, voffA);
;             PG8_WAIT_V(8); PG8_WAIT_L(0); PG8_BAR; PG8_MMA(1, 0, At, B0); PG8_MMA(1, 1, At, B1); PG8_BAR; PG8_SCHED;
.LBB0_337:
	ds_read_b128 v[152:155], v148
	ds_read_b128 v[156:159], v148 offset:1024
	ds_read_b128 v[160:163], v148 offset:2048
	ds_read_b128 v[164:167], v148 offset:3072
	ds_read_b128 v[168:171], v149
	ds_read_b128 v[172:175], v149 offset:1024
	ds_read_b128 v[176:179], v149 offset:2048
	ds_read_b128 v[180:183], v149 offset:3072
	s_add_u32 s26, s24, 0xfffc0080
	s_addc_u32 s27, s25, -1
	s_cmp_eq_u32 s54, 12
	s_cselect_b32 s29, s17, s27
	s_cselect_b32 s28, s50, s26
	s_cselect_b32 s27, s15, s53
	s_cselect_b32 s26, s51, s52
	s_add_i32 m0, s23, 0xc000
	ds_read_b128 v[184:187], v150
	ds_read_b128 v[188:191], v150 offset:1024
	ds_read_b128 v[192:195], v150 offset:2048
	ds_read_b128 v[196:199], v150 offset:3072
	ds_read_b128 v[200:203], v150 offset:4096
	ds_read_b128 v[204:207], v150 offset:5120
	ds_read_b128 v[208:211], v150 offset:6144
	ds_read_b128 v[212:215], v150 offset:7168
	global_load_lds_dwordx4 v136, s[24:25]
	s_add_i32 m0, s23, 0xe000
	s_nop 0
	global_load_lds_dwordx4 v138, s[24:25]
	s_waitcnt vmcnt(8)
	s_waitcnt lgkmcnt(0)
	s_setprio 1
	s_barrier
	v_mfma_f32_16x16x32_bf16 v[124:127], v[152:155], v[184:187], v[124:127]
	v_mfma_f32_16x16x32_bf16 v[120:123], v[160:163], v[184:187], v[120:123]
	v_mfma_f32_16x16x32_bf16 v[108:111], v[152:155], v[192:195], v[108:111]
	v_mfma_f32_16x16x32_bf16 v[104:107], v[160:163], v[192:195], v[104:107]
	v_mfma_f32_16x16x32_bf16 v[92:95], v[152:155], v[200:203], v[92:95]
	v_mfma_f32_16x16x32_bf16 v[88:91], v[160:163], v[200:203], v[88:91]
	v_mfma_f32_16x16x32_bf16 v[76:79], v[152:155], v[208:211], v[76:79]
	v_mfma_f32_16x16x32_bf16 v[72:75], v[160:163], v[208:211], v[72:75]
	v_mfma_f32_16x16x32_bf16 v[124:127], v[156:159], v[188:191], v[124:127]
	v_mfma_f32_16x16x32_bf16 v[120:123], v[164:167], v[188:191], v[120:123]
	v_mfma_f32_16x16x32_bf16 v[108:111], v[156:159], v[196:199], v[108:111]
	v_mfma_f32_16x16x32_bf16 v[104:107], v[164:167], v[196:199], v[104:107]
	v_mfma_f32_16x16x32_bf16 v[92:95], v[156:159], v[204:207], v[92:95]
	v_mfma_f32_16x16x32_bf16 v[88:91], v[164:167], v[204:207], v[88:91]
	v_mfma_f32_16x16x32_bf16 v[76:79], v[156:159], v[212:215], v[76:79]
	v_mfma_f32_16x16x32_bf16 v[72:75], v[164:167], v[212:215], v[72:75]
	v_mfma_f32_16x16x32_bf16 v[116:119], v[168:171], v[184:187], v[116:119]
	v_mfma_f32_16x16x32_bf16 v[112:115], v[176:179], v[184:187], v[112:115]
	v_mfma_f32_16x16x32_bf16 v[100:103], v[168:171], v[192:195], v[100:103]
	v_mfma_f32_16x16x32_bf16 v[96:99], v[176:179], v[192:195], v[96:99]
	v_mfma_f32_16x16x32_bf16 v[84:87], v[168:171], v[200:203], v[84:87]
	v_mfma_f32_16x16x32_bf16 v[80:83], v[176:179], v[200:203], v[80:83]
	v_mfma_f32_16x16x32_bf16 v[68:71], v[168:171], v[208:211], v[68:71]
	v_mfma_f32_16x16x32_bf16 v[64:67], v[176:179], v[208:211], v[64:67]
	v_mfma_f32_16x16x32_bf16 v[116:119], v[172:175], v[188:191], v[116:119]
	v_mfma_f32_16x16x32_bf16 v[112:115], v[180:183], v[188:191], v[112:115]
	v_mfma_f32_16x16x32_bf16 v[100:103], v[172:175], v[196:199], v[100:103]
	v_mfma_f32_16x16x32_bf16 v[96:99], v[180:183], v[196:199], v[96:99]
	v_mfma_f32_16x16x32_bf16 v[84:87], v[172:175], v[204:207], v[84:87]
	v_mfma_f32_16x16x32_bf16 v[80:83], v[180:183], v[204:207], v[80:83]
	v_mfma_f32_16x16x32_bf16 v[68:71], v[172:175], v[212:215], v[68:71]
	v_mfma_f32_16x16x32_bf16 v[64:67], v[180:183], v[212:215], v[64:67]
	s_barrier
	s_setprio 0
	s_add_i32 s55, s44, s33
	v_lshl_add_u64 v[216:217], s[26:27], 0, v[132:133]
	s_mov_b32 m0, s55
	ds_read_b128 v[184:187], v150 offset:16384
	ds_read_b128 v[188:191], v150 offset:17408
	ds_read_b128 v[192:195], v150 offset:18432
	ds_read_b128 v[196:199], v150 offset:19456
	ds_read_b128 v[200:203], v150 offset:20480
	ds_read_b128 v[204:207], v150 offset:21504
	ds_read_b128 v[208:211], v150 offset:22528
	ds_read_b128 v[212:215], v150 offset:23552
	global_load_lds_dwordx4 v[216:217], off
	s_add_i32 m0, s55, 0x2000
	s_add_u32 s56, s26, 0x40000
	v_lshl_add_u64 v[218:219], s[26:27], 0, v[128:129]
	s_addc_u32 s57, s27, 0
	s_add_i32 s55, s45, s33
	global_load_lds_dwordx4 v[218:219], off
	s_mov_b32 m0, s55
	v_lshl_add_u64 v[222:223], s[28:29], 0, v[130:131]
	global_load_lds_dwordx4 v132, s[56:57]
	s_add_i32 m0, s55, 0x2000
	s_nop 0
	global_load_lds_dwordx4 v128, s[56:57]
	v_lshl_add_u64 v[220:221], s[28:29], 0, v[134:135]
	s_mov_b32 m0, s23
	s_nop 0
	global_load_lds_dwordx4 v[220:221], off
	s_mov_b32 m0, s39
	s_nop 0
	global_load_lds_dwordx4 v[222:223], off
	s_waitcnt vmcnt(8)
	s_waitcnt lgkmcnt(0)
	s_setprio 1
	s_barrier
	v_mfma_f32_16x16x32_bf16 v[60:63], v[152:155], v[184:187], v[60:63]
	v_mfma_f32_16x16x32_bf16 v[56:59], v[160:163], v[184:187], v[56:59]
	v_mfma_f32_16x16x32_bf16 v[44:47], v[152:155], v[192:195], v[44:47]
	v_mfma_f32_16x16x32_bf16 v[40:43], v[160:163], v[192:195], v[40:43]
	v_mfma_f32_16x16x32_bf16 v[28:31], v[152:155], v[200:203], v[28:31]
	v_mfma_f32_16x16x32_bf16 v[24:27], v[160:163], v[200:203], v[24:27]
	v_mfma_f32_16x16x32_bf16 v[12:15], v[152:155], v[208:211], v[12:15]
	v_mfma_f32_16x16x32_bf16 v[8:11], v[160:163], v[208:211], v[8:11]
	v_mfma_f32_16x16x32_bf16 v[60:63], v[156:159], v[188:191], v[60:63]
	v_mfma_f32_16x16x32_bf16 v[56:59], v[164:167], v[188:191], v[56:59]
	v_mfma_f32_16x16x32_bf16 v[44:47], v[156:159], v[196:199], v[44:47]
	v_mfma_f32_16x16x32_bf16 v[40:43], v[164:167], v[196:199], v[40:43]
	v_mfma_f32_16x16x32_bf16 v[28:31], v[156:159], v[204:207], v[28:31]
	v_mfma_f32_16x16x32_bf16 v[24:27], v[164:167], v[204:207], v[24:27]
	v_mfma_f32_16x16x32_bf16 v[12:15], v[156:159], v[212:215], v[12:15]
	v_mfma_f32_16x16x32_bf16 v[8:11], v[164:167], v[212:215], v[8:11]
	v_mfma_f32_16x16x32_bf16 v[52:55], v[168:171], v[184:187], v[52:55]
	v_mfma_f32_16x16x32_bf16 v[48:51], v[176:179], v[184:187], v[48:51]
	v_mfma_f32_16x16x32_bf16 v[36:39], v[168:171], v[192:195], v[36:39]
	v_mfma_f32_16x16x32_bf16 v[32:35], v[176:179], v[192:195], v[32:35]
	v_mfma_f32_16x16x32_bf16 v[20:23], v[168:171], v[200:203], v[20:23]
	v_mfma_f32_16x16x32_bf16 v[16:19], v[176:179], v[200:203], v[16:19]
	v_mfma_f32_16x16x32_bf16 v[4:7], v[168:171], v[208:211], v[4:7]
	v_mfma_f32_16x16x32_bf16 v[0:3], v[176:179], v[208:211], v[0:3]
	v_mfma_f32_16x16x32_bf16 v[52:55], v[172:175], v[188:191], v[52:55]
	v_mfma_f32_16x16x32_bf16 v[48:51], v[180:183], v[188:191], v[48:51]
	v_mfma_f32_16x16x32_bf16 v[36:39], v[172:175], v[196:199], v[36:39]
	v_mfma_f32_16x16x32_bf16 v[32:35], v[180:183], v[196:199], v[32:35]
	v_mfma_f32_16x16x32_bf16 v[20:23], v[172:175], v[204:207], v[20:23]
	v_mfma_f32_16x16x32_bf16 v[16:19], v[180:183], v[204:207], v[16:19]
	v_mfma_f32_16x16x32_bf16 v[4:7], v[172:175], v[212:215], v[4:7]
	v_mfma_f32_16x16x32_bf16 v[0:3], v[180:183], v[212:215], v[0:3]
	s_barrier
; #define PG8_STAGE(bufoff, gbase, voff) do { _Pragma("unroll") for (int _i = 0; _i < 2; ++_i) \
;         __builtin_amdgcn_global_load_lds((const unsigned*)((const char*)(gbase) + (voff)[_i]), (PG8_LAS unsigned*)(lds + (bufoff) + ldsw + _i * 8192), 16, 0, 0); } while (0)
; #define PG8_LDA(dst, b, h) do { _Pragma("unroll") for (int m = 0; m < 4; ++m) _Pragma("unroll") for (int k = 0; k < 2; ++k) dst[m][k] = *(const PG8_LAS bf16x8*)(lds + PG8_SA(b, h) + aoff + m * 2048 + k * 1024); } while (0)
; #define PG8_LDB(dst, b, h) do { _Pragma("unroll") for (int n = 0; n < 2; ++n) _Pragma("unroll") for (int k = 0; k < 2; ++k) dst[n][k] = *(const PG8_LAS bf16x8*)(lds + PG8_SB(b, h) + boff + n * 2048 + k * 1024); } while (0)
; #define PG8_MMA(ai, bj, At, Bt) do { __builtin_amdgcn_s_setprio(1); _Pragma("unroll") for (int m = 0; m < 4; ++m) _Pragma("unroll") for (int n = 0; n < 2; ++n) _Pragma("unroll") for (int k = 0; k < 2; ++k) \
;         acc[ai][bj][m][n] = __builtin_amdgcn_mfma_f32_16x16x32_bf16(Bt[n][k], At[m][k], acc[ai][bj][m][n], 0, 0, 0); __builtin_amdgcn_s_setprio(0); } while (0)
; #define PG8_WAIT_V(n) asm volatile("s_waitcnt vmcnt(" #n ")" ::: "memory")
; #define PG8_WAIT_L(n) asm volatile("s_waitcnt lgkmcnt(" #n ")" ::: "memory")
; #define PG8_BAR __builtin_amdgcn_s_barrier()
; #define PG8_SCHED __builtin_amdgcn_sched_barrier(0)
; template <class Epi, class Sched, bool ALIGN_EPI = false, bool SP2 = false>
; __device__ __forceinline__ void gemm_phase(PG8_LAS unsigned char* lds, const Gemm g, const Sched& S, const Epi& E) {
;     ...
;             PG8_LDB(B0, 1, 0); PG8_LDB(B1, 1, 1); PG8_SCHED; PG8_LDA(At, 1, 0); PG8_STAGE(PG8_SA(0, 1), a2 + hstep, voffA);
;             PG8_WAIT_V(8); PG8_WAIT_L(0); PG8_BAR; PG8_MMA(0, 0, At, B0); PG8_MMA(0, 1, At, B1); PG8_BAR; PG8_SCHED;
;             PG8_LDA(At, 1, 1); PG8_STAGE(PG8_SB(1, 0), b3, voffB); PG8_STAGE(PG8_SB(1, 1), b3 + hstep, voffB); PG8_STAGE(PG8_SA(1, 0), a3, voffA);
;             PG8_WAIT_V(8); PG8_WAIT_L(0); PG8_BAR; PG8_MMA(1, 0, At, B0); PG8_MMA(1, 1, At, B1); PG8_BAR; PG8_SCHED;
;     ...
;         if constexpr (ALIGN_EPI) { if (wr == 0) PG8_BAR; }
	s_setprio 0
	s_add_i32 s55, 0, 0x18000
	v_add_u32_e32 v151, s55, v145
	s_add_i32 s56, 0, 0x1c000
	ds_read_b128 v[152:155], v151
	ds_read_b128 v[156:159], v151 offset:1024
	ds_read_b128 v[160:163], v151 offset:2048
	ds_read_b128 v[164:167], v151 offset:3072
	v_add_u32_e32 v151, s56, v145
	ds_read_b128 v[168:171], v151
	ds_read_b128 v[172:175], v151 offset:1024
	ds_read_b128 v[176:179], v151 offset:2048
	ds_read_b128 v[180:183], v151 offset:3072
	s_add_u32 s28, s28, 0x40000
	s_addc_u32 s29, s29, 0
	s_mov_b32 m0, s40
	ds_read_b128 v[184:187], v150 offset:32768
	ds_read_b128 v[188:191], v150 offset:33792
	ds_read_b128 v[192:195], v150 offset:34816
	ds_read_b128 v[196:199], v150 offset:35840
	ds_read_b128 v[200:203], v150 offset:36864
	ds_read_b128 v[204:207], v150 offset:37888
	ds_read_b128 v[208:211], v150 offset:38912
	ds_read_b128 v[212:215], v150 offset:39936
	global_load_lds_dwordx4 v134, s[28:29]
	s_mov_b32 m0, s41
	s_nop 0
	global_load_lds_dwordx4 v130, s[28:29]
	s_waitcnt vmcnt(8)
	s_waitcnt lgkmcnt(0)
	s_setprio 1
	s_barrier
	v_mfma_f32_16x16x32_bf16 v[124:127], v[152:155], v[184:187], v[124:127]
	v_mfma_f32_16x16x32_bf16 v[120:123], v[160:163], v[184:187], v[120:123]
	v_mfma_f32_16x16x32_bf16 v[108:111], v[152:155], v[192:195], v[108:111]
	v_mfma_f32_16x16x32_bf16 v[104:107], v[160:163], v[192:195], v[104:107]
	v_mfma_f32_16x16x32_bf16 v[92:95], v[152:155], v[200:203], v[92:95]
	v_mfma_f32_16x16x32_bf16 v[88:91], v[160:163], v[200:203], v[88:91]
	v_mfma_f32_16x16x32_bf16 v[76:79], v[152:155], v[208:211], v[76:79]
	v_mfma_f32_16x16x32_bf16 v[72:75], v[160:163], v[208:211], v[72:75]
	v_mfma_f32_16x16x32_bf16 v[124:127], v[156:159], v[188:191], v[124:127]
	v_mfma_f32_16x16x32_bf16 v[120:123], v[164:167], v[188:191], v[120:123]
	v_mfma_f32_16x16x32_bf16 v[108:111], v[156:159], v[196:199], v[108:111]
	v_mfma_f32_16x16x32_bf16 v[104:107], v[164:167], v[196:199], v[104:107]
	v_mfma_f32_16x16x32_bf16 v[92:95], v[156:159], v[204:207], v[92:95]
	v_mfma_f32_16x16x32_bf16 v[88:91], v[164:167], v[204:207], v[88:91]
	v_mfma_f32_16x16x32_bf16 v[76:79], v[156:159], v[212:215], v[76:79]
	v_mfma_f32_16x16x32_bf16 v[72:75], v[164:167], v[212:215], v[72:75]
	v_mfma_f32_16x16x32_bf16 v[116:119], v[168:171], v[184:187], v[116:119]
	v_mfma_f32_16x16x32_bf16 v[112:115], v[176:179], v[184:187], v[112:115]
	v_mfma_f32_16x16x32_bf16 v[100:103], v[168:171], v[192:195], v[100:103]
	v_mfma_f32_16x16x32_bf16 v[96:99], v[176:179], v[192:195], v[96:99]
	v_mfma_f32_16x16x32_bf16 v[84:87], v[168:171], v[200:203], v[84:87]
	v_mfma_f32_16x16x32_bf16 v[80:83], v[176:179], v[200:203], v[80:83]
	v_mfma_f32_16x16x32_bf16 v[68:71], v[168:171], v[208:211], v[68:71]
	v_mfma_f32_16x16x32_bf16 v[64:67], v[176:179], v[208:211], v[64:67]
	v_mfma_f32_16x16x32_bf16 v[116:119], v[172:175], v[188:191], v[116:119]
	v_mfma_f32_16x16x32_bf16 v[112:115], v[180:183], v[188:191], v[112:115]
	v_mfma_f32_16x16x32_bf16 v[100:103], v[172:175], v[196:199], v[100:103]
	v_mfma_f32_16x16x32_bf16 v[96:99], v[180:183], v[196:199], v[96:99]
	v_mfma_f32_16x16x32_bf16 v[84:87], v[172:175], v[204:207], v[84:87]
	v_mfma_f32_16x16x32_bf16 v[80:83], v[180:183], v[204:207], v[80:83]
	v_mfma_f32_16x16x32_bf16 v[68:71], v[172:175], v[212:215], v[68:71]
	v_mfma_f32_16x16x32_bf16 v[64:67], v[180:183], v[212:215], v[64:67]
	s_barrier
	s_setprio 0
	s_add_i32 s28, s55, s33
	v_lshl_add_u64 v[216:217], v[216:217], 0, s[8:9]
	s_mov_b32 m0, s28
	ds_read_b128 v[184:187], v150 offset:49152
	ds_read_b128 v[188:191], v150 offset:50176
	ds_read_b128 v[192:195], v150 offset:51200
	ds_read_b128 v[196:199], v150 offset:52224
	ds_read_b128 v[200:203], v150 offset:53248
	ds_read_b128 v[204:207], v150 offset:54272
	ds_read_b128 v[208:211], v150 offset:55296
	ds_read_b128 v[212:215], v150 offset:56320
	global_load_lds_dwordx4 v[216:217], off
	s_add_i32 m0, s28, 0x2000
	s_add_u32 s26, s26, 0x40080
	v_lshl_add_u64 v[216:217], v[218:219], 0, s[8:9]
	s_addc_u32 s27, s27, 0
	s_add_i32 s28, s56, s33
	global_load_lds_dwordx4 v[216:217], off
	s_mov_b32 m0, s28
	s_nop 0
	global_load_lds_dwordx4 v132, s[26:27]
	s_add_i32 m0, s28, 0x2000
	s_nop 0
	global_load_lds_dwordx4 v128, s[26:27]
	v_lshl_add_u64 v[216:217], v[220:221], 0, s[8:9]
	s_mov_b32 m0, s42
	s_nop 0
	global_load_lds_dwordx4 v[216:217], off
	v_lshl_add_u64 v[216:217], v[222:223], 0, s[8:9]
	s_mov_b32 m0, s43
	s_nop 0
	global_load_lds_dwordx4 v[216:217], off
	s_waitcnt vmcnt(8)
	s_waitcnt lgkmcnt(0)
	s_setprio 1
	s_barrier
	v_mfma_f32_16x16x32_bf16 v[60:63], v[152:155], v[184:187], v[60:63]
	v_mfma_f32_16x16x32_bf16 v[56:59], v[160:163], v[184:187], v[56:59]
	v_mfma_f32_16x16x32_bf16 v[44:47], v[152:155], v[192:195], v[44:47]
	v_mfma_f32_16x16x32_bf16 v[40:43], v[160:163], v[192:195], v[40:43]
	v_mfma_f32_16x16x32_bf16 v[28:31], v[152:155], v[200:203], v[28:31]
	v_mfma_f32_16x16x32_bf16 v[24:27], v[160:163], v[200:203], v[24:27]
	v_mfma_f32_16x16x32_bf16 v[12:15], v[152:155], v[208:211], v[12:15]
	v_mfma_f32_16x16x32_bf16 v[8:11], v[160:163], v[208:211], v[8:11]
	v_mfma_f32_16x16x32_bf16 v[60:63], v[156:159], v[188:191], v[60:63]
	v_mfma_f32_16x16x32_bf16 v[56:59], v[164:167], v[188:191], v[56:59]
	v_mfma_f32_16x16x32_bf16 v[44:47], v[156:159], v[196:199], v[44:47]
	v_mfma_f32_16x16x32_bf16 v[40:43], v[164:167], v[196:199], v[40:43]
	v_mfma_f32_16x16x32_bf16 v[28:31], v[156:159], v[204:207], v[28:31]
	v_mfma_f32_16x16x32_bf16 v[24:27], v[164:167], v[204:207], v[24:27]
	v_mfma_f32_16x16x32_bf16 v[12:15], v[156:159], v[212:215], v[12:15]
	v_mfma_f32_16x16x32_bf16 v[8:11], v[164:167], v[212:215], v[8:11]
	v_mfma_f32_16x16x32_bf16 v[52:55], v[168:171], v[184:187], v[52:55]
	v_mfma_f32_16x16x32_bf16 v[48:51], v[176:179], v[184:187], v[48:51]
	v_mfma_f32_16x16x32_bf16 v[36:39], v[168:171], v[192:195], v[36:39]
	v_mfma_f32_16x16x32_bf16 v[32:35], v[176:179], v[192:195], v[32:35]
	v_mfma_f32_16x16x32_bf16 v[20:23], v[168:171], v[200:203], v[20:23]
	v_mfma_f32_16x16x32_bf16 v[16:19], v[176:179], v[200:203], v[16:19]
	v_mfma_f32_16x16x32_bf16 v[4:7], v[168:171], v[208:211], v[4:7]
	v_mfma_f32_16x16x32_bf16 v[0:3], v[176:179], v[208:211], v[0:3]
	v_mfma_f32_16x16x32_bf16 v[52:55], v[172:175], v[188:191], v[52:55]
	v_mfma_f32_16x16x32_bf16 v[48:51], v[180:183], v[188:191], v[48:51]
	v_mfma_f32_16x16x32_bf16 v[36:39], v[172:175], v[196:199], v[36:39]
	v_mfma_f32_16x16x32_bf16 v[32:35], v[180:183], v[196:199], v[32:35]
	v_mfma_f32_16x16x32_bf16 v[20:23], v[172:175], v[204:207], v[20:23]
	v_mfma_f32_16x16x32_bf16 v[16:19], v[180:183], v[204:207], v[16:19]
	v_mfma_f32_16x16x32_bf16 v[4:7], v[172:175], v[212:215], v[4:7]
	v_mfma_f32_16x16x32_bf16 v[0:3], v[180:183], v[212:215], v[0:3]
	s_barrier
	s_setprio 0
	s_add_i32 s54, s54, 2
	s_add_u32 s24, s24, 0x100
	s_addc_u32 s25, s25, 0
	s_add_u32 s52, s52, 0x100
	s_addc_u32 s53, s53, 0
	s_cmp_gt_u32 s54, 13
	s_cbranch_scc0 .LBB0_337
	s_and_b64 vcc, exec, s[12:13]
	s_cbranch_vccz .LBB0_340
	s_barrier

; #define PG8_STAGE(bufoff, gbase, voff) do { _Pragma("unroll") for (int _i = 0; _i < 2; ++_i) \
;         __builtin_amdgcn_global_load_lds((const unsigned*)((const char*)(gbase) + (voff)[_i]), (PG8_LAS unsigned*)(lds + (bufoff) + ldsw + _i * 8192), 16, 0, 0); } while (0)
; #define PG8_WAIT_V(n) asm volatile("s_waitcnt vmcnt(" #n ")" ::: "memory")
; #define PG8_BAR __builtin_amdgcn_s_barrier()
; template <class Epi, class Sched, bool ALIGN_EPI = false, bool SP2 = false>
; __device__ __forceinline__ void gemm_phase(PG8_LAS unsigned char* lds, const Gemm g, const Sched& S, const Epi& E) {
;     const int tid = threadIdx.x, wid = __builtin_amdgcn_readfirstlane(tid >> 6), lane = tid & 63, wr = wid >> 2, wc = wid & 3, fr = lane & 15, fq = lane >> 4;
;     const int K = g.K, nt = K / BK;
;     unsigned voffA[2], voffB[2];
; #pragma unroll
;     for (int i = 0; i < 2; ++i) { int R, C; stage_rc(tid * 16 + i * 8192, R, C); const int Rb = Epi::PERM ? ((R & ~31) + perm32(R & 31)) : R;
;         voffA[i] = (unsigned)(R * K + C) * 2u; voffB[i] = (unsigned)(Rb * K + C) * 2u; }
;     const size_t kstep = (size_t)(BK * 2);
;     const size_t hstep = (size_t)HALF * K * 2;
;     const size_t tstep = 2 * hstep;
;     const unsigned ldsw = (unsigned)wid * 1024u;
;     const int aoff = lds_byte(wr * 64 + fr, fq * 8), boff = lds_byte(wc * 32 + fr, fq * 8);
;     ...
;         PG8_STAGE(PG8_SB(1, 0), cB + kstep, voffB); PG8_STAGE(PG8_SA(1, 0), cA + kstep, voffA); PG8_STAGE(PG8_SB(1, 1), cB + hstep + kstep, voffB);
;         PG8_WAIT_V(6); PG8_BAR;
.LBB0_404:
	s_add_u32 s14, s90, 0x6400000
	s_addc_u32 s15, s91, 0
	s_add_u32 s16, s90, 0x5900000
	s_mov_b64 s[18:19], 0x80
	s_addc_u32 s17, s91, 0
	s_and_b32 s39, s1, 3
	s_add_i32 m0, s35, 0x18000
	v_lshl_add_u64 v[6:7], v[6:7], 0, s[18:19]
	s_lshl_b32 s1, s0, 13
	s_lshl_b32 s7, s39, 12
	s_waitcnt vmcnt(2)
	s_barrier
	global_load_lds_dwordx4 v[6:7], off
	v_lshl_add_u64 v[4:5], v[4:5], 0, s[18:19]
	s_add_i32 m0, s35, 0x1a000
	s_add_i32 s40, s35, 0x8000
	s_add_i32 s41, s35, 0xa000
	global_load_lds_dwordx4 v[4:5], off
	v_lshl_add_u64 v[0:1], v[0:1], 0, s[18:19]
	s_mov_b32 m0, s40
	s_add_u32 s4, s26, 0xb0080
	global_load_lds_dwordx4 v[0:1], off
	v_lshl_add_u64 v[0:1], v[2:3], 0, s[18:19]
	s_mov_b32 m0, s41
	s_addc_u32 s5, s27, 0
	global_load_lds_dwordx4 v[0:1], off
	s_add_i32 m0, s35, 0x1c000
	s_nop 0
	global_load_lds_dwordx4 v194, s[4:5]
	v_lshl_add_u64 v[0:1], s[4:5], 0, v[198:199]
	s_add_i32 m0, s35, 0x1e000
	v_lshlrev_b32_e32 v4, 2, v254
	global_load_lds_dwordx4 v[0:1], off
	v_bfe_u32 v0, v254, 4, 2
	v_and_b32_e32 v1, 15, v254
	v_lshlrev_b32_e32 v3, 4, v0
	v_lshl_or_b32 v242, s0, 6, v1
	v_lshl_or_b32 v1, v1, 6, v3
	v_and_b32_e32 v4, 32, v4
	v_lshlrev_b32_e32 v5, 6, v254
	s_movk_i32 s0, 0x3c0
	v_lshlrev_b32_e32 v2, 3, v0
	v_bitop3_b32 v1, v1, s1, v4 bitop3:0xde
	v_and_or_b32 v3, v5, s0, v3
	v_cmp_eq_u32_e64 s[0:1], 0, v0
	v_add_u16_e32 v0, v8, v9
	s_waitcnt vmcnt(6)
	s_cmpk_lt_u32 s6, 0x100
	v_lshrrev_b16_e32 v0, 1, v0
	v_bitop3_b32 v243, s7, v3, v4 bitop3:0xf6
	s_cselect_b64 s[20:21], -1, 0
	v_add_lshl_u32 v200, v10, v0, 1
	v_add_lshl_u32 v202, v11, v0, 1
	s_add_i32 s45, 0, 0x10000
	s_add_i32 s46, 0, 0x14000
	v_mbcnt_lo_u32_b32 v0, -1, 0
	v_lshl_or_b32 v244, s39, 5, v2
	s_ashr_i32 s42, s94, 31
	s_mov_b32 s43, s94
	s_ashr_i32 s44, s2, 31
	v_mov_b32_e32 v201, v195
	v_mov_b32_e32 v203, v195
	v_add_u32_e32 v245, s45, v243
	v_add_u32_e32 v246, s46, v243
	v_add_u32_e32 v247, 0, v1
	v_mbcnt_hi_u32_b32 v248, -1, v0
	s_mov_b32 s47, 0
	s_barrier
	s_branch .LBB0_407

; #define PG8_STAGE(bufoff, gbase, voff) do { _Pragma("unroll") for (int _i = 0; _i < 2; ++_i) \
;         __builtin_amdgcn_global_load_lds((const unsigned*)((const char*)(gbase) + (voff)[_i]), (PG8_LAS unsigned*)(lds + (bufoff) + ldsw + _i * 8192), 16, 0, 0); } while (0)
; #define PG8_LDA(dst, b, h) do { _Pragma("unroll") for (int m = 0; m < 4; ++m) _Pragma("unroll") for (int k = 0; k < 2; ++k) dst[m][k] = *(const PG8_LAS bf16x8*)(lds + PG8_SA(b, h) + aoff + m * 2048 + k * 1024); } while (0)
; #define PG8_LDB(dst, b, h) do { _Pragma("unroll") for (int n = 0; n < 2; ++n) _Pragma("unroll") for (int k = 0; k < 2; ++k) dst[n][k] = *(const PG8_LAS bf16x8*)(lds + PG8_SB(b, h) + boff + n * 2048 + k * 1024); } while (0)
; #define PG8_MMA(ai, bj, At, Bt) do { __builtin_amdgcn_s_setprio(1); _Pragma("unroll") for (int m = 0; m < 4; ++m) _Pragma("unroll") for (int n = 0; n < 2; ++n) _Pragma("unroll") for (int k = 0; k < 2; ++k) \
;         acc[ai][bj][m][n] = __builtin_amdgcn_mfma_f32_16x16x32_bf16(Bt[n][k], At[m][k], acc[ai][bj][m][n], 0, 0, 0); __builtin_amdgcn_s_setprio(0); } while (0)
; #define PG8_WAIT_V(n) asm volatile("s_waitcnt vmcnt(" #n ")" ::: "memory")
; #define PG8_WAIT_L(n) asm volatile("s_waitcnt lgkmcnt(" #n ")" ::: "memory")
; #define PG8_BAR __builtin_amdgcn_s_barrier()
; #define PG8_SCHED __builtin_amdgcn_sched_barrier(0)
; template <class Epi, class Sched, bool ALIGN_EPI = false, bool SP2 = false>
; __device__ __forceinline__ void gemm_phase(PG8_LAS unsigned char* lds, const Gemm g, const Sched& S, const Epi& E) {
;     ...
;             PG8_LDB(B0, 0, 0); PG8_LDB(B1, 0, 1); PG8_SCHED; PG8_LDA(At, 0, 0); PG8_STAGE(PG8_SA(1, 1), a1 + hstep, voffA);
;             PG8_WAIT_V(8); PG8_WAIT_L(0); PG8_BAR; PG8_MMA(0, 0, At, B0); PG8_MMA(0, 1, At, B1); PG8_BAR; PG8_SCHED;
;             PG8_LDA(At, 0, 1); PG8_STAGE(PG8_SB(0, 0), b2, voffB); PG8_STAGE(PG8_SB(0, 1), b2 + hstep, voffB); PG8_STAGE(PG8_SA(0, 0), a2, voffA);
;             PG8_WAIT_V(8); PG8_WAIT_L(0); PG8_BAR; PG8_MMA(1, 0, At, B0); PG8_MMA(1, 1, At, B1); PG8_BAR; PG8_SCHED;
.LBB0_417:
	s_add_u32 s24, s24, 0xb0080
	s_addc_u32 s25, s25, 0
	s_add_u32 s51, s26, 0x100
	s_addc_u32 s52, s27, 0
	s_mov_b32 s53, -2
	s_waitcnt lgkmcnt(0)
	s_add_u32 s26, s24, 0xfff50080
	s_addc_u32 s27, s25, -1
	s_cmp_eq_u32 s53, 40
	s_cselect_b32 s29, s7, s27
	s_cselect_b32 s28, s6, s26
	s_cselect_b32 s27, s23, s52
	s_cselect_b32 s26, s22, s51
	s_add_i32 m0, s35, 0xc000
	s_nop 0
	global_load_lds_dwordx4 v200, s[24:25]
	s_add_i32 m0, s35, 0xe000
	s_nop 0
	global_load_lds_dwordx4 v202, s[24:25]
	s_waitcnt vmcnt(8)
	s_waitcnt lgkmcnt(0)
	s_setprio 1
	s_barrier
	v_mfma_f32_16x16x32_bf16 v[132:135], v[120:123], v[160:163], 0
	v_mfma_f32_16x16x32_bf16 v[124:127], v[136:139], v[160:163], 0
	v_mfma_f32_16x16x32_bf16 v[108:111], v[120:123], v[168:171], 0
	v_mfma_f32_16x16x32_bf16 v[104:107], v[136:139], v[168:171], 0
	v_mfma_f32_16x16x32_bf16 v[92:95], v[120:123], v[176:179], 0
	v_mfma_f32_16x16x32_bf16 v[88:91], v[136:139], v[176:179], 0
	v_mfma_f32_16x16x32_bf16 v[76:79], v[120:123], v[184:187], 0
	v_mfma_f32_16x16x32_bf16 v[72:75], v[136:139], v[184:187], 0
	v_mfma_f32_16x16x32_bf16 v[132:135], v[128:131], v[164:167], v[132:135]
	v_mfma_f32_16x16x32_bf16 v[124:127], v[140:143], v[164:167], v[124:127]
	v_mfma_f32_16x16x32_bf16 v[108:111], v[128:131], v[172:175], v[108:111]
	v_mfma_f32_16x16x32_bf16 v[104:107], v[140:143], v[172:175], v[104:107]
	v_mfma_f32_16x16x32_bf16 v[92:95], v[128:131], v[180:183], v[92:95]
	v_mfma_f32_16x16x32_bf16 v[88:91], v[140:143], v[180:183], v[88:91]
	v_mfma_f32_16x16x32_bf16 v[76:79], v[128:131], v[188:191], v[76:79]
	v_mfma_f32_16x16x32_bf16 v[72:75], v[140:143], v[188:191], v[72:75]
	v_mfma_f32_16x16x32_bf16 v[116:119], v[144:147], v[160:163], 0
	v_mfma_f32_16x16x32_bf16 v[112:115], v[152:155], v[160:163], 0
	v_mfma_f32_16x16x32_bf16 v[100:103], v[144:147], v[168:171], 0
	v_mfma_f32_16x16x32_bf16 v[96:99], v[152:155], v[168:171], 0
	v_mfma_f32_16x16x32_bf16 v[84:87], v[144:147], v[176:179], 0
	v_mfma_f32_16x16x32_bf16 v[80:83], v[152:155], v[176:179], 0
	v_mfma_f32_16x16x32_bf16 v[68:71], v[144:147], v[184:187], 0
	v_mfma_f32_16x16x32_bf16 v[64:67], v[152:155], v[184:187], 0
	v_mfma_f32_16x16x32_bf16 v[116:119], v[148:151], v[164:167], v[116:119]
	v_mfma_f32_16x16x32_bf16 v[112:115], v[156:159], v[164:167], v[112:115]
	v_mfma_f32_16x16x32_bf16 v[100:103], v[148:151], v[172:175], v[100:103]
	v_mfma_f32_16x16x32_bf16 v[96:99], v[156:159], v[172:175], v[96:99]
	v_mfma_f32_16x16x32_bf16 v[84:87], v[148:151], v[180:183], v[84:87]
	v_mfma_f32_16x16x32_bf16 v[80:83], v[156:159], v[180:183], v[80:83]
	v_mfma_f32_16x16x32_bf16 v[68:71], v[148:151], v[188:191], v[68:71]
	v_mfma_f32_16x16x32_bf16 v[64:67], v[156:159], v[188:191], v[64:67]
	s_barrier
	s_setprio 0
	s_add_i32 s54, s45, s34
	v_lshl_add_u64 v[204:205], s[26:27], 0, v[194:195]
	s_mov_b32 m0, s54
	ds_read_b128 v[160:163], v247 offset:16384
	ds_read_b128 v[164:167], v247 offset:17408
	ds_read_b128 v[168:171], v247 offset:18432
	ds_read_b128 v[172:175], v247 offset:19456
	ds_read_b128 v[176:179], v247 offset:20480
	ds_read_b128 v[180:183], v247 offset:21504
	ds_read_b128 v[184:187], v247 offset:22528
	ds_read_b128 v[188:191], v247 offset:23552
	global_load_lds_dwordx4 v[204:205], off
	s_add_i32 m0, s54, 0x2000
	s_add_u32 s54, s26, 0xb0000
	v_lshl_add_u64 v[206:207], s[26:27], 0, v[198:199]
	s_addc_u32 s55, s27, 0
	s_add_i32 s56, s46, s34
	global_load_lds_dwordx4 v[206:207], off
	s_mov_b32 m0, s56
	v_lshl_add_u64 v[210:211], s[28:29], 0, v[196:197]
	global_load_lds_dwordx4 v194, s[54:55]
	s_add_i32 m0, s56, 0x2000
	s_nop 0
	global_load_lds_dwordx4 v198, s[54:55]
	v_lshl_add_u64 v[208:209], s[28:29], 0, v[192:193]
	s_mov_b32 m0, s35
	s_nop 0
	global_load_lds_dwordx4 v[208:209], off
	s_mov_b32 m0, s36
	s_nop 0
	global_load_lds_dwordx4 v[210:211], off
	s_waitcnt vmcnt(8)
	s_waitcnt lgkmcnt(0)
	s_setprio 1
	s_barrier
	v_mfma_f32_16x16x32_bf16 v[60:63], v[120:123], v[160:163], 0
	v_mfma_f32_16x16x32_bf16 v[56:59], v[136:139], v[160:163], 0
	v_mfma_f32_16x16x32_bf16 v[44:47], v[120:123], v[168:171], 0
	v_mfma_f32_16x16x32_bf16 v[40:43], v[136:139], v[168:171], 0
	v_mfma_f32_16x16x32_bf16 v[28:31], v[120:123], v[176:179], 0
	v_mfma_f32_16x16x32_bf16 v[24:27], v[136:139], v[176:179], 0
	v_mfma_f32_16x16x32_bf16 v[12:15], v[120:123], v[184:187], 0
	v_mfma_f32_16x16x32_bf16 v[8:11], v[136:139], v[184:187], 0
	v_mfma_f32_16x16x32_bf16 v[60:63], v[128:131], v[164:167], v[60:63]
	v_mfma_f32_16x16x32_bf16 v[56:59], v[140:143], v[164:167], v[56:59]
	v_mfma_f32_16x16x32_bf16 v[44:47], v[128:131], v[172:175], v[44:47]
	v_mfma_f32_16x16x32_bf16 v[40:43], v[140:143], v[172:175], v[40:43]
	v_mfma_f32_16x16x32_bf16 v[28:31], v[128:131], v[180:183], v[28:31]
	v_mfma_f32_16x16x32_bf16 v[24:27], v[140:143], v[180:183], v[24:27]
	v_mfma_f32_16x16x32_bf16 v[12:15], v[128:131], v[188:191], v[12:15]
	v_mfma_f32_16x16x32_bf16 v[8:11], v[140:143], v[188:191], v[8:11]
	v_mfma_f32_16x16x32_bf16 v[52:55], v[144:147], v[160:163], 0
	v_mfma_f32_16x16x32_bf16 v[48:51], v[152:155], v[160:163], 0
	v_mfma_f32_16x16x32_bf16 v[36:39], v[144:147], v[168:171], 0
	v_mfma_f32_16x16x32_bf16 v[32:35], v[152:155], v[168:171], 0
	v_mfma_f32_16x16x32_bf16 v[20:23], v[144:147], v[176:179], 0
	v_mfma_f32_16x16x32_bf16 v[16:19], v[152:155], v[176:179], 0
	v_mfma_f32_16x16x32_bf16 v[4:7], v[144:147], v[184:187], 0
	v_mfma_f32_16x16x32_bf16 v[0:3], v[152:155], v[184:187], 0
	v_mfma_f32_16x16x32_bf16 v[52:55], v[148:151], v[164:167], v[52:55]
	v_mfma_f32_16x16x32_bf16 v[48:51], v[156:159], v[164:167], v[48:51]
	v_mfma_f32_16x16x32_bf16 v[36:39], v[148:151], v[172:175], v[36:39]
	v_mfma_f32_16x16x32_bf16 v[32:35], v[156:159], v[172:175], v[32:35]
	v_mfma_f32_16x16x32_bf16 v[20:23], v[148:151], v[180:183], v[20:23]
	v_mfma_f32_16x16x32_bf16 v[16:19], v[156:159], v[180:183], v[16:19]
	v_mfma_f32_16x16x32_bf16 v[4:7], v[148:151], v[188:191], v[4:7]
	v_mfma_f32_16x16x32_bf16 v[0:3], v[156:159], v[188:191], v[0:3]
	s_barrier
; #define PG8_STAGE(bufoff, gbase, voff) do { _Pragma("unroll") for (int _i = 0; _i < 2; ++_i) \
;         __builtin_amdgcn_global_load_lds((const unsigned*)((const char*)(gbase) + (voff)[_i]), (PG8_LAS unsigned*)(lds + (bufoff) + ldsw + _i * 8192), 16, 0, 0); } while (0)
; #define PG8_LDA(dst, b, h) do { _Pragma("unroll") for (int m = 0; m < 4; ++m) _Pragma("unroll") for (int k = 0; k < 2; ++k) dst[m][k] = *(const PG8_LAS bf16x8*)(lds + PG8_SA(b, h) + aoff + m * 2048 + k * 1024); } while (0)
; #define PG8_LDB(dst, b, h) do { _Pragma("unroll") for (int n = 0; n < 2; ++n) _Pragma("unroll") for (int k = 0; k < 2; ++k) dst[n][k] = *(const PG8_LAS bf16x8*)(lds + PG8_SB(b, h) + boff + n * 2048 + k * 1024); } while (0)
; #define PG8_MMA(ai, bj, At, Bt) do { __builtin_amdgcn_s_setprio(1); _Pragma("unroll") for (int m = 0; m < 4; ++m) _Pragma("unroll") for (int n = 0; n < 2; ++n) _Pragma("unroll") for (int k = 0; k < 2; ++k) \
;         acc[ai][bj][m][n] = __builtin_amdgcn_mfma_f32_16x16x32_bf16(Bt[n][k], At[m][k], acc[ai][bj][m][n], 0, 0, 0); __builtin_amdgcn_s_setprio(0); } while (0)
; #define PG8_WAIT_V(n) asm volatile("s_waitcnt vmcnt(" #n ")" ::: "memory")
; #define PG8_WAIT_L(n) asm volatile("s_waitcnt lgkmcnt(" #n ")" ::: "memory")
; #define PG8_BAR __builtin_amdgcn_s_barrier()
; #define PG8_SCHED __builtin_amdgcn_sched_barrier(0)
; template <class Epi, class Sched, bool ALIGN_EPI = false, bool SP2 = false>
; __device__ __forceinline__ void gemm_phase(PG8_LAS unsigned char* lds, const Gemm g, const Sched& S, const Epi& E) {
;     ...
;             PG8_LDB(B0, 1, 0); PG8_LDB(B1, 1, 1); PG8_SCHED; PG8_LDA(At, 1, 0); PG8_STAGE(PG8_SA(0, 1), a2 + hstep, voffA);
;             PG8_WAIT_V(8); PG8_WAIT_L(0); PG8_BAR; PG8_MMA(0, 0, At, B0); PG8_MMA(0, 1, At, B1); PG8_BAR; PG8_SCHED;
;             PG8_LDA(At, 1, 1); PG8_STAGE(PG8_SB(1, 0), b3, voffB); PG8_STAGE(PG8_SB(1, 1), b3 + hstep, voffB); PG8_STAGE(PG8_SA(1, 0), a3, voffA);
;             PG8_WAIT_V(8); PG8_WAIT_L(0); PG8_BAR; PG8_MMA(1, 0, At, B0); PG8_MMA(1, 1, At, B1); PG8_BAR; PG8_SCHED;
	s_setprio 0
	s_add_i32 s54, 0, 0x18000
	s_add_i32 s55, 0, 0x1c000
	v_add_u32_e32 v140, s54, v243
	v_add_u32_e32 v156, s55, v243
	ds_read_b128 v[120:123], v140
	ds_read_b128 v[128:131], v140 offset:1024
	ds_read_b128 v[136:139], v140 offset:2048
	ds_read_b128 v[140:143], v140 offset:3072
	ds_read_b128 v[144:147], v156
	ds_read_b128 v[148:151], v156 offset:1024
	ds_read_b128 v[152:155], v156 offset:2048
	ds_read_b128 v[156:159], v156 offset:3072
	s_add_u32 s28, s28, 0xb0000
	s_addc_u32 s29, s29, 0
	s_mov_b32 m0, s37
	ds_read_b128 v[160:163], v247 offset:32768
	ds_read_b128 v[164:167], v247 offset:33792
	ds_read_b128 v[168:171], v247 offset:34816
	ds_read_b128 v[172:175], v247 offset:35840
	ds_read_b128 v[176:179], v247 offset:36864
	ds_read_b128 v[180:183], v247 offset:37888
	ds_read_b128 v[184:187], v247 offset:38912
	ds_read_b128 v[188:191], v247 offset:39936
	global_load_lds_dwordx4 v192, s[28:29]
	s_mov_b32 m0, s38
	s_nop 0
	global_load_lds_dwordx4 v196, s[28:29]
	s_waitcnt vmcnt(8)
	s_waitcnt lgkmcnt(0)
	s_setprio 1
	s_barrier
	v_mfma_f32_16x16x32_bf16 v[132:135], v[120:123], v[160:163], v[132:135]
	v_mfma_f32_16x16x32_bf16 v[124:127], v[136:139], v[160:163], v[124:127]
	v_mfma_f32_16x16x32_bf16 v[108:111], v[120:123], v[168:171], v[108:111]
	v_mfma_f32_16x16x32_bf16 v[104:107], v[136:139], v[168:171], v[104:107]
	v_mfma_f32_16x16x32_bf16 v[92:95], v[120:123], v[176:179], v[92:95]
	v_mfma_f32_16x16x32_bf16 v[88:91], v[136:139], v[176:179], v[88:91]
	v_mfma_f32_16x16x32_bf16 v[76:79], v[120:123], v[184:187], v[76:79]
	v_mfma_f32_16x16x32_bf16 v[72:75], v[136:139], v[184:187], v[72:75]
	v_mfma_f32_16x16x32_bf16 v[132:135], v[128:131], v[164:167], v[132:135]
	v_mfma_f32_16x16x32_bf16 v[124:127], v[140:143], v[164:167], v[124:127]
	v_mfma_f32_16x16x32_bf16 v[108:111], v[128:131], v[172:175], v[108:111]
	v_mfma_f32_16x16x32_bf16 v[104:107], v[140:143], v[172:175], v[104:107]
	v_mfma_f32_16x16x32_bf16 v[92:95], v[128:131], v[180:183], v[92:95]
	v_mfma_f32_16x16x32_bf16 v[88:91], v[140:143], v[180:183], v[88:91]
	v_mfma_f32_16x16x32_bf16 v[76:79], v[128:131], v[188:191], v[76:79]
	v_mfma_f32_16x16x32_bf16 v[72:75], v[140:143], v[188:191], v[72:75]
	v_mfma_f32_16x16x32_bf16 v[116:119], v[144:147], v[160:163], v[116:119]
	v_mfma_f32_16x16x32_bf16 v[112:115], v[152:155], v[160:163], v[112:115]
	v_mfma_f32_16x16x32_bf16 v[100:103], v[144:147], v[168:171], v[100:103]
	v_mfma_f32_16x16x32_bf16 v[96:99], v[152:155], v[168:171], v[96:99]
	v_mfma_f32_16x16x32_bf16 v[84:87], v[144:147], v[176:179], v[84:87]
	v_mfma_f32_16x16x32_bf16 v[80:83], v[152:155], v[176:179], v[80:83]
	v_mfma_f32_16x16x32_bf16 v[68:71], v[144:147], v[184:187], v[68:71]
	v_mfma_f32_16x16x32_bf16 v[64:67], v[152:155], v[184:187], v[64:67]
	v_mfma_f32_16x16x32_bf16 v[116:119], v[148:151], v[164:167], v[116:119]
	v_mfma_f32_16x16x32_bf16 v[112:115], v[156:159], v[164:167], v[112:115]
	v_mfma_f32_16x16x32_bf16 v[100:103], v[148:151], v[172:175], v[100:103]
	v_mfma_f32_16x16x32_bf16 v[96:99], v[156:159], v[172:175], v[96:99]
	v_mfma_f32_16x16x32_bf16 v[84:87], v[148:151], v[180:183], v[84:87]
	v_mfma_f32_16x16x32_bf16 v[80:83], v[156:159], v[180:183], v[80:83]
	v_mfma_f32_16x16x32_bf16 v[68:71], v[148:151], v[188:191], v[68:71]
	v_mfma_f32_16x16x32_bf16 v[64:67], v[156:159], v[188:191], v[64:67]
	s_barrier
	s_setprio 0
	s_add_i32 s28, s54, s34
	v_lshl_add_u64 v[204:205], v[204:205], 0, s[18:19]
	s_mov_b32 m0, s28
	ds_read_b128 v[160:163], v247 offset:49152
	ds_read_b128 v[164:167], v247 offset:50176
	ds_read_b128 v[168:171], v247 offset:51200
	ds_read_b128 v[172:175], v247 offset:52224
	ds_read_b128 v[176:179], v247 offset:53248
	ds_read_b128 v[180:183], v247 offset:54272
	ds_read_b128 v[184:187], v247 offset:55296
	ds_read_b128 v[188:191], v247 offset:56320
	global_load_lds_dwordx4 v[204:205], off
	s_add_i32 m0, s28, 0x2000
	s_add_u32 s26, s26, 0xb0080
	v_lshl_add_u64 v[204:205], v[206:207], 0, s[18:19]
	s_addc_u32 s27, s27, 0
	s_add_i32 s28, s55, s34
	global_load_lds_dwordx4 v[204:205], off
	s_mov_b32 m0, s28
	s_nop 0
	global_load_lds_dwordx4 v194, s[26:27]
	s_add_i32 m0, s28, 0x2000
	s_nop 0
	global_load_lds_dwordx4 v198, s[26:27]
	v_lshl_add_u64 v[204:205], v[208:209], 0, s[18:19]
	s_mov_b32 m0, s40
	s_nop 0
	global_load_lds_dwordx4 v[204:205], off
	v_lshl_add_u64 v[204:205], v[210:211], 0, s[18:19]
	s_mov_b32 m0, s41
	s_nop 0
	global_load_lds_dwordx4 v[204:205], off
	s_waitcnt vmcnt(8)
	s_waitcnt lgkmcnt(0)
	s_setprio 1
	s_barrier
	v_mfma_f32_16x16x32_bf16 v[60:63], v[120:123], v[160:163], v[60:63]
	v_mfma_f32_16x16x32_bf16 v[56:59], v[136:139], v[160:163], v[56:59]
	v_mfma_f32_16x16x32_bf16 v[44:47], v[120:123], v[168:171], v[44:47]
	v_mfma_f32_16x16x32_bf16 v[40:43], v[136:139], v[168:171], v[40:43]
	v_mfma_f32_16x16x32_bf16 v[28:31], v[120:123], v[176:179], v[28:31]
	v_mfma_f32_16x16x32_bf16 v[24:27], v[136:139], v[176:179], v[24:27]
	v_mfma_f32_16x16x32_bf16 v[12:15], v[120:123], v[184:187], v[12:15]
	v_mfma_f32_16x16x32_bf16 v[8:11], v[136:139], v[184:187], v[8:11]
	v_mfma_f32_16x16x32_bf16 v[60:63], v[128:131], v[164:167], v[60:63]
	v_mfma_f32_16x16x32_bf16 v[56:59], v[140:143], v[164:167], v[56:59]
	v_mfma_f32_16x16x32_bf16 v[44:47], v[128:131], v[172:175], v[44:47]
	v_mfma_f32_16x16x32_bf16 v[40:43], v[140:143], v[172:175], v[40:43]
	v_mfma_f32_16x16x32_bf16 v[28:31], v[128:131], v[180:183], v[28:31]
	v_mfma_f32_16x16x32_bf16 v[24:27], v[140:143], v[180:183], v[24:27]
	v_mfma_f32_16x16x32_bf16 v[12:15], v[128:131], v[188:191], v[12:15]
	v_mfma_f32_16x16x32_bf16 v[8:11], v[140:143], v[188:191], v[8:11]
	v_mfma_f32_16x16x32_bf16 v[52:55], v[144:147], v[160:163], v[52:55]
	v_mfma_f32_16x16x32_bf16 v[48:51], v[152:155], v[160:163], v[48:51]
	v_mfma_f32_16x16x32_bf16 v[36:39], v[144:147], v[168:171], v[36:39]
	v_mfma_f32_16x16x32_bf16 v[32:35], v[152:155], v[168:171], v[32:35]
	v_mfma_f32_16x16x32_bf16 v[20:23], v[144:147], v[176:179], v[20:23]
	v_mfma_f32_16x16x32_bf16 v[16:19], v[152:155], v[176:179], v[16:19]
	v_mfma_f32_16x16x32_bf16 v[4:7], v[144:147], v[184:187], v[4:7]
	v_mfma_f32_16x16x32_bf16 v[0:3], v[152:155], v[184:187], v[0:3]
	v_mfma_f32_16x16x32_bf16 v[52:55], v[148:151], v[164:167], v[52:55]
	v_mfma_f32_16x16x32_bf16 v[48:51], v[156:159], v[164:167], v[48:51]
	v_mfma_f32_16x16x32_bf16 v[36:39], v[148:151], v[172:175], v[36:39]
	v_mfma_f32_16x16x32_bf16 v[32:35], v[156:159], v[172:175], v[32:35]
	v_mfma_f32_16x16x32_bf16 v[20:23], v[148:151], v[180:183], v[20:23]
	v_mfma_f32_16x16x32_bf16 v[16:19], v[156:159], v[180:183], v[16:19]
	v_mfma_f32_16x16x32_bf16 v[4:7], v[148:151], v[188:191], v[4:7]
	v_mfma_f32_16x16x32_bf16 v[0:3], v[156:159], v[188:191], v[0:3]
	s_barrier
	s_setprio 0
	s_add_i32 s53, s53, 2
	s_add_u32 s24, s24, 0x100
	s_addc_u32 s25, s25, 0
	s_add_u32 s51, s51, 0x100
	s_addc_u32 s52, s52, 0
	s_cmp_gt_u32 s53, 41
; #define PG8_STAGE(bufoff, gbase, voff) do { _Pragma("unroll") for (int _i = 0; _i < 2; ++_i) \
;         __builtin_amdgcn_global_load_lds((const unsigned*)((const char*)(gbase) + (voff)[_i]), (PG8_LAS unsigned*)(lds + (bufoff) + ldsw + _i * 8192), 16, 0, 0); } while (0)
; #define PG8_LDA(dst, b, h) do { _Pragma("unroll") for (int m = 0; m < 4; ++m) _Pragma("unroll") for (int k = 0; k < 2; ++k) dst[m][k] = *(const PG8_LAS bf16x8*)(lds + PG8_SA(b, h) + aoff + m * 2048 + k * 1024); } while (0)
; #define PG8_LDB(dst, b, h) do { _Pragma("unroll") for (int n = 0; n < 2; ++n) _Pragma("unroll") for (int k = 0; k < 2; ++k) dst[n][k] = *(const PG8_LAS bf16x8*)(lds + PG8_SB(b, h) + boff + n * 2048 + k * 1024); } while (0)
; #define PG8_MMA(ai, bj, At, Bt) do { __builtin_amdgcn_s_setprio(1); _Pragma("unroll") for (int m = 0; m < 4; ++m) _Pragma("unroll") for (int n = 0; n < 2; ++n) _Pragma("unroll") for (int k = 0; k < 2; ++k) \
;         acc[ai][bj][m][n] = __builtin_amdgcn_mfma_f32_16x16x32_bf16(Bt[n][k], At[m][k], acc[ai][bj][m][n], 0, 0, 0); __builtin_amdgcn_s_setprio(0); } while (0)
; #define PG8_WAIT_V(n) asm volatile("s_waitcnt vmcnt(" #n ")" ::: "memory")
; #define PG8_WAIT_L(n) asm volatile("s_waitcnt lgkmcnt(" #n ")" ::: "memory")
; #define PG8_BAR __builtin_amdgcn_s_barrier()
; #define PG8_SCHED __builtin_amdgcn_sched_barrier(0)
; template <class Epi, class Sched, bool ALIGN_EPI = false, bool SP2 = false>
; __device__ __forceinline__ void gemm_phase(PG8_LAS unsigned char* lds, const Gemm g, const Sched& S, const Epi& E) {
;     ...
;             PG8_LDB(B0, 0, 0); PG8_LDB(B1, 0, 1); PG8_SCHED; PG8_LDA(At, 0, 0); PG8_STAGE(PG8_SA(1, 1), a1 + hstep, voffA);
;             PG8_WAIT_V(8); PG8_WAIT_L(0); PG8_BAR; PG8_MMA(0, 0, At, B0); PG8_MMA(0, 1, At, B1); PG8_BAR; PG8_SCHED;
;             PG8_LDA(At, 0, 1); PG8_STAGE(PG8_SB(0, 0), b2, voffB); PG8_STAGE(PG8_SB(0, 1), b2 + hstep, voffB); PG8_STAGE(PG8_SA(0, 0), a2, voffA);
;             PG8_WAIT_V(8); PG8_WAIT_L(0); PG8_BAR; PG8_MMA(1, 0, At, B0); PG8_MMA(1, 1, At, B1); PG8_BAR; PG8_SCHED;
.LBB0_418:
	ds_read_b128 v[120:123], v245
	ds_read_b128 v[128:131], v245 offset:1024
	ds_read_b128 v[136:139], v245 offset:2048
	ds_read_b128 v[140:143], v245 offset:3072
	ds_read_b128 v[144:147], v246
	ds_read_b128 v[148:151], v246 offset:1024
	ds_read_b128 v[152:155], v246 offset:2048
	ds_read_b128 v[156:159], v246 offset:3072
	s_add_u32 s26, s24, 0xfff50080
	s_addc_u32 s27, s25, -1
	s_cmp_eq_u32 s53, 40
	s_cselect_b32 s29, s7, s27
	s_cselect_b32 s28, s6, s26
	s_cselect_b32 s27, s23, s52
	s_cselect_b32 s26, s22, s51
	s_add_i32 m0, s35, 0xc000
	ds_read_b128 v[160:163], v247
	ds_read_b128 v[164:167], v247 offset:1024
	ds_read_b128 v[168:171], v247 offset:2048
	ds_read_b128 v[172:175], v247 offset:3072
	ds_read_b128 v[176:179], v247 offset:4096
	ds_read_b128 v[180:183], v247 offset:5120
	ds_read_b128 v[184:187], v247 offset:6144
	ds_read_b128 v[188:191], v247 offset:7168
	global_load_lds_dwordx4 v200, s[24:25]
	s_add_i32 m0, s35, 0xe000
	s_nop 0
	global_load_lds_dwordx4 v202, s[24:25]
	s_waitcnt vmcnt(8)
	s_waitcnt lgkmcnt(0)
	s_setprio 1
	s_barrier
	v_mfma_f32_16x16x32_bf16 v[132:135], v[120:123], v[160:163], v[132:135]
	v_mfma_f32_16x16x32_bf16 v[124:127], v[136:139], v[160:163], v[124:127]
	v_mfma_f32_16x16x32_bf16 v[108:111], v[120:123], v[168:171], v[108:111]
	v_mfma_f32_16x16x32_bf16 v[104:107], v[136:139], v[168:171], v[104:107]
	v_mfma_f32_16x16x32_bf16 v[92:95], v[120:123], v[176:179], v[92:95]
	v_mfma_f32_16x16x32_bf16 v[88:91], v[136:139], v[176:179], v[88:91]
	v_mfma_f32_16x16x32_bf16 v[76:79], v[120:123], v[184:187], v[76:79]
	v_mfma_f32_16x16x32_bf16 v[72:75], v[136:139], v[184:187], v[72:75]
	v_mfma_f32_16x16x32_bf16 v[132:135], v[128:131], v[164:167], v[132:135]
	v_mfma_f32_16x16x32_bf16 v[124:127], v[140:143], v[164:167], v[124:127]
	v_mfma_f32_16x16x32_bf16 v[108:111], v[128:131], v[172:175], v[108:111]
	v_mfma_f32_16x16x32_bf16 v[104:107], v[140:143], v[172:175], v[104:107]
	v_mfma_f32_16x16x32_bf16 v[92:95], v[128:131], v[180:183], v[92:95]
	v_mfma_f32_16x16x32_bf16 v[88:91], v[140:143], v[180:183], v[88:91]
	v_mfma_f32_16x16x32_bf16 v[76:79], v[128:131], v[188:191], v[76:79]
	v_mfma_f32_16x16x32_bf16 v[72:75], v[140:143], v[188:191], v[72:75]
	v_mfma_f32_16x16x32_bf16 v[116:119], v[144:147], v[160:163], v[116:119]
	v_mfma_f32_16x16x32_bf16 v[112:115], v[152:155], v[160:163], v[112:115]
	v_mfma_f32_16x16x32_bf16 v[100:103], v[144:147], v[168:171], v[100:103]
	v_mfma_f32_16x16x32_bf16 v[96:99], v[152:155], v[168:171], v[96:99]
	v_mfma_f32_16x16x32_bf16 v[84:87], v[144:147], v[176:179], v[84:87]
	v_mfma_f32_16x16x32_bf16 v[80:83], v[152:155], v[176:179], v[80:83]
	v_mfma_f32_16x16x32_bf16 v[68:71], v[144:147], v[184:187], v[68:71]
	v_mfma_f32_16x16x32_bf16 v[64:67], v[152:155], v[184:187], v[64:67]
	v_mfma_f32_16x16x32_bf16 v[116:119], v[148:151], v[164:167], v[116:119]
	v_mfma_f32_16x16x32_bf16 v[112:115], v[156:159], v[164:167], v[112:115]
	v_mfma_f32_16x16x32_bf16 v[100:103], v[148:151], v[172:175], v[100:103]
	v_mfma_f32_16x16x32_bf16 v[96:99], v[156:159], v[172:175], v[96:99]
	v_mfma_f32_16x16x32_bf16 v[84:87], v[148:151], v[180:183], v[84:87]
	v_mfma_f32_16x16x32_bf16 v[80:83], v[156:159], v[180:183], v[80:83]
	v_mfma_f32_16x16x32_bf16 v[68:71], v[148:151], v[188:191], v[68:71]
	v_mfma_f32_16x16x32_bf16 v[64:67], v[156:159], v[188:191], v[64:67]
	s_barrier
	s_setprio 0
	s_add_i32 s54, s45, s34
	v_lshl_add_u64 v[204:205], s[26:27], 0, v[194:195]
	s_mov_b32 m0, s54
	ds_read_b128 v[160:163], v247 offset:16384
	ds_read_b128 v[164:167], v247 offset:17408
	ds_read_b128 v[168:171], v247 offset:18432
	ds_read_b128 v[172:175], v247 offset:19456
	ds_read_b128 v[176:179], v247 offset:20480
	ds_read_b128 v[180:183], v247 offset:21504
	ds_read_b128 v[184:187], v247 offset:22528
	ds_read_b128 v[188:191], v247 offset:23552
	global_load_lds_dwordx4 v[204:205], off
	s_add_i32 m0, s54, 0x2000
	s_add_u32 s54, s26, 0xb0000
	v_lshl_add_u64 v[206:207], s[26:27], 0, v[198:199]
	s_addc_u32 s55, s27, 0
	s_add_i32 s56, s46, s34
	global_load_lds_dwordx4 v[206:207], off
	s_mov_b32 m0, s56
	v_lshl_add_u64 v[210:211], s[28:29], 0, v[196:197]
	global_load_lds_dwordx4 v194, s[54:55]
	s_add_i32 m0, s56, 0x2000
	s_nop 0
	global_load_lds_dwordx4 v198, s[54:55]
	v_lshl_add_u64 v[208:209], s[28:29], 0, v[192:193]
	s_mov_b32 m0, s35
	s_nop 0
	global_load_lds_dwordx4 v[208:209], off
	s_mov_b32 m0, s36
	s_nop 0
	global_load_lds_dwordx4 v[210:211], off
	s_waitcnt vmcnt(8)
	s_waitcnt lgkmcnt(0)
	s_setprio 1
	s_barrier
	v_mfma_f32_16x16x32_bf16 v[60:63], v[120:123], v[160:163], v[60:63]
	v_mfma_f32_16x16x32_bf16 v[56:59], v[136:139], v[160:163], v[56:59]
	v_mfma_f32_16x16x32_bf16 v[44:47], v[120:123], v[168:171], v[44:47]
	v_mfma_f32_16x16x32_bf16 v[40:43], v[136:139], v[168:171], v[40:43]
	v_mfma_f32_16x16x32_bf16 v[28:31], v[120:123], v[176:179], v[28:31]
	v_mfma_f32_16x16x32_bf16 v[24:27], v[136:139], v[176:179], v[24:27]
	v_mfma_f32_16x16x32_bf16 v[12:15], v[120:123], v[184:187], v[12:15]
	v_mfma_f32_16x16x32_bf16 v[8:11], v[136:139], v[184:187], v[8:11]
	v_mfma_f32_16x16x32_bf16 v[60:63], v[128:131], v[164:167], v[60:63]
	v_mfma_f32_16x16x32_bf16 v[56:59], v[140:143], v[164:167], v[56:59]
	v_mfma_f32_16x16x32_bf16 v[44:47], v[128:131], v[172:175], v[44:47]
	v_mfma_f32_16x16x32_bf16 v[40:43], v[140:143], v[172:175], v[40:43]
	v_mfma_f32_16x16x32_bf16 v[28:31], v[128:131], v[180:183], v[28:31]
	v_mfma_f32_16x16x32_bf16 v[24:27], v[140:143], v[180:183], v[24:27]
	v_mfma_f32_16x16x32_bf16 v[12:15], v[128:131], v[188:191], v[12:15]
	v_mfma_f32_16x16x32_bf16 v[8:11], v[140:143], v[188:191], v[8:11]
	v_mfma_f32_16x16x32_bf16 v[52:55], v[144:147], v[160:163], v[52:55]
	v_mfma_f32_16x16x32_bf16 v[48:51], v[152:155], v[160:163], v[48:51]
	v_mfma_f32_16x16x32_bf16 v[36:39], v[144:147], v[168:171], v[36:39]
	v_mfma_f32_16x16x32_bf16 v[32:35], v[152:155], v[168:171], v[32:35]
	v_mfma_f32_16x16x32_bf16 v[20:23], v[144:147], v[176:179], v[20:23]
	v_mfma_f32_16x16x32_bf16 v[16:19], v[152:155], v[176:179], v[16:19]
	v_mfma_f32_16x16x32_bf16 v[4:7], v[144:147], v[184:187], v[4:7]
	v_mfma_f32_16x16x32_bf16 v[0:3], v[152:155], v[184:187], v[0:3]
	v_mfma_f32_16x16x32_bf16 v[52:55], v[148:151], v[164:167], v[52:55]
	v_mfma_f32_16x16x32_bf16 v[48:51], v[156:159], v[164:167], v[48:51]
	v_mfma_f32_16x16x32_bf16 v[36:39], v[148:151], v[172:175], v[36:39]
	v_mfma_f32_16x16x32_bf16 v[32:35], v[156:159], v[172:175], v[32:35]
	v_mfma_f32_16x16x32_bf16 v[20:23], v[148:151], v[180:183], v[20:23]
	v_mfma_f32_16x16x32_bf16 v[16:19], v[156:159], v[180:183], v[16:19]
	v_mfma_f32_16x16x32_bf16 v[4:7], v[148:151], v[188:191], v[4:7]
	v_mfma_f32_16x16x32_bf16 v[0:3], v[156:159], v[188:191], v[0:3]
	s_barrier
; #define PG8_STAGE(bufoff, gbase, voff) do { _Pragma("unroll") for (int _i = 0; _i < 2; ++_i) \
;         __builtin_amdgcn_global_load_lds((const unsigned*)((const char*)(gbase) + (voff)[_i]), (PG8_LAS unsigned*)(lds + (bufoff) + ldsw + _i * 8192), 16, 0, 0); } while (0)
; #define PG8_LDA(dst, b, h) do { _Pragma("unroll") for (int m = 0; m < 4; ++m) _Pragma("unroll") for (int k = 0; k < 2; ++k) dst[m][k] = *(const PG8_LAS bf16x8*)(lds + PG8_SA(b, h) + aoff + m * 2048 + k * 1024); } while (0)
; #define PG8_LDB(dst, b, h) do { _Pragma("unroll") for (int n = 0; n < 2; ++n) _Pragma("unroll") for (int k = 0; k < 2; ++k) dst[n][k] = *(const PG8_LAS bf16x8*)(lds + PG8_SB(b, h) + boff + n * 2048 + k * 1024); } while (0)
; #define PG8_MMA(ai, bj, At, Bt) do { __builtin_amdgcn_s_setprio(1); _Pragma("unroll") for (int m = 0; m < 4; ++m) _Pragma("unroll") for (int n = 0; n < 2; ++n) _Pragma("unroll") for (int k = 0; k < 2; ++k) \
;         acc[ai][bj][m][n] = __builtin_amdgcn_mfma_f32_16x16x32_bf16(Bt[n][k], At[m][k], acc[ai][bj][m][n], 0, 0, 0); __builtin_amdgcn_s_setprio(0); } while (0)
; #define PG8_WAIT_V(n) asm volatile("s_waitcnt vmcnt(" #n ")" ::: "memory")
; #define PG8_WAIT_L(n) asm volatile("s_waitcnt lgkmcnt(" #n ")" ::: "memory")
; #define PG8_BAR __builtin_amdgcn_s_barrier()
; #define PG8_SCHED __builtin_amdgcn_sched_barrier(0)
; template <class Epi, class Sched, bool ALIGN_EPI = false, bool SP2 = false>
; __device__ __forceinline__ void gemm_phase(PG8_LAS unsigned char* lds, const Gemm g, const Sched& S, const Epi& E) {
;     ...
;             PG8_LDB(B0, 1, 0); PG8_LDB(B1, 1, 1); PG8_SCHED; PG8_LDA(At, 1, 0); PG8_STAGE(PG8_SA(0, 1), a2 + hstep, voffA);
;             PG8_WAIT_V(8); PG8_WAIT_L(0); PG8_BAR; PG8_MMA(0, 0, At, B0); PG8_MMA(0, 1, At, B1); PG8_BAR; PG8_SCHED;
;             PG8_LDA(At, 1, 1); PG8_STAGE(PG8_SB(1, 0), b3, voffB); PG8_STAGE(PG8_SB(1, 1), b3 + hstep, voffB); PG8_STAGE(PG8_SA(1, 0), a3, voffA);
;             PG8_WAIT_V(8); PG8_WAIT_L(0); PG8_BAR; PG8_MMA(1, 0, At, B0); PG8_MMA(1, 1, At, B1); PG8_BAR; PG8_SCHED;
;     ...
;         if constexpr (ALIGN_EPI) { if (wr == 0) PG8_BAR; }
	s_setprio 0
	s_add_i32 s54, 0, 0x18000
	s_add_i32 s55, 0, 0x1c000
	v_add_u32_e32 v140, s54, v243
	v_add_u32_e32 v156, s55, v243
	ds_read_b128 v[120:123], v140
	ds_read_b128 v[128:131], v140 offset:1024
	ds_read_b128 v[136:139], v140 offset:2048
	ds_read_b128 v[140:143], v140 offset:3072
	ds_read_b128 v[144:147], v156
	ds_read_b128 v[148:151], v156 offset:1024
	ds_read_b128 v[152:155], v156 offset:2048
	ds_read_b128 v[156:159], v156 offset:3072
	s_add_u32 s28, s28, 0xb0000
	s_addc_u32 s29, s29, 0
	s_mov_b32 m0, s37
	ds_read_b128 v[160:163], v247 offset:32768
	ds_read_b128 v[164:167], v247 offset:33792
	ds_read_b128 v[168:171], v247 offset:34816
	ds_read_b128 v[172:175], v247 offset:35840
	ds_read_b128 v[176:179], v247 offset:36864
	ds_read_b128 v[180:183], v247 offset:37888
	ds_read_b128 v[184:187], v247 offset:38912
	ds_read_b128 v[188:191], v247 offset:39936
	global_load_lds_dwordx4 v192, s[28:29]
	v_lshl_add_u64 v[212:213], s[28:29], 0, v[196:197]
	s_mov_b32 m0, s38
	s_nop 0
	global_load_lds_dwordx4 v[212:213], off
	s_waitcnt vmcnt(8)
	s_waitcnt lgkmcnt(0)
	s_setprio 1
	s_barrier
	v_mfma_f32_16x16x32_bf16 v[132:135], v[120:123], v[160:163], v[132:135]
	v_mfma_f32_16x16x32_bf16 v[124:127], v[136:139], v[160:163], v[124:127]
	v_mfma_f32_16x16x32_bf16 v[108:111], v[120:123], v[168:171], v[108:111]
	v_mfma_f32_16x16x32_bf16 v[104:107], v[136:139], v[168:171], v[104:107]
	v_mfma_f32_16x16x32_bf16 v[92:95], v[120:123], v[176:179], v[92:95]
	v_mfma_f32_16x16x32_bf16 v[88:91], v[136:139], v[176:179], v[88:91]
	v_mfma_f32_16x16x32_bf16 v[76:79], v[120:123], v[184:187], v[76:79]
	v_mfma_f32_16x16x32_bf16 v[72:75], v[136:139], v[184:187], v[72:75]
	v_mfma_f32_16x16x32_bf16 v[132:135], v[128:131], v[164:167], v[132:135]
	v_mfma_f32_16x16x32_bf16 v[124:127], v[140:143], v[164:167], v[124:127]
	v_mfma_f32_16x16x32_bf16 v[108:111], v[128:131], v[172:175], v[108:111]
	v_mfma_f32_16x16x32_bf16 v[104:107], v[140:143], v[172:175], v[104:107]
	v_mfma_f32_16x16x32_bf16 v[92:95], v[128:131], v[180:183], v[92:95]
	v_mfma_f32_16x16x32_bf16 v[88:91], v[140:143], v[180:183], v[88:91]
	v_mfma_f32_16x16x32_bf16 v[76:79], v[128:131], v[188:191], v[76:79]
	v_mfma_f32_16x16x32_bf16 v[72:75], v[140:143], v[188:191], v[72:75]
	v_mfma_f32_16x16x32_bf16 v[116:119], v[144:147], v[160:163], v[116:119]
	v_mfma_f32_16x16x32_bf16 v[112:115], v[152:155], v[160:163], v[112:115]
	v_mfma_f32_16x16x32_bf16 v[100:103], v[144:147], v[168:171], v[100:103]
	v_mfma_f32_16x16x32_bf16 v[96:99], v[152:155], v[168:171], v[96:99]
	v_mfma_f32_16x16x32_bf16 v[84:87], v[144:147], v[176:179], v[84:87]
	v_mfma_f32_16x16x32_bf16 v[80:83], v[152:155], v[176:179], v[80:83]
	v_mfma_f32_16x16x32_bf16 v[68:71], v[144:147], v[184:187], v[68:71]
	v_mfma_f32_16x16x32_bf16 v[64:67], v[152:155], v[184:187], v[64:67]
	v_mfma_f32_16x16x32_bf16 v[116:119], v[148:151], v[164:167], v[116:119]
	v_mfma_f32_16x16x32_bf16 v[112:115], v[156:159], v[164:167], v[112:115]
	v_mfma_f32_16x16x32_bf16 v[100:103], v[148:151], v[172:175], v[100:103]
	v_mfma_f32_16x16x32_bf16 v[96:99], v[156:159], v[172:175], v[96:99]
	v_mfma_f32_16x16x32_bf16 v[84:87], v[148:151], v[180:183], v[84:87]
	v_mfma_f32_16x16x32_bf16 v[80:83], v[156:159], v[180:183], v[80:83]
	v_mfma_f32_16x16x32_bf16 v[68:71], v[148:151], v[188:191], v[68:71]
	v_mfma_f32_16x16x32_bf16 v[64:67], v[156:159], v[188:191], v[64:67]
	s_barrier
	s_setprio 0
	s_add_i32 s28, s54, s34
	v_lshl_add_u64 v[204:205], v[204:205], 0, s[18:19]
	s_mov_b32 m0, s28
	ds_read_b128 v[160:163], v247 offset:49152
	ds_read_b128 v[164:167], v247 offset:50176
	ds_read_b128 v[168:171], v247 offset:51200
	ds_read_b128 v[172:175], v247 offset:52224
	ds_read_b128 v[176:179], v247 offset:53248
	ds_read_b128 v[180:183], v247 offset:54272
	ds_read_b128 v[184:187], v247 offset:55296
	ds_read_b128 v[188:191], v247 offset:56320
	global_load_lds_dwordx4 v[204:205], off
	s_add_i32 m0, s28, 0x2000
	s_add_u32 s26, s26, 0xb0080
	v_lshl_add_u64 v[204:205], v[206:207], 0, s[18:19]
	s_addc_u32 s27, s27, 0
	s_add_i32 s28, s55, s34
	global_load_lds_dwordx4 v[204:205], off
	s_mov_b32 m0, s28
	s_nop 0
	global_load_lds_dwordx4 v194, s[26:27]
	s_add_i32 m0, s28, 0x2000
	s_nop 0
	global_load_lds_dwordx4 v198, s[26:27]
	v_lshl_add_u64 v[204:205], v[208:209], 0, s[18:19]
	s_mov_b32 m0, s40
	s_nop 0
	global_load_lds_dwordx4 v[204:205], off
	v_lshl_add_u64 v[204:205], v[210:211], 0, s[18:19]
	s_mov_b32 m0, s41
	s_nop 0
	global_load_lds_dwordx4 v[204:205], off
	s_waitcnt vmcnt(8)
	s_waitcnt lgkmcnt(0)
	s_setprio 1
	s_barrier
	v_mfma_f32_16x16x32_bf16 v[60:63], v[120:123], v[160:163], v[60:63]
	v_mfma_f32_16x16x32_bf16 v[56:59], v[136:139], v[160:163], v[56:59]
	v_mfma_f32_16x16x32_bf16 v[44:47], v[120:123], v[168:171], v[44:47]
	v_mfma_f32_16x16x32_bf16 v[40:43], v[136:139], v[168:171], v[40:43]
	v_mfma_f32_16x16x32_bf16 v[28:31], v[120:123], v[176:179], v[28:31]
	v_mfma_f32_16x16x32_bf16 v[24:27], v[136:139], v[176:179], v[24:27]
	v_mfma_f32_16x16x32_bf16 v[12:15], v[120:123], v[184:187], v[12:15]
	v_mfma_f32_16x16x32_bf16 v[8:11], v[136:139], v[184:187], v[8:11]
	v_mfma_f32_16x16x32_bf16 v[60:63], v[128:131], v[164:167], v[60:63]
	v_mfma_f32_16x16x32_bf16 v[56:59], v[140:143], v[164:167], v[56:59]
	v_mfma_f32_16x16x32_bf16 v[44:47], v[128:131], v[172:175], v[44:47]
	v_mfma_f32_16x16x32_bf16 v[40:43], v[140:143], v[172:175], v[40:43]
	v_mfma_f32_16x16x32_bf16 v[28:31], v[128:131], v[180:183], v[28:31]
	v_mfma_f32_16x16x32_bf16 v[24:27], v[140:143], v[180:183], v[24:27]
	v_mfma_f32_16x16x32_bf16 v[12:15], v[128:131], v[188:191], v[12:15]
	v_mfma_f32_16x16x32_bf16 v[8:11], v[140:143], v[188:191], v[8:11]
	v_mfma_f32_16x16x32_bf16 v[52:55], v[144:147], v[160:163], v[52:55]
	v_mfma_f32_16x16x32_bf16 v[48:51], v[152:155], v[160:163], v[48:51]
	v_mfma_f32_16x16x32_bf16 v[36:39], v[144:147], v[168:171], v[36:39]
	v_mfma_f32_16x16x32_bf16 v[32:35], v[152:155], v[168:171], v[32:35]
	v_mfma_f32_16x16x32_bf16 v[20:23], v[144:147], v[176:179], v[20:23]
	v_mfma_f32_16x16x32_bf16 v[16:19], v[152:155], v[176:179], v[16:19]
	v_mfma_f32_16x16x32_bf16 v[4:7], v[144:147], v[184:187], v[4:7]
	v_mfma_f32_16x16x32_bf16 v[0:3], v[152:155], v[184:187], v[0:3]
	v_mfma_f32_16x16x32_bf16 v[52:55], v[148:151], v[164:167], v[52:55]
	v_mfma_f32_16x16x32_bf16 v[48:51], v[156:159], v[164:167], v[48:51]
	v_mfma_f32_16x16x32_bf16 v[36:39], v[148:151], v[172:175], v[36:39]
	v_mfma_f32_16x16x32_bf16 v[32:35], v[156:159], v[172:175], v[32:35]
	v_mfma_f32_16x16x32_bf16 v[20:23], v[148:151], v[180:183], v[20:23]
	v_mfma_f32_16x16x32_bf16 v[16:19], v[156:159], v[180:183], v[16:19]
	v_mfma_f32_16x16x32_bf16 v[4:7], v[148:151], v[188:191], v[4:7]
	v_mfma_f32_16x16x32_bf16 v[0:3], v[156:159], v[188:191], v[0:3]
	s_barrier
	s_setprio 0
	s_add_i32 s53, s53, 2
	s_add_u32 s24, s24, 0x100
	s_addc_u32 s25, s25, 0
	s_add_u32 s51, s51, 0x100
	s_addc_u32 s52, s52, 0
	s_cmp_gt_u32 s53, 41
	s_cbranch_scc0 .LBB0_418
	s_and_b64 vcc, exec, s[20:21]
	s_cbranch_vccz .LBB0_421
	s_barrier

; #define PG8_STAGE(bufoff, gbase, voff) do { _Pragma("unroll") for (int _i = 0; _i < 2; ++_i) \
;         __builtin_amdgcn_global_load_lds((const unsigned*)((const char*)(gbase) + (voff)[_i]), (PG8_LAS unsigned*)(lds + (bufoff) + ldsw + _i * 8192), 16, 0, 0); } while (0)
; #define PG8_LDA(dst, b, h) do { _Pragma("unroll") for (int m = 0; m < 4; ++m) _Pragma("unroll") for (int k = 0; k < 2; ++k) dst[m][k] = *(const PG8_LAS bf16x8*)(lds + PG8_SA(b, h) + aoff + m * 2048 + k * 1024); } while (0)
; #define PG8_LDB(dst, b, h) do { _Pragma("unroll") for (int n = 0; n < 2; ++n) _Pragma("unroll") for (int k = 0; k < 2; ++k) dst[n][k] = *(const PG8_LAS bf16x8*)(lds + PG8_SB(b, h) + boff + n * 2048 + k * 1024); } while (0)
; #define PG8_MMA(ai, bj, At, Bt) do { __builtin_amdgcn_s_setprio(1); _Pragma("unroll") for (int m = 0; m < 4; ++m) _Pragma("unroll") for (int n = 0; n < 2; ++n) _Pragma("unroll") for (int k = 0; k < 2; ++k) \
;         acc[ai][bj][m][n] = __builtin_amdgcn_mfma_f32_16x16x32_bf16(Bt[n][k], At[m][k], acc[ai][bj][m][n], 0, 0, 0); __builtin_amdgcn_s_setprio(0); } while (0)
; #define PG8_WAIT_V(n) asm volatile("s_waitcnt vmcnt(" #n ")" ::: "memory")
; #define PG8_WAIT_L(n) asm volatile("s_waitcnt lgkmcnt(" #n ")" ::: "memory")
; #define PG8_BAR __builtin_amdgcn_s_barrier()
; #define PG8_SCHED __builtin_amdgcn_sched_barrier(0)
; template <class Epi, class Sched, bool ALIGN_EPI = false, bool SP2 = false>
; __device__ __forceinline__ void gemm_phase(PG8_LAS unsigned char* lds, const Gemm g, const Sched& S, const Epi& E) {
;     ...
;             PG8_LDB(B0, 0, 0); PG8_LDB(B1, 0, 1); PG8_SCHED; PG8_LDA(At, 0, 0); PG8_STAGE(PG8_SA(1, 1), a1 + hstep, voffA);
;             PG8_WAIT_V(8); PG8_WAIT_L(0); PG8_BAR; PG8_MMA(0, 0, At, B0); PG8_MMA(0, 1, At, B1); PG8_BAR; PG8_SCHED;
;             PG8_LDA(At, 0, 1); PG8_STAGE(PG8_SB(0, 0), b2, voffB); PG8_STAGE(PG8_SB(0, 1), b2 + hstep, voffB); PG8_STAGE(PG8_SA(0, 0), a2, voffA);
;             PG8_WAIT_V(8); PG8_WAIT_L(0); PG8_BAR; PG8_MMA(1, 0, At, B0); PG8_MMA(1, 1, At, B1); PG8_BAR; PG8_SCHED;
.LBB0_508:
	s_ashr_i32 s31, s30, 31
	s_lshl_b64 s[34:35], s[30:31], 19
	s_add_u32 s34, s48, s34
	s_addc_u32 s35, s49, s35
	s_and_b64 s[36:37], s[4:5], exec
	s_cselect_b32 s9, s35, s39
	s_cselect_b32 s14, s34, s38
	s_ashr_i32 s29, s28, 31
	s_lshl_b64 s[36:37], s[28:29], 19
	s_add_u32 s36, s50, s36
	s_addc_u32 s37, s51, s37
	s_and_b64 s[42:43], s[4:5], exec
	s_cselect_b32 s29, s37, s41
	s_cselect_b32 s31, s36, s40
	s_add_u32 s38, s38, 0x40080
	s_addc_u32 s39, s39, 0
	s_add_u32 s44, s40, 0x100
	s_addc_u32 s45, s41, 0
	s_mov_b32 s70, -2
	s_add_u32 s40, s38, 0xfffc0080
	s_addc_u32 s41, s39, -1
	s_cmp_eq_u32 s70, 12
	s_cselect_b32 s43, s9, s41
	s_cselect_b32 s42, s14, s40
	s_cselect_b32 s41, s29, s45
	s_cselect_b32 s40, s31, s44
	v_lshl_add_u64 v[226:227], s[38:39], 0, v[132:133]
	s_add_i32 m0, s52, 0xc000
	s_nop 0
	global_load_lds_dwordx4 v[226:227], off
	v_lshl_add_u64 v[226:227], s[38:39], 0, v[134:135]
	s_add_i32 m0, s52, 0xe000
	s_nop 0
	global_load_lds_dwordx4 v[226:227], off
	s_waitcnt vmcnt(8)
	s_waitcnt lgkmcnt(0)
	s_setprio 1
	s_barrier
	v_mfma_f32_16x16x32_bf16 v[124:127], v[148:151], v[194:197], 0
	v_mfma_f32_16x16x32_bf16 v[120:123], v[170:173], v[194:197], 0
	v_mfma_f32_16x16x32_bf16 v[108:111], v[148:151], v[202:205], 0
	v_mfma_f32_16x16x32_bf16 v[104:107], v[170:173], v[202:205], 0
	v_mfma_f32_16x16x32_bf16 v[92:95], v[148:151], v[210:213], 0
	v_mfma_f32_16x16x32_bf16 v[88:91], v[170:173], v[210:213], 0
	v_mfma_f32_16x16x32_bf16 v[76:79], v[148:151], v[218:221], 0
	v_mfma_f32_16x16x32_bf16 v[72:75], v[170:173], v[218:221], 0
	v_mfma_f32_16x16x32_bf16 v[124:127], v[166:169], v[198:201], v[124:127]
	v_mfma_f32_16x16x32_bf16 v[120:123], v[174:177], v[198:201], v[120:123]
	v_mfma_f32_16x16x32_bf16 v[108:111], v[166:169], v[206:209], v[108:111]
	v_mfma_f32_16x16x32_bf16 v[104:107], v[174:177], v[206:209], v[104:107]
	v_mfma_f32_16x16x32_bf16 v[92:95], v[166:169], v[214:217], v[92:95]
	v_mfma_f32_16x16x32_bf16 v[88:91], v[174:177], v[214:217], v[88:91]
	v_mfma_f32_16x16x32_bf16 v[76:79], v[166:169], v[222:225], v[76:79]
	v_mfma_f32_16x16x32_bf16 v[72:75], v[174:177], v[222:225], v[72:75]
	v_mfma_f32_16x16x32_bf16 v[116:119], v[178:181], v[194:197], 0
	v_mfma_f32_16x16x32_bf16 v[112:115], v[186:189], v[194:197], 0
	v_mfma_f32_16x16x32_bf16 v[100:103], v[178:181], v[202:205], 0
	v_mfma_f32_16x16x32_bf16 v[96:99], v[186:189], v[202:205], 0
	v_mfma_f32_16x16x32_bf16 v[84:87], v[178:181], v[210:213], 0
	v_mfma_f32_16x16x32_bf16 v[80:83], v[186:189], v[210:213], 0
	v_mfma_f32_16x16x32_bf16 v[68:71], v[178:181], v[218:221], 0
	v_mfma_f32_16x16x32_bf16 v[64:67], v[186:189], v[218:221], 0
	v_mfma_f32_16x16x32_bf16 v[116:119], v[182:185], v[198:201], v[116:119]
	v_mfma_f32_16x16x32_bf16 v[112:115], v[190:193], v[198:201], v[112:115]
	v_mfma_f32_16x16x32_bf16 v[100:103], v[182:185], v[206:209], v[100:103]
	v_mfma_f32_16x16x32_bf16 v[96:99], v[190:193], v[206:209], v[96:99]
	v_mfma_f32_16x16x32_bf16 v[84:87], v[182:185], v[214:217], v[84:87]
	v_mfma_f32_16x16x32_bf16 v[80:83], v[190:193], v[214:217], v[80:83]
	v_mfma_f32_16x16x32_bf16 v[68:71], v[182:185], v[222:225], v[68:71]
	v_mfma_f32_16x16x32_bf16 v[64:67], v[190:193], v[222:225], v[64:67]
	s_barrier
	s_setprio 0
	s_add_i32 s71, s61, s33
	v_lshl_add_u64 v[226:227], s[40:41], 0, v[138:139]
	s_mov_b32 m0, s71
	ds_read_b128 v[194:197], v164 offset:16384
	ds_read_b128 v[198:201], v164 offset:17408
	ds_read_b128 v[202:205], v164 offset:18432
	ds_read_b128 v[206:209], v164 offset:19456
	ds_read_b128 v[210:213], v164 offset:20480
	ds_read_b128 v[214:217], v164 offset:21504
	ds_read_b128 v[218:221], v164 offset:22528
	ds_read_b128 v[222:225], v164 offset:23552
	global_load_lds_dwordx4 v[226:227], off
	s_add_i32 m0, s71, 0x2000
	s_add_u32 s72, s40, 0x40000
	v_lshl_add_u64 v[228:229], s[40:41], 0, v[142:143]
	s_addc_u32 s73, s41, 0
	s_add_i32 s71, s62, s33
	global_load_lds_dwordx4 v[228:229], off
	v_lshl_add_u64 v[230:231], s[72:73], 0, v[138:139]
	s_mov_b32 m0, s71
	v_lshl_add_u64 v[232:233], s[42:43], 0, v[140:141]
	global_load_lds_dwordx4 v[230:231], off
	v_lshl_add_u64 v[230:231], s[72:73], 0, v[142:143]
	s_add_i32 m0, s71, 0x2000
	s_nop 0
	global_load_lds_dwordx4 v[230:231], off
	v_lshl_add_u64 v[230:231], s[42:43], 0, v[136:137]
	s_mov_b32 m0, s52
	s_nop 0
	global_load_lds_dwordx4 v[230:231], off
	s_mov_b32 m0, s53
	s_nop 0
	global_load_lds_dwordx4 v[232:233], off
	s_waitcnt vmcnt(8)
	s_waitcnt lgkmcnt(0)
	s_setprio 1
	s_barrier
	v_mfma_f32_16x16x32_bf16 v[60:63], v[148:151], v[194:197], 0
	v_mfma_f32_16x16x32_bf16 v[56:59], v[170:173], v[194:197], 0
	v_mfma_f32_16x16x32_bf16 v[44:47], v[148:151], v[202:205], 0
	v_mfma_f32_16x16x32_bf16 v[40:43], v[170:173], v[202:205], 0
	v_mfma_f32_16x16x32_bf16 v[28:31], v[148:151], v[210:213], 0
	v_mfma_f32_16x16x32_bf16 v[24:27], v[170:173], v[210:213], 0
	v_mfma_f32_16x16x32_bf16 v[12:15], v[148:151], v[218:221], 0
	v_mfma_f32_16x16x32_bf16 v[8:11], v[170:173], v[218:221], 0
	v_mfma_f32_16x16x32_bf16 v[60:63], v[166:169], v[198:201], v[60:63]
	v_mfma_f32_16x16x32_bf16 v[56:59], v[174:177], v[198:201], v[56:59]
	v_mfma_f32_16x16x32_bf16 v[44:47], v[166:169], v[206:209], v[44:47]
	v_mfma_f32_16x16x32_bf16 v[40:43], v[174:177], v[206:209], v[40:43]
	v_mfma_f32_16x16x32_bf16 v[28:31], v[166:169], v[214:217], v[28:31]
	v_mfma_f32_16x16x32_bf16 v[24:27], v[174:177], v[214:217], v[24:27]
	v_mfma_f32_16x16x32_bf16 v[12:15], v[166:169], v[222:225], v[12:15]
	v_mfma_f32_16x16x32_bf16 v[8:11], v[174:177], v[222:225], v[8:11]
	v_mfma_f32_16x16x32_bf16 v[52:55], v[178:181], v[194:197], 0
	v_mfma_f32_16x16x32_bf16 v[48:51], v[186:189], v[194:197], 0
	v_mfma_f32_16x16x32_bf16 v[36:39], v[178:181], v[202:205], 0
	v_mfma_f32_16x16x32_bf16 v[32:35], v[186:189], v[202:205], 0
	v_mfma_f32_16x16x32_bf16 v[20:23], v[178:181], v[210:213], 0
	v_mfma_f32_16x16x32_bf16 v[16:19], v[186:189], v[210:213], 0
	v_mfma_f32_16x16x32_bf16 v[4:7], v[178:181], v[218:221], 0
	v_mfma_f32_16x16x32_bf16 v[0:3], v[186:189], v[218:221], 0
	v_mfma_f32_16x16x32_bf16 v[52:55], v[182:185], v[198:201], v[52:55]
	v_mfma_f32_16x16x32_bf16 v[48:51], v[190:193], v[198:201], v[48:51]
	v_mfma_f32_16x16x32_bf16 v[36:39], v[182:185], v[206:209], v[36:39]
	v_mfma_f32_16x16x32_bf16 v[32:35], v[190:193], v[206:209], v[32:35]
	v_mfma_f32_16x16x32_bf16 v[20:23], v[182:185], v[214:217], v[20:23]
	v_mfma_f32_16x16x32_bf16 v[16:19], v[190:193], v[214:217], v[16:19]
	v_mfma_f32_16x16x32_bf16 v[4:7], v[182:185], v[222:225], v[4:7]
	v_mfma_f32_16x16x32_bf16 v[0:3], v[190:193], v[222:225], v[0:3]
	s_barrier
; #define PG8_STAGE(bufoff, gbase, voff) do { _Pragma("unroll") for (int _i = 0; _i < 2; ++_i) \
;         __builtin_amdgcn_global_load_lds((const unsigned*)((const char*)(gbase) + (voff)[_i]), (PG8_LAS unsigned*)(lds + (bufoff) + ldsw + _i * 8192), 16, 0, 0); } while (0)
; #define PG8_LDA(dst, b, h) do { _Pragma("unroll") for (int m = 0; m < 4; ++m) _Pragma("unroll") for (int k = 0; k < 2; ++k) dst[m][k] = *(const PG8_LAS bf16x8*)(lds + PG8_SA(b, h) + aoff + m * 2048 + k * 1024); } while (0)
; #define PG8_LDB(dst, b, h) do { _Pragma("unroll") for (int n = 0; n < 2; ++n) _Pragma("unroll") for (int k = 0; k < 2; ++k) dst[n][k] = *(const PG8_LAS bf16x8*)(lds + PG8_SB(b, h) + boff + n * 2048 + k * 1024); } while (0)
; #define PG8_MMA(ai, bj, At, Bt) do { __builtin_amdgcn_s_setprio(1); _Pragma("unroll") for (int m = 0; m < 4; ++m) _Pragma("unroll") for (int n = 0; n < 2; ++n) _Pragma("unroll") for (int k = 0; k < 2; ++k) \
;         acc[ai][bj][m][n] = __builtin_amdgcn_mfma_f32_16x16x32_bf16(Bt[n][k], At[m][k], acc[ai][bj][m][n], 0, 0, 0); __builtin_amdgcn_s_setprio(0); } while (0)
; #define PG8_WAIT_V(n) asm volatile("s_waitcnt vmcnt(" #n ")" ::: "memory")
; #define PG8_WAIT_L(n) asm volatile("s_waitcnt lgkmcnt(" #n ")" ::: "memory")
; #define PG8_BAR __builtin_amdgcn_s_barrier()
; #define PG8_SCHED __builtin_amdgcn_sched_barrier(0)
; template <class Epi, class Sched, bool ALIGN_EPI = false, bool SP2 = false>
; __device__ __forceinline__ void gemm_phase(PG8_LAS unsigned char* lds, const Gemm g, const Sched& S, const Epi& E) {
;     ...
;             PG8_LDB(B0, 1, 0); PG8_LDB(B1, 1, 1); PG8_SCHED; PG8_LDA(At, 1, 0); PG8_STAGE(PG8_SA(0, 1), a2 + hstep, voffA);
;             PG8_WAIT_V(8); PG8_WAIT_L(0); PG8_BAR; PG8_MMA(0, 0, At, B0); PG8_MMA(0, 1, At, B1); PG8_BAR; PG8_SCHED;
;             PG8_LDA(At, 1, 1); PG8_STAGE(PG8_SB(1, 0), b3, voffB); PG8_STAGE(PG8_SB(1, 1), b3 + hstep, voffB); PG8_STAGE(PG8_SA(1, 0), a3, voffA);
;             PG8_WAIT_V(8); PG8_WAIT_L(0); PG8_BAR; PG8_MMA(1, 0, At, B0); PG8_MMA(1, 1, At, B1); PG8_BAR; PG8_SCHED;
	s_setprio 0
	s_add_i32 s71, 0, 0x18000
	v_add_u32_e32 v130, s71, v160
	s_add_i32 s72, 0, 0x1c000
	ds_read_b128 v[148:151], v130
	ds_read_b128 v[166:169], v130 offset:1024
	ds_read_b128 v[170:173], v130 offset:2048
	ds_read_b128 v[174:177], v130 offset:3072
	v_add_u32_e32 v130, s72, v160
	ds_read_b128 v[178:181], v130
	ds_read_b128 v[182:185], v130 offset:1024
	ds_read_b128 v[186:189], v130 offset:2048
	ds_read_b128 v[190:193], v130 offset:3072
	s_add_u32 s42, s42, 0x40000
	s_addc_u32 s43, s43, 0
	s_mov_b32 m0, s54
	v_lshl_add_u64 v[234:235], s[42:43], 0, v[136:137]
	ds_read_b128 v[194:197], v164 offset:32768
	ds_read_b128 v[198:201], v164 offset:33792
	ds_read_b128 v[202:205], v164 offset:34816
	ds_read_b128 v[206:209], v164 offset:35840
	ds_read_b128 v[210:213], v164 offset:36864
	ds_read_b128 v[214:217], v164 offset:37888
	ds_read_b128 v[218:221], v164 offset:38912
	ds_read_b128 v[222:225], v164 offset:39936
	global_load_lds_dwordx4 v[234:235], off
	v_lshl_add_u64 v[234:235], s[42:43], 0, v[140:141]
	s_mov_b32 m0, s55
	s_nop 0
	global_load_lds_dwordx4 v[234:235], off
	s_waitcnt vmcnt(8)
	s_waitcnt lgkmcnt(0)
	s_setprio 1
	s_barrier
	v_mfma_f32_16x16x32_bf16 v[124:127], v[148:151], v[194:197], v[124:127]
	v_mfma_f32_16x16x32_bf16 v[120:123], v[170:173], v[194:197], v[120:123]
	v_mfma_f32_16x16x32_bf16 v[108:111], v[148:151], v[202:205], v[108:111]
	v_mfma_f32_16x16x32_bf16 v[104:107], v[170:173], v[202:205], v[104:107]
	v_mfma_f32_16x16x32_bf16 v[92:95], v[148:151], v[210:213], v[92:95]
	v_mfma_f32_16x16x32_bf16 v[88:91], v[170:173], v[210:213], v[88:91]
	v_mfma_f32_16x16x32_bf16 v[76:79], v[148:151], v[218:221], v[76:79]
	v_mfma_f32_16x16x32_bf16 v[72:75], v[170:173], v[218:221], v[72:75]
	v_mfma_f32_16x16x32_bf16 v[124:127], v[166:169], v[198:201], v[124:127]
	v_mfma_f32_16x16x32_bf16 v[120:123], v[174:177], v[198:201], v[120:123]
	v_mfma_f32_16x16x32_bf16 v[108:111], v[166:169], v[206:209], v[108:111]
	v_mfma_f32_16x16x32_bf16 v[104:107], v[174:177], v[206:209], v[104:107]
	v_mfma_f32_16x16x32_bf16 v[92:95], v[166:169], v[214:217], v[92:95]
	v_mfma_f32_16x16x32_bf16 v[88:91], v[174:177], v[214:217], v[88:91]
	v_mfma_f32_16x16x32_bf16 v[76:79], v[166:169], v[222:225], v[76:79]
	v_mfma_f32_16x16x32_bf16 v[72:75], v[174:177], v[222:225], v[72:75]
	v_mfma_f32_16x16x32_bf16 v[116:119], v[178:181], v[194:197], v[116:119]
	v_mfma_f32_16x16x32_bf16 v[112:115], v[186:189], v[194:197], v[112:115]
	v_mfma_f32_16x16x32_bf16 v[100:103], v[178:181], v[202:205], v[100:103]
	v_mfma_f32_16x16x32_bf16 v[96:99], v[186:189], v[202:205], v[96:99]
	v_mfma_f32_16x16x32_bf16 v[84:87], v[178:181], v[210:213], v[84:87]
	v_mfma_f32_16x16x32_bf16 v[80:83], v[186:189], v[210:213], v[80:83]
	v_mfma_f32_16x16x32_bf16 v[68:71], v[178:181], v[218:221], v[68:71]
	v_mfma_f32_16x16x32_bf16 v[64:67], v[186:189], v[218:221], v[64:67]
	v_mfma_f32_16x16x32_bf16 v[116:119], v[182:185], v[198:201], v[116:119]
	v_mfma_f32_16x16x32_bf16 v[112:115], v[190:193], v[198:201], v[112:115]
	v_mfma_f32_16x16x32_bf16 v[100:103], v[182:185], v[206:209], v[100:103]
	v_mfma_f32_16x16x32_bf16 v[96:99], v[190:193], v[206:209], v[96:99]
	v_mfma_f32_16x16x32_bf16 v[84:87], v[182:185], v[214:217], v[84:87]
	v_mfma_f32_16x16x32_bf16 v[80:83], v[190:193], v[214:217], v[80:83]
	v_mfma_f32_16x16x32_bf16 v[68:71], v[182:185], v[222:225], v[68:71]
	v_mfma_f32_16x16x32_bf16 v[64:67], v[190:193], v[222:225], v[64:67]
	s_barrier
	s_setprio 0
	s_add_i32 s42, s71, s33
	v_lshl_add_u64 v[226:227], v[226:227], 0, s[24:25]
	s_mov_b32 m0, s42
	ds_read_b128 v[194:197], v164 offset:49152
	ds_read_b128 v[198:201], v164 offset:50176
	ds_read_b128 v[202:205], v164 offset:51200
	ds_read_b128 v[206:209], v164 offset:52224
	ds_read_b128 v[210:213], v164 offset:53248
	ds_read_b128 v[214:217], v164 offset:54272
	ds_read_b128 v[218:221], v164 offset:55296
	ds_read_b128 v[222:225], v164 offset:56320
	global_load_lds_dwordx4 v[226:227], off
	s_add_i32 m0, s42, 0x2000
	s_add_u32 s40, s40, 0x40080
	v_lshl_add_u64 v[226:227], v[228:229], 0, s[24:25]
	s_addc_u32 s41, s41, 0
	s_add_i32 s42, s72, s33
	global_load_lds_dwordx4 v[226:227], off
	v_lshl_add_u64 v[226:227], s[40:41], 0, v[138:139]
	s_mov_b32 m0, s42
	s_nop 0
	global_load_lds_dwordx4 v[226:227], off
	v_lshl_add_u64 v[226:227], s[40:41], 0, v[142:143]
	s_add_i32 m0, s42, 0x2000
	s_nop 0
	global_load_lds_dwordx4 v[226:227], off
	v_lshl_add_u64 v[226:227], v[230:231], 0, s[24:25]
	s_mov_b32 m0, s57
	s_nop 0
	global_load_lds_dwordx4 v[226:227], off
	v_lshl_add_u64 v[226:227], v[232:233], 0, s[24:25]
	s_mov_b32 m0, s58
	s_nop 0
	global_load_lds_dwordx4 v[226:227], off
	s_waitcnt vmcnt(8)
	s_waitcnt lgkmcnt(0)
	s_setprio 1
	s_barrier
	v_mfma_f32_16x16x32_bf16 v[60:63], v[148:151], v[194:197], v[60:63]
	v_mfma_f32_16x16x32_bf16 v[56:59], v[170:173], v[194:197], v[56:59]
	v_mfma_f32_16x16x32_bf16 v[44:47], v[148:151], v[202:205], v[44:47]
	v_mfma_f32_16x16x32_bf16 v[40:43], v[170:173], v[202:205], v[40:43]
	v_mfma_f32_16x16x32_bf16 v[28:31], v[148:151], v[210:213], v[28:31]
	v_mfma_f32_16x16x32_bf16 v[24:27], v[170:173], v[210:213], v[24:27]
	v_mfma_f32_16x16x32_bf16 v[12:15], v[148:151], v[218:221], v[12:15]
	v_mfma_f32_16x16x32_bf16 v[8:11], v[170:173], v[218:221], v[8:11]
	v_mfma_f32_16x16x32_bf16 v[60:63], v[166:169], v[198:201], v[60:63]
	v_mfma_f32_16x16x32_bf16 v[56:59], v[174:177], v[198:201], v[56:59]
	v_mfma_f32_16x16x32_bf16 v[44:47], v[166:169], v[206:209], v[44:47]
	v_mfma_f32_16x16x32_bf16 v[40:43], v[174:177], v[206:209], v[40:43]
	v_mfma_f32_16x16x32_bf16 v[28:31], v[166:169], v[214:217], v[28:31]
	v_mfma_f32_16x16x32_bf16 v[24:27], v[174:177], v[214:217], v[24:27]
	v_mfma_f32_16x16x32_bf16 v[12:15], v[166:169], v[222:225], v[12:15]
	v_mfma_f32_16x16x32_bf16 v[8:11], v[174:177], v[222:225], v[8:11]
	v_mfma_f32_16x16x32_bf16 v[52:55], v[178:181], v[194:197], v[52:55]
	v_mfma_f32_16x16x32_bf16 v[48:51], v[186:189], v[194:197], v[48:51]
	v_mfma_f32_16x16x32_bf16 v[36:39], v[178:181], v[202:205], v[36:39]
	v_mfma_f32_16x16x32_bf16 v[32:35], v[186:189], v[202:205], v[32:35]
	v_mfma_f32_16x16x32_bf16 v[20:23], v[178:181], v[210:213], v[20:23]
	v_mfma_f32_16x16x32_bf16 v[16:19], v[186:189], v[210:213], v[16:19]
	v_mfma_f32_16x16x32_bf16 v[4:7], v[178:181], v[218:221], v[4:7]
	v_mfma_f32_16x16x32_bf16 v[0:3], v[186:189], v[218:221], v[0:3]
	v_mfma_f32_16x16x32_bf16 v[52:55], v[182:185], v[198:201], v[52:55]
	v_mfma_f32_16x16x32_bf16 v[48:51], v[190:193], v[198:201], v[48:51]
	v_mfma_f32_16x16x32_bf16 v[36:39], v[182:185], v[206:209], v[36:39]
	v_mfma_f32_16x16x32_bf16 v[32:35], v[190:193], v[206:209], v[32:35]
	v_mfma_f32_16x16x32_bf16 v[20:23], v[182:185], v[214:217], v[20:23]
	v_mfma_f32_16x16x32_bf16 v[16:19], v[190:193], v[214:217], v[16:19]
	v_mfma_f32_16x16x32_bf16 v[4:7], v[182:185], v[222:225], v[4:7]
	v_mfma_f32_16x16x32_bf16 v[0:3], v[190:193], v[222:225], v[0:3]
	s_barrier
	s_setprio 0
	s_add_i32 s70, s70, 2
	s_add_u32 s38, s38, 0x100
	s_addc_u32 s39, s39, 0
	s_add_u32 s44, s44, 0x100
	s_addc_u32 s45, s45, 0
	s_cmp_gt_u32 s70, 13

; #define PG8_STAGE(bufoff, gbase, voff) do { _Pragma("unroll") for (int _i = 0; _i < 2; ++_i) \
;         __builtin_amdgcn_global_load_lds((const unsigned*)((const char*)(gbase) + (voff)[_i]), (PG8_LAS unsigned*)(lds + (bufoff) + ldsw + _i * 8192), 16, 0, 0); } while (0)
; #define PG8_LDA(dst, b, h) do { _Pragma("unroll") for (int m = 0; m < 4; ++m) _Pragma("unroll") for (int k = 0; k < 2; ++k) dst[m][k] = *(const PG8_LAS bf16x8*)(lds + PG8_SA(b, h) + aoff + m * 2048 + k * 1024); } while (0)
; #define PG8_LDB(dst, b, h) do { _Pragma("unroll") for (int n = 0; n < 2; ++n) _Pragma("unroll") for (int k = 0; k < 2; ++k) dst[n][k] = *(const PG8_LAS bf16x8*)(lds + PG8_SB(b, h) + boff + n * 2048 + k * 1024); } while (0)
; #define PG8_MMA(ai, bj, At, Bt) do { __builtin_amdgcn_s_setprio(1); _Pragma("unroll") for (int m = 0; m < 4; ++m) _Pragma("unroll") for (int n = 0; n < 2; ++n) _Pragma("unroll") for (int k = 0; k < 2; ++k) \
;         acc[ai][bj][m][n] = __builtin_amdgcn_mfma_f32_16x16x32_bf16(Bt[n][k], At[m][k], acc[ai][bj][m][n], 0, 0, 0); __builtin_amdgcn_s_setprio(0); } while (0)
; #define PG8_WAIT_V(n) asm volatile("s_waitcnt vmcnt(" #n ")" ::: "memory")
; #define PG8_WAIT_L(n) asm volatile("s_waitcnt lgkmcnt(" #n ")" ::: "memory")
; #define PG8_BAR __builtin_amdgcn_s_barrier()
; #define PG8_SCHED __builtin_amdgcn_sched_barrier(0)
; template <class Epi, class Sched, bool ALIGN_EPI = false, bool SP2 = false>
; __device__ __forceinline__ void gemm_phase(PG8_LAS unsigned char* lds, const Gemm g, const Sched& S, const Epi& E) {
;     ...
;             PG8_LDB(B0, 0, 0); PG8_LDB(B1, 0, 1); PG8_SCHED; PG8_LDA(At, 0, 0); PG8_STAGE(PG8_SA(1, 1), a1 + hstep, voffA);
;             PG8_WAIT_V(8); PG8_WAIT_L(0); PG8_BAR; PG8_MMA(0, 0, At, B0); PG8_MMA(0, 1, At, B1); PG8_BAR; PG8_SCHED;
;             PG8_LDA(At, 0, 1); PG8_STAGE(PG8_SB(0, 0), b2, voffB); PG8_STAGE(PG8_SB(0, 1), b2 + hstep, voffB); PG8_STAGE(PG8_SA(0, 0), a2, voffA);
;             PG8_WAIT_V(8); PG8_WAIT_L(0); PG8_BAR; PG8_MMA(1, 0, At, B0); PG8_MMA(1, 1, At, B1); PG8_BAR; PG8_SCHED;
.LBB0_606:
	s_ashr_i32 s21, s20, 31
	s_lshl_b64 s[22:23], s[20:21], 19
	s_add_u32 s22, s36, s22
	s_addc_u32 s23, s37, s23
	s_and_b64 s[24:25], s[4:5], exec
	s_cselect_b32 s21, s23, s29
	s_cselect_b32 s55, s22, s28
	s_ashr_i32 s19, s18, 31
	s_lshl_b64 s[24:25], s[18:19], 19
	s_add_u32 s24, s48, s24
	s_addc_u32 s25, s49, s25
	s_and_b64 s[34:35], s[4:5], exec
	s_cselect_b32 s19, s25, s31
	s_cselect_b32 s56, s24, s30
	s_add_u32 s28, s28, 0x40080
	s_addc_u32 s29, s29, 0
	s_add_u32 s57, s30, 0x100
	s_addc_u32 s58, s31, 0
	s_mov_b32 s59, -2
	s_add_u32 s30, s28, 0xfffc0080
	s_addc_u32 s31, s29, -1
	s_cmp_eq_u32 s59, 12
	s_cselect_b32 s35, s21, s31
	s_cselect_b32 s34, s55, s30
	s_cselect_b32 s31, s19, s58
	s_cselect_b32 s30, s56, s57
	v_lshl_add_u64 v[160:161], s[28:29], 0, v[152:153]
	s_add_i32 m0, s38, 0xc000
	s_nop 0
	global_load_lds_dwordx4 v[160:161], off
	v_lshl_add_u64 v[160:161], s[28:29], 0, v[154:155]
	s_add_i32 m0, s38, 0xe000
	s_nop 0
	global_load_lds_dwordx4 v[160:161], off
	s_waitcnt vmcnt(8)
	s_waitcnt lgkmcnt(0)
	s_setprio 1
	s_barrier
	v_mfma_f32_16x16x32_bf16 v[124:127], v[128:131], v[198:201], 0
	v_mfma_f32_16x16x32_bf16 v[120:123], v[174:177], v[198:201], 0
	v_mfma_f32_16x16x32_bf16 v[116:119], v[128:131], v[206:209], 0
	v_mfma_f32_16x16x32_bf16 v[112:115], v[174:177], v[206:209], 0
	v_mfma_f32_16x16x32_bf16 v[108:111], v[128:131], v[214:217], 0
	v_mfma_f32_16x16x32_bf16 v[104:107], v[174:177], v[214:217], 0
	v_mfma_f32_16x16x32_bf16 v[100:103], v[128:131], v[222:225], 0
	v_mfma_f32_16x16x32_bf16 v[96:99], v[174:177], v[222:225], 0
	v_mfma_f32_16x16x32_bf16 v[124:127], v[132:135], v[202:205], v[124:127]
	v_mfma_f32_16x16x32_bf16 v[120:123], v[178:181], v[202:205], v[120:123]
	v_mfma_f32_16x16x32_bf16 v[116:119], v[132:135], v[210:213], v[116:119]
	v_mfma_f32_16x16x32_bf16 v[112:115], v[178:181], v[210:213], v[112:115]
	v_mfma_f32_16x16x32_bf16 v[108:111], v[132:135], v[218:221], v[108:111]
	v_mfma_f32_16x16x32_bf16 v[104:107], v[178:181], v[218:221], v[104:107]
	v_mfma_f32_16x16x32_bf16 v[100:103], v[132:135], v[226:229], v[100:103]
	v_mfma_f32_16x16x32_bf16 v[96:99], v[178:181], v[226:229], v[96:99]
	v_mfma_f32_16x16x32_bf16 v[60:63], v[182:185], v[198:201], 0
	v_mfma_f32_16x16x32_bf16 v[56:59], v[190:193], v[198:201], 0
	v_mfma_f32_16x16x32_bf16 v[52:55], v[182:185], v[206:209], 0
	v_mfma_f32_16x16x32_bf16 v[48:51], v[190:193], v[206:209], 0
	v_mfma_f32_16x16x32_bf16 v[44:47], v[182:185], v[214:217], 0
	v_mfma_f32_16x16x32_bf16 v[40:43], v[190:193], v[214:217], 0
	v_mfma_f32_16x16x32_bf16 v[36:39], v[182:185], v[222:225], 0
	v_mfma_f32_16x16x32_bf16 v[32:35], v[190:193], v[222:225], 0
	v_mfma_f32_16x16x32_bf16 v[60:63], v[186:189], v[202:205], v[60:63]
	v_mfma_f32_16x16x32_bf16 v[56:59], v[194:197], v[202:205], v[56:59]
	v_mfma_f32_16x16x32_bf16 v[52:55], v[186:189], v[210:213], v[52:55]
	v_mfma_f32_16x16x32_bf16 v[48:51], v[194:197], v[210:213], v[48:51]
	v_mfma_f32_16x16x32_bf16 v[44:47], v[186:189], v[218:221], v[44:47]
	v_mfma_f32_16x16x32_bf16 v[40:43], v[194:197], v[218:221], v[40:43]
	v_mfma_f32_16x16x32_bf16 v[36:39], v[186:189], v[226:229], v[36:39]
	v_mfma_f32_16x16x32_bf16 v[32:35], v[194:197], v[226:229], v[32:35]
	s_barrier
	s_setprio 0
	s_add_i32 s60, s45, s33
	v_lshl_add_u64 v[160:161], s[30:31], 0, v[138:139]
	s_mov_b32 m0, s60
	ds_read_b128 v[198:201], v172 offset:16384
	ds_read_b128 v[202:205], v172 offset:17408
	ds_read_b128 v[206:209], v172 offset:18432
	ds_read_b128 v[210:213], v172 offset:19456
	ds_read_b128 v[214:217], v172 offset:20480
	ds_read_b128 v[218:221], v172 offset:21504
	ds_read_b128 v[222:225], v172 offset:22528
	ds_read_b128 v[226:229], v172 offset:23552
	global_load_lds_dwordx4 v[160:161], off
	s_add_i32 m0, s60, 0x2000
	s_add_u32 s60, s30, 0x40000
	v_lshl_add_u64 v[230:231], s[30:31], 0, v[142:143]
	s_addc_u32 s61, s31, 0
	s_add_i32 s62, s50, s33
	global_load_lds_dwordx4 v[230:231], off
	v_lshl_add_u64 v[232:233], s[60:61], 0, v[138:139]
	s_mov_b32 m0, s62
	v_lshl_add_u64 v[234:235], s[34:35], 0, v[140:141]
	global_load_lds_dwordx4 v[232:233], off
	v_lshl_add_u64 v[232:233], s[60:61], 0, v[142:143]
	s_add_i32 m0, s62, 0x2000
	s_nop 0
	global_load_lds_dwordx4 v[232:233], off
	v_lshl_add_u64 v[232:233], s[34:35], 0, v[136:137]
	s_mov_b32 m0, s38
	s_nop 0
	global_load_lds_dwordx4 v[232:233], off
	s_mov_b32 m0, s39
	s_nop 0
	global_load_lds_dwordx4 v[234:235], off
	s_waitcnt vmcnt(8)
	s_waitcnt lgkmcnt(0)
	s_setprio 1
	s_barrier
	v_mfma_f32_16x16x32_bf16 v[92:95], v[128:131], v[198:201], 0
	v_mfma_f32_16x16x32_bf16 v[88:91], v[174:177], v[198:201], 0
	v_mfma_f32_16x16x32_bf16 v[84:87], v[128:131], v[206:209], 0
	v_mfma_f32_16x16x32_bf16 v[80:83], v[174:177], v[206:209], 0
	v_mfma_f32_16x16x32_bf16 v[76:79], v[128:131], v[214:217], 0
	v_mfma_f32_16x16x32_bf16 v[72:75], v[174:177], v[214:217], 0
	v_mfma_f32_16x16x32_bf16 v[68:71], v[128:131], v[222:225], 0
	v_mfma_f32_16x16x32_bf16 v[64:67], v[174:177], v[222:225], 0
	v_mfma_f32_16x16x32_bf16 v[92:95], v[132:135], v[202:205], v[92:95]
	v_mfma_f32_16x16x32_bf16 v[88:91], v[178:181], v[202:205], v[88:91]
	v_mfma_f32_16x16x32_bf16 v[84:87], v[132:135], v[210:213], v[84:87]
	v_mfma_f32_16x16x32_bf16 v[80:83], v[178:181], v[210:213], v[80:83]
	v_mfma_f32_16x16x32_bf16 v[76:79], v[132:135], v[218:221], v[76:79]
	v_mfma_f32_16x16x32_bf16 v[72:75], v[178:181], v[218:221], v[72:75]
	v_mfma_f32_16x16x32_bf16 v[68:71], v[132:135], v[226:229], v[68:71]
	v_mfma_f32_16x16x32_bf16 v[64:67], v[178:181], v[226:229], v[64:67]
	v_mfma_f32_16x16x32_bf16 v[28:31], v[182:185], v[198:201], 0
	v_mfma_f32_16x16x32_bf16 v[24:27], v[190:193], v[198:201], 0
	v_mfma_f32_16x16x32_bf16 v[20:23], v[182:185], v[206:209], 0
	v_mfma_f32_16x16x32_bf16 v[16:19], v[190:193], v[206:209], 0
	v_mfma_f32_16x16x32_bf16 v[12:15], v[182:185], v[214:217], 0
	v_mfma_f32_16x16x32_bf16 v[8:11], v[190:193], v[214:217], 0
	v_mfma_f32_16x16x32_bf16 v[4:7], v[182:185], v[222:225], 0
	v_mfma_f32_16x16x32_bf16 v[0:3], v[190:193], v[222:225], 0
	v_mfma_f32_16x16x32_bf16 v[28:31], v[186:189], v[202:205], v[28:31]
	v_mfma_f32_16x16x32_bf16 v[24:27], v[194:197], v[202:205], v[24:27]
	v_mfma_f32_16x16x32_bf16 v[20:23], v[186:189], v[210:213], v[20:23]
	v_mfma_f32_16x16x32_bf16 v[16:19], v[194:197], v[210:213], v[16:19]
	v_mfma_f32_16x16x32_bf16 v[12:15], v[186:189], v[218:221], v[12:15]
	v_mfma_f32_16x16x32_bf16 v[8:11], v[194:197], v[218:221], v[8:11]
	v_mfma_f32_16x16x32_bf16 v[4:7], v[186:189], v[226:229], v[4:7]
	v_mfma_f32_16x16x32_bf16 v[0:3], v[194:197], v[226:229], v[0:3]
	s_barrier
; #define PG8_STAGE(bufoff, gbase, voff) do { _Pragma("unroll") for (int _i = 0; _i < 2; ++_i) \
;         __builtin_amdgcn_global_load_lds((const unsigned*)((const char*)(gbase) + (voff)[_i]), (PG8_LAS unsigned*)(lds + (bufoff) + ldsw + _i * 8192), 16, 0, 0); } while (0)
; #define PG8_LDA(dst, b, h) do { _Pragma("unroll") for (int m = 0; m < 4; ++m) _Pragma("unroll") for (int k = 0; k < 2; ++k) dst[m][k] = *(const PG8_LAS bf16x8*)(lds + PG8_SA(b, h) + aoff + m * 2048 + k * 1024); } while (0)
; #define PG8_LDB(dst, b, h) do { _Pragma("unroll") for (int n = 0; n < 2; ++n) _Pragma("unroll") for (int k = 0; k < 2; ++k) dst[n][k] = *(const PG8_LAS bf16x8*)(lds + PG8_SB(b, h) + boff + n * 2048 + k * 1024); } while (0)
; #define PG8_MMA(ai, bj, At, Bt) do { __builtin_amdgcn_s_setprio(1); _Pragma("unroll") for (int m = 0; m < 4; ++m) _Pragma("unroll") for (int n = 0; n < 2; ++n) _Pragma("unroll") for (int k = 0; k < 2; ++k) \
;         acc[ai][bj][m][n] = __builtin_amdgcn_mfma_f32_16x16x32_bf16(Bt[n][k], At[m][k], acc[ai][bj][m][n], 0, 0, 0); __builtin_amdgcn_s_setprio(0); } while (0)
; #define PG8_WAIT_V(n) asm volatile("s_waitcnt vmcnt(" #n ")" ::: "memory")
; #define PG8_WAIT_L(n) asm volatile("s_waitcnt lgkmcnt(" #n ")" ::: "memory")
; #define PG8_BAR __builtin_amdgcn_s_barrier()
; #define PG8_SCHED __builtin_amdgcn_sched_barrier(0)
; template <class Epi, class Sched, bool ALIGN_EPI = false, bool SP2 = false>
; __device__ __forceinline__ void gemm_phase(PG8_LAS unsigned char* lds, const Gemm g, const Sched& S, const Epi& E) {
;     ...
;             PG8_LDB(B0, 1, 0); PG8_LDB(B1, 1, 1); PG8_SCHED; PG8_LDA(At, 1, 0); PG8_STAGE(PG8_SA(0, 1), a2 + hstep, voffA);
;             PG8_WAIT_V(8); PG8_WAIT_L(0); PG8_BAR; PG8_MMA(0, 0, At, B0); PG8_MMA(0, 1, At, B1); PG8_BAR; PG8_SCHED;
;             PG8_LDA(At, 1, 1); PG8_STAGE(PG8_SB(1, 0), b3, voffB); PG8_STAGE(PG8_SB(1, 1), b3 + hstep, voffB); PG8_STAGE(PG8_SA(1, 0), a3, voffA);
;             PG8_WAIT_V(8); PG8_WAIT_L(0); PG8_BAR; PG8_MMA(1, 0, At, B0); PG8_MMA(1, 1, At, B1); PG8_BAR; PG8_SCHED;
	s_setprio 0
	s_add_i32 s60, 0, 0x18000
	s_add_i32 s61, 0, 0x1c000
	v_add_u32_e32 v178, s60, v163
	v_add_u32_e32 v194, s61, v163
	ds_read_b128 v[128:131], v178
	ds_read_b128 v[132:135], v178 offset:1024
	ds_read_b128 v[174:177], v178 offset:2048
	ds_read_b128 v[178:181], v178 offset:3072
	ds_read_b128 v[182:185], v194
	ds_read_b128 v[186:189], v194 offset:1024
	ds_read_b128 v[190:193], v194 offset:2048
	ds_read_b128 v[194:197], v194 offset:3072
	s_add_u32 s34, s34, 0x40000
	s_addc_u32 s35, s35, 0
	s_mov_b32 m0, s40
	v_lshl_add_u64 v[236:237], s[34:35], 0, v[136:137]
	ds_read_b128 v[198:201], v172 offset:32768
	ds_read_b128 v[202:205], v172 offset:33792
	ds_read_b128 v[206:209], v172 offset:34816
	ds_read_b128 v[210:213], v172 offset:35840
	ds_read_b128 v[214:217], v172 offset:36864
	ds_read_b128 v[218:221], v172 offset:37888
	ds_read_b128 v[222:225], v172 offset:38912
	ds_read_b128 v[226:229], v172 offset:39936
	global_load_lds_dwordx4 v[236:237], off
	v_lshl_add_u64 v[236:237], s[34:35], 0, v[140:141]
	s_mov_b32 m0, s41
	s_nop 0
	global_load_lds_dwordx4 v[236:237], off
	s_waitcnt vmcnt(8)
	s_waitcnt lgkmcnt(0)
	s_setprio 1
	s_barrier
	v_mfma_f32_16x16x32_bf16 v[124:127], v[128:131], v[198:201], v[124:127]
	v_mfma_f32_16x16x32_bf16 v[120:123], v[174:177], v[198:201], v[120:123]
	v_mfma_f32_16x16x32_bf16 v[116:119], v[128:131], v[206:209], v[116:119]
	v_mfma_f32_16x16x32_bf16 v[112:115], v[174:177], v[206:209], v[112:115]
	v_mfma_f32_16x16x32_bf16 v[108:111], v[128:131], v[214:217], v[108:111]
	v_mfma_f32_16x16x32_bf16 v[104:107], v[174:177], v[214:217], v[104:107]
	v_mfma_f32_16x16x32_bf16 v[100:103], v[128:131], v[222:225], v[100:103]
	v_mfma_f32_16x16x32_bf16 v[96:99], v[174:177], v[222:225], v[96:99]
	v_mfma_f32_16x16x32_bf16 v[124:127], v[132:135], v[202:205], v[124:127]
	v_mfma_f32_16x16x32_bf16 v[120:123], v[178:181], v[202:205], v[120:123]
	v_mfma_f32_16x16x32_bf16 v[116:119], v[132:135], v[210:213], v[116:119]
	v_mfma_f32_16x16x32_bf16 v[112:115], v[178:181], v[210:213], v[112:115]
	v_mfma_f32_16x16x32_bf16 v[108:111], v[132:135], v[218:221], v[108:111]
	v_mfma_f32_16x16x32_bf16 v[104:107], v[178:181], v[218:221], v[104:107]
	v_mfma_f32_16x16x32_bf16 v[100:103], v[132:135], v[226:229], v[100:103]
	v_mfma_f32_16x16x32_bf16 v[96:99], v[178:181], v[226:229], v[96:99]
	v_mfma_f32_16x16x32_bf16 v[60:63], v[182:185], v[198:201], v[60:63]
	v_mfma_f32_16x16x32_bf16 v[56:59], v[190:193], v[198:201], v[56:59]
	v_mfma_f32_16x16x32_bf16 v[52:55], v[182:185], v[206:209], v[52:55]
	v_mfma_f32_16x16x32_bf16 v[48:51], v[190:193], v[206:209], v[48:51]
	v_mfma_f32_16x16x32_bf16 v[44:47], v[182:185], v[214:217], v[44:47]
	v_mfma_f32_16x16x32_bf16 v[40:43], v[190:193], v[214:217], v[40:43]
	v_mfma_f32_16x16x32_bf16 v[36:39], v[182:185], v[222:225], v[36:39]
	v_mfma_f32_16x16x32_bf16 v[32:35], v[190:193], v[222:225], v[32:35]
	v_mfma_f32_16x16x32_bf16 v[60:63], v[186:189], v[202:205], v[60:63]
	v_mfma_f32_16x16x32_bf16 v[56:59], v[194:197], v[202:205], v[56:59]
	v_mfma_f32_16x16x32_bf16 v[52:55], v[186:189], v[210:213], v[52:55]
	v_mfma_f32_16x16x32_bf16 v[48:51], v[194:197], v[210:213], v[48:51]
	v_mfma_f32_16x16x32_bf16 v[44:47], v[186:189], v[218:221], v[44:47]
	v_mfma_f32_16x16x32_bf16 v[40:43], v[194:197], v[218:221], v[40:43]
	v_mfma_f32_16x16x32_bf16 v[36:39], v[186:189], v[226:229], v[36:39]
	v_mfma_f32_16x16x32_bf16 v[32:35], v[194:197], v[226:229], v[32:35]
	s_barrier
	s_setprio 0
	s_add_i32 s34, s60, s33
	v_lshl_add_u64 v[160:161], v[160:161], 0, s[16:17]
	s_mov_b32 m0, s34
	ds_read_b128 v[198:201], v172 offset:49152
	ds_read_b128 v[202:205], v172 offset:50176
	ds_read_b128 v[206:209], v172 offset:51200
	ds_read_b128 v[210:213], v172 offset:52224
	ds_read_b128 v[214:217], v172 offset:53248
	ds_read_b128 v[218:221], v172 offset:54272
	ds_read_b128 v[222:225], v172 offset:55296
	ds_read_b128 v[226:229], v172 offset:56320
	global_load_lds_dwordx4 v[160:161], off
	s_add_i32 m0, s34, 0x2000
	s_add_u32 s30, s30, 0x40080
	v_lshl_add_u64 v[160:161], v[230:231], 0, s[16:17]
	s_addc_u32 s31, s31, 0
	s_add_i32 s34, s61, s33
	global_load_lds_dwordx4 v[160:161], off
	v_lshl_add_u64 v[160:161], s[30:31], 0, v[138:139]
	s_mov_b32 m0, s34
	s_nop 0
	global_load_lds_dwordx4 v[160:161], off
	v_lshl_add_u64 v[160:161], s[30:31], 0, v[142:143]
	s_add_i32 m0, s34, 0x2000
	s_nop 0
	global_load_lds_dwordx4 v[160:161], off
	v_lshl_add_u64 v[160:161], v[232:233], 0, s[16:17]
	s_mov_b32 m0, s42
	s_nop 0
	global_load_lds_dwordx4 v[160:161], off
	v_lshl_add_u64 v[160:161], v[234:235], 0, s[16:17]
	s_mov_b32 m0, s43
	s_nop 0
	global_load_lds_dwordx4 v[160:161], off
	s_waitcnt vmcnt(8)
	s_waitcnt lgkmcnt(0)
	s_setprio 1
	s_barrier
	v_mfma_f32_16x16x32_bf16 v[92:95], v[128:131], v[198:201], v[92:95]
	v_mfma_f32_16x16x32_bf16 v[88:91], v[174:177], v[198:201], v[88:91]
	v_mfma_f32_16x16x32_bf16 v[84:87], v[128:131], v[206:209], v[84:87]
	v_mfma_f32_16x16x32_bf16 v[80:83], v[174:177], v[206:209], v[80:83]
	v_mfma_f32_16x16x32_bf16 v[76:79], v[128:131], v[214:217], v[76:79]
	v_mfma_f32_16x16x32_bf16 v[72:75], v[174:177], v[214:217], v[72:75]
	v_mfma_f32_16x16x32_bf16 v[68:71], v[128:131], v[222:225], v[68:71]
	v_mfma_f32_16x16x32_bf16 v[64:67], v[174:177], v[222:225], v[64:67]
	v_mfma_f32_16x16x32_bf16 v[92:95], v[132:135], v[202:205], v[92:95]
	v_mfma_f32_16x16x32_bf16 v[88:91], v[178:181], v[202:205], v[88:91]
	v_mfma_f32_16x16x32_bf16 v[84:87], v[132:135], v[210:213], v[84:87]
	v_mfma_f32_16x16x32_bf16 v[80:83], v[178:181], v[210:213], v[80:83]
	v_mfma_f32_16x16x32_bf16 v[76:79], v[132:135], v[218:221], v[76:79]
	v_mfma_f32_16x16x32_bf16 v[72:75], v[178:181], v[218:221], v[72:75]
	v_mfma_f32_16x16x32_bf16 v[68:71], v[132:135], v[226:229], v[68:71]
	v_mfma_f32_16x16x32_bf16 v[64:67], v[178:181], v[226:229], v[64:67]
	v_mfma_f32_16x16x32_bf16 v[28:31], v[182:185], v[198:201], v[28:31]
	v_mfma_f32_16x16x32_bf16 v[24:27], v[190:193], v[198:201], v[24:27]
	v_mfma_f32_16x16x32_bf16 v[20:23], v[182:185], v[206:209], v[20:23]
	v_mfma_f32_16x16x32_bf16 v[16:19], v[190:193], v[206:209], v[16:19]
	v_mfma_f32_16x16x32_bf16 v[12:15], v[182:185], v[214:217], v[12:15]
	v_mfma_f32_16x16x32_bf16 v[8:11], v[190:193], v[214:217], v[8:11]
	v_mfma_f32_16x16x32_bf16 v[4:7], v[182:185], v[222:225], v[4:7]
	v_mfma_f32_16x16x32_bf16 v[0:3], v[190:193], v[222:225], v[0:3]
	v_mfma_f32_16x16x32_bf16 v[28:31], v[186:189], v[202:205], v[28:31]
	v_mfma_f32_16x16x32_bf16 v[24:27], v[194:197], v[202:205], v[24:27]
	v_mfma_f32_16x16x32_bf16 v[20:23], v[186:189], v[210:213], v[20:23]
	v_mfma_f32_16x16x32_bf16 v[16:19], v[194:197], v[210:213], v[16:19]
	v_mfma_f32_16x16x32_bf16 v[12:15], v[186:189], v[218:221], v[12:15]
	v_mfma_f32_16x16x32_bf16 v[8:11], v[194:197], v[218:221], v[8:11]
	v_mfma_f32_16x16x32_bf16 v[4:7], v[186:189], v[226:229], v[4:7]
	v_mfma_f32_16x16x32_bf16 v[0:3], v[194:197], v[226:229], v[0:3]
	s_barrier
	s_setprio 0
	s_add_i32 s59, s59, 2
	s_add_u32 s28, s28, 0x100
	s_addc_u32 s29, s29, 0
	s_add_u32 s57, s57, 0x100
	s_addc_u32 s58, s58, 0
	s_cmp_gt_u32 s59, 13

; #define PG8_STAGE(bufoff, gbase, voff) do { _Pragma("unroll") for (int _i = 0; _i < 2; ++_i) \
;         __builtin_amdgcn_global_load_lds((const unsigned*)((const char*)(gbase) + (voff)[_i]), (PG8_LAS unsigned*)(lds + (bufoff) + ldsw + _i * 8192), 16, 0, 0); } while (0)
; #define PG8_WAIT_V(n) asm volatile("s_waitcnt vmcnt(" #n ")" ::: "memory")
; #define PG8_BAR __builtin_amdgcn_s_barrier()
; template <class Epi, class Sched, bool ALIGN_EPI = false, bool SP2 = false>
; __device__ __forceinline__ void gemm_phase(PG8_LAS unsigned char* lds, const Gemm g, const Sched& S, const Epi& E) {
;     const int tid = threadIdx.x, wid = __builtin_amdgcn_readfirstlane(tid >> 6), lane = tid & 63, wr = wid >> 2, wc = wid & 3, fr = lane & 15, fq = lane >> 4;
;     const int K = g.K, nt = K / BK;
;     unsigned voffA[2], voffB[2];
; #pragma unroll
;     for (int i = 0; i < 2; ++i) { int R, C; stage_rc(tid * 16 + i * 8192, R, C); const int Rb = Epi::PERM ? ((R & ~31) + perm32(R & 31)) : R;
;         voffA[i] = (unsigned)(R * K + C) * 2u; voffB[i] = (unsigned)(Rb * K + C) * 2u; }
;     const size_t kstep = (size_t)(BK * 2);
;     const size_t hstep = (size_t)HALF * K * 2;
;     const size_t tstep = 2 * hstep;
;     const unsigned ldsw = (unsigned)wid * 1024u;
;     const int aoff = lds_byte(wr * 64 + fr, fq * 8), boff = lds_byte(wc * 32 + fr, fq * 8);
;     ...
;         PG8_STAGE(PG8_SB(1, 0), cB + kstep, voffB); PG8_STAGE(PG8_SA(1, 0), cA + kstep, voffA); PG8_STAGE(PG8_SB(1, 1), cB + hstep + kstep, voffB);
;         PG8_WAIT_V(6); PG8_BAR;
.LBB0_950:
	s_add_u32 s12, s90, 0x6400000
	s_addc_u32 s13, s91, 0
	s_add_u32 s14, s90, 0x5900000
	s_mov_b64 s[16:17], 0x80
	s_addc_u32 s15, s91, 0
	s_and_b32 s45, s1, 3
	s_add_i32 m0, s41, 0x18000
	v_lshl_add_u64 v[6:7], v[6:7], 0, s[16:17]
	s_lshl_b32 s1, s0, 13
	s_lshl_b32 s19, s45, 12
	s_waitcnt vmcnt(2)
	s_barrier
	global_load_lds_dwordx4 v[6:7], off
	v_lshl_add_u64 v[4:5], v[4:5], 0, s[16:17]
	s_add_i32 m0, s41, 0x1a000
	s_add_i32 s46, s41, 0x8000
	s_add_i32 s47, s41, 0xa000
	global_load_lds_dwordx4 v[4:5], off
	v_lshl_add_u64 v[0:1], v[0:1], 0, s[16:17]
	s_mov_b32 m0, s46
	s_add_u32 s4, s34, 0x40080
	global_load_lds_dwordx4 v[0:1], off
	v_lshl_add_u64 v[0:1], v[2:3], 0, s[16:17]
	s_mov_b32 m0, s47
	s_addc_u32 s5, s35, 0
	global_load_lds_dwordx4 v[0:1], off
	s_add_i32 m0, s41, 0x1c000
	s_nop 0
	global_load_lds_dwordx4 v194, s[4:5]
	v_lshl_add_u64 v[0:1], s[4:5], 0, v[198:199]
	s_add_i32 m0, s41, 0x1e000
	v_lshlrev_b32_e32 v4, 2, v254
	global_load_lds_dwordx4 v[0:1], off
	v_bfe_u32 v0, v254, 4, 2
	v_and_b32_e32 v1, 15, v254
	v_lshlrev_b32_e32 v3, 4, v0
	v_lshl_or_b32 v242, s0, 6, v1
	v_lshl_or_b32 v1, v1, 6, v3
	v_and_b32_e32 v4, 32, v4
	v_lshlrev_b32_e32 v5, 6, v254
	s_movk_i32 s0, 0x3c0
	v_lshlrev_b32_e32 v2, 3, v0
	v_bitop3_b32 v1, v1, s1, v4 bitop3:0xde
	v_and_or_b32 v3, v5, s0, v3
	v_cmp_eq_u32_e64 s[0:1], 0, v0
	v_lshlrev_b32_e32 v0, 8, v254
	v_lshl_or_b32 v244, s45, 5, v2
	v_and_b32_e32 v0, 0x38000, v0
	v_lshlrev_b32_e32 v2, 11, v10
	v_or3_b32 v0, v8, v0, v2
	v_add_u32_e32 v200, v0, v9
	v_lshlrev_b32_e32 v0, 4, v11
	v_and_b32_e32 v0, 0x78000, v0
	s_waitcnt vmcnt(6)
	s_cmpk_lt_u32 s18, 0x100
	v_or3_b32 v0, v8, v0, v2
	v_bitop3_b32 v243, s19, v3, v4 bitop3:0xf6
	s_cselect_b64 s[18:19], -1, 0
	v_add_u32_e32 v202, v0, v9
	s_add_i32 s51, 0, 0x10000
	s_add_i32 s52, 0, 0x14000
	v_mbcnt_lo_u32_b32 v0, -1, 0
	s_ashr_i32 s48, s94, 31
	s_mov_b32 s49, s94
	s_ashr_i32 s50, s2, 31
	v_mov_b32_e32 v201, v195
	v_mov_b32_e32 v203, v195
	v_add_u32_e32 v245, s51, v243
	v_add_u32_e32 v246, s52, v243
	v_add_u32_e32 v247, 0, v1
	v_mbcnt_hi_u32_b32 v248, -1, v0
	s_mov_b32 s53, 0
	s_barrier
	s_branch .LBB0_953

; #define PG8_STAGE(bufoff, gbase, voff) do { _Pragma("unroll") for (int _i = 0; _i < 2; ++_i) \
;         __builtin_amdgcn_global_load_lds((const unsigned*)((const char*)(gbase) + (voff)[_i]), (PG8_LAS unsigned*)(lds + (bufoff) + ldsw + _i * 8192), 16, 0, 0); } while (0)
; #define PG8_LDA(dst, b, h) do { _Pragma("unroll") for (int m = 0; m < 4; ++m) _Pragma("unroll") for (int k = 0; k < 2; ++k) dst[m][k] = *(const PG8_LAS bf16x8*)(lds + PG8_SA(b, h) + aoff + m * 2048 + k * 1024); } while (0)
; #define PG8_LDB(dst, b, h) do { _Pragma("unroll") for (int n = 0; n < 2; ++n) _Pragma("unroll") for (int k = 0; k < 2; ++k) dst[n][k] = *(const PG8_LAS bf16x8*)(lds + PG8_SB(b, h) + boff + n * 2048 + k * 1024); } while (0)
; #define PG8_MMA(ai, bj, At, Bt) do { __builtin_amdgcn_s_setprio(1); _Pragma("unroll") for (int m = 0; m < 4; ++m) _Pragma("unroll") for (int n = 0; n < 2; ++n) _Pragma("unroll") for (int k = 0; k < 2; ++k) \
;         acc[ai][bj][m][n] = __builtin_amdgcn_mfma_f32_16x16x32_bf16(Bt[n][k], At[m][k], acc[ai][bj][m][n], 0, 0, 0); __builtin_amdgcn_s_setprio(0); } while (0)
; #define PG8_WAIT_V(n) asm volatile("s_waitcnt vmcnt(" #n ")" ::: "memory")
; #define PG8_WAIT_L(n) asm volatile("s_waitcnt lgkmcnt(" #n ")" ::: "memory")
; #define PG8_BAR __builtin_amdgcn_s_barrier()
; #define PG8_SCHED __builtin_amdgcn_sched_barrier(0)
; template <class Epi, class Sched, bool ALIGN_EPI = false, bool SP2 = false>
; __device__ __forceinline__ void gemm_phase(PG8_LAS unsigned char* lds, const Gemm g, const Sched& S, const Epi& E) {
;     ...
;             PG8_LDB(B0, 0, 0); PG8_LDB(B1, 0, 1); PG8_SCHED; PG8_LDA(At, 0, 0); PG8_STAGE(PG8_SA(1, 1), a1 + hstep, voffA);
;             PG8_WAIT_V(8); PG8_WAIT_L(0); PG8_BAR; PG8_MMA(0, 0, At, B0); PG8_MMA(0, 1, At, B1); PG8_BAR; PG8_SCHED;
;             PG8_LDA(At, 0, 1); PG8_STAGE(PG8_SB(0, 0), b2, voffB); PG8_STAGE(PG8_SB(0, 1), b2 + hstep, voffB); PG8_STAGE(PG8_SA(0, 0), a2, voffA);
;             PG8_WAIT_V(8); PG8_WAIT_L(0); PG8_BAR; PG8_MMA(1, 0, At, B0); PG8_MMA(1, 1, At, B1); PG8_BAR; PG8_SCHED;
.LBB0_959:
	s_ashr_i32 s23, s22, 31
	s_lshl_b64 s[24:25], s[22:23], 19
	s_add_u32 s24, s3, s24
	s_addc_u32 s25, s33, s25
	s_and_b64 s[26:27], s[4:5], exec
	s_cselect_b32 s23, s25, s31
	s_cselect_b32 s29, s24, s30
	s_ashr_i32 s21, s20, 31
	s_lshl_b64 s[26:27], s[20:21], 19
	s_add_u32 s26, s38, s26
	s_addc_u32 s27, s39, s27
	s_and_b64 s[36:37], s[4:5], exec
	s_cselect_b32 s21, s27, s35
	s_cselect_b32 s54, s26, s34
	s_add_u32 s30, s30, 0x40080
	s_addc_u32 s31, s31, 0
	s_add_u32 s55, s34, 0x100
	s_addc_u32 s56, s35, 0
	s_mov_b32 s57, -2
	s_add_u32 s34, s30, 0xfffc0080
	s_addc_u32 s35, s31, -1
	s_cmp_eq_u32 s57, 12
	s_cselect_b32 s37, s23, s35
	s_cselect_b32 s36, s29, s34
	s_cselect_b32 s35, s21, s56
	s_cselect_b32 s34, s54, s55
	s_add_i32 m0, s41, 0xc000
	s_nop 0
	global_load_lds_dwordx4 v200, s[30:31]
	s_add_i32 m0, s41, 0xe000
	s_nop 0
	global_load_lds_dwordx4 v202, s[30:31]
	s_waitcnt vmcnt(8)
	s_waitcnt lgkmcnt(0)
	s_setprio 1
	s_barrier
	v_mfma_f32_16x16x32_bf16 v[132:135], v[120:123], v[160:163], 0
	v_mfma_f32_16x16x32_bf16 v[124:127], v[136:139], v[160:163], 0
	v_mfma_f32_16x16x32_bf16 v[108:111], v[120:123], v[168:171], 0
	v_mfma_f32_16x16x32_bf16 v[104:107], v[136:139], v[168:171], 0
	v_mfma_f32_16x16x32_bf16 v[92:95], v[120:123], v[176:179], 0
	v_mfma_f32_16x16x32_bf16 v[88:91], v[136:139], v[176:179], 0
	v_mfma_f32_16x16x32_bf16 v[76:79], v[120:123], v[184:187], 0
	v_mfma_f32_16x16x32_bf16 v[72:75], v[136:139], v[184:187], 0
	v_mfma_f32_16x16x32_bf16 v[132:135], v[128:131], v[164:167], v[132:135]
	v_mfma_f32_16x16x32_bf16 v[124:127], v[140:143], v[164:167], v[124:127]
	v_mfma_f32_16x16x32_bf16 v[108:111], v[128:131], v[172:175], v[108:111]
	v_mfma_f32_16x16x32_bf16 v[104:107], v[140:143], v[172:175], v[104:107]
	v_mfma_f32_16x16x32_bf16 v[92:95], v[128:131], v[180:183], v[92:95]
	v_mfma_f32_16x16x32_bf16 v[88:91], v[140:143], v[180:183], v[88:91]
	v_mfma_f32_16x16x32_bf16 v[76:79], v[128:131], v[188:191], v[76:79]
	v_mfma_f32_16x16x32_bf16 v[72:75], v[140:143], v[188:191], v[72:75]
	v_mfma_f32_16x16x32_bf16 v[116:119], v[144:147], v[160:163], 0
	v_mfma_f32_16x16x32_bf16 v[112:115], v[152:155], v[160:163], 0
	v_mfma_f32_16x16x32_bf16 v[100:103], v[144:147], v[168:171], 0
	v_mfma_f32_16x16x32_bf16 v[96:99], v[152:155], v[168:171], 0
	v_mfma_f32_16x16x32_bf16 v[84:87], v[144:147], v[176:179], 0
	v_mfma_f32_16x16x32_bf16 v[80:83], v[152:155], v[176:179], 0
	v_mfma_f32_16x16x32_bf16 v[68:71], v[144:147], v[184:187], 0
	v_mfma_f32_16x16x32_bf16 v[64:67], v[152:155], v[184:187], 0
	v_mfma_f32_16x16x32_bf16 v[116:119], v[148:151], v[164:167], v[116:119]
	v_mfma_f32_16x16x32_bf16 v[112:115], v[156:159], v[164:167], v[112:115]
	v_mfma_f32_16x16x32_bf16 v[100:103], v[148:151], v[172:175], v[100:103]
	v_mfma_f32_16x16x32_bf16 v[96:99], v[156:159], v[172:175], v[96:99]
	v_mfma_f32_16x16x32_bf16 v[84:87], v[148:151], v[180:183], v[84:87]
	v_mfma_f32_16x16x32_bf16 v[80:83], v[156:159], v[180:183], v[80:83]
	v_mfma_f32_16x16x32_bf16 v[68:71], v[148:151], v[188:191], v[68:71]
	v_mfma_f32_16x16x32_bf16 v[64:67], v[156:159], v[188:191], v[64:67]
	s_barrier
	s_setprio 0
	s_add_i32 s58, s51, s40
	v_lshl_add_u64 v[204:205], s[34:35], 0, v[194:195]
	s_mov_b32 m0, s58
	ds_read_b128 v[160:163], v247 offset:16384
	ds_read_b128 v[164:167], v247 offset:17408
	ds_read_b128 v[168:171], v247 offset:18432
	ds_read_b128 v[172:175], v247 offset:19456
	ds_read_b128 v[176:179], v247 offset:20480
	ds_read_b128 v[180:183], v247 offset:21504
	ds_read_b128 v[184:187], v247 offset:22528
	ds_read_b128 v[188:191], v247 offset:23552
	global_load_lds_dwordx4 v[204:205], off
	s_add_i32 m0, s58, 0x2000
	s_add_u32 s58, s34, 0x40000
	v_lshl_add_u64 v[206:207], s[34:35], 0, v[198:199]
	s_addc_u32 s59, s35, 0
	s_add_i32 s60, s52, s40
	global_load_lds_dwordx4 v[206:207], off
	s_mov_b32 m0, s60
	v_lshl_add_u64 v[210:211], s[36:37], 0, v[196:197]
	global_load_lds_dwordx4 v194, s[58:59]
	s_add_i32 m0, s60, 0x2000
	s_nop 0
	global_load_lds_dwordx4 v198, s[58:59]
	v_lshl_add_u64 v[208:209], s[36:37], 0, v[192:193]
	s_mov_b32 m0, s41
	s_nop 0
	global_load_lds_dwordx4 v[208:209], off
	s_mov_b32 m0, s42
	s_nop 0
	global_load_lds_dwordx4 v[210:211], off
	s_waitcnt vmcnt(8)
	s_waitcnt lgkmcnt(0)
	s_setprio 1
	s_barrier
	v_mfma_f32_16x16x32_bf16 v[60:63], v[120:123], v[160:163], 0
	v_mfma_f32_16x16x32_bf16 v[56:59], v[136:139], v[160:163], 0
	v_mfma_f32_16x16x32_bf16 v[44:47], v[120:123], v[168:171], 0
	v_mfma_f32_16x16x32_bf16 v[40:43], v[136:139], v[168:171], 0
	v_mfma_f32_16x16x32_bf16 v[28:31], v[120:123], v[176:179], 0
	v_mfma_f32_16x16x32_bf16 v[24:27], v[136:139], v[176:179], 0
	v_mfma_f32_16x16x32_bf16 v[12:15], v[120:123], v[184:187], 0
	v_mfma_f32_16x16x32_bf16 v[8:11], v[136:139], v[184:187], 0
	v_mfma_f32_16x16x32_bf16 v[60:63], v[128:131], v[164:167], v[60:63]
	v_mfma_f32_16x16x32_bf16 v[56:59], v[140:143], v[164:167], v[56:59]
	v_mfma_f32_16x16x32_bf16 v[44:47], v[128:131], v[172:175], v[44:47]
	v_mfma_f32_16x16x32_bf16 v[40:43], v[140:143], v[172:175], v[40:43]
	v_mfma_f32_16x16x32_bf16 v[28:31], v[128:131], v[180:183], v[28:31]
	v_mfma_f32_16x16x32_bf16 v[24:27], v[140:143], v[180:183], v[24:27]
	v_mfma_f32_16x16x32_bf16 v[12:15], v[128:131], v[188:191], v[12:15]
	v_mfma_f32_16x16x32_bf16 v[8:11], v[140:143], v[188:191], v[8:11]
	v_mfma_f32_16x16x32_bf16 v[52:55], v[144:147], v[160:163], 0
	v_mfma_f32_16x16x32_bf16 v[48:51], v[152:155], v[160:163], 0
	v_mfma_f32_16x16x32_bf16 v[36:39], v[144:147], v[168:171], 0
	v_mfma_f32_16x16x32_bf16 v[32:35], v[152:155], v[168:171], 0
	v_mfma_f32_16x16x32_bf16 v[20:23], v[144:147], v[176:179], 0
	v_mfma_f32_16x16x32_bf16 v[16:19], v[152:155], v[176:179], 0
	v_mfma_f32_16x16x32_bf16 v[4:7], v[144:147], v[184:187], 0
	v_mfma_f32_16x16x32_bf16 v[0:3], v[152:155], v[184:187], 0
	v_mfma_f32_16x16x32_bf16 v[52:55], v[148:151], v[164:167], v[52:55]
	v_mfma_f32_16x16x32_bf16 v[48:51], v[156:159], v[164:167], v[48:51]
	v_mfma_f32_16x16x32_bf16 v[36:39], v[148:151], v[172:175], v[36:39]
	v_mfma_f32_16x16x32_bf16 v[32:35], v[156:159], v[172:175], v[32:35]
	v_mfma_f32_16x16x32_bf16 v[20:23], v[148:151], v[180:183], v[20:23]
	v_mfma_f32_16x16x32_bf16 v[16:19], v[156:159], v[180:183], v[16:19]
	v_mfma_f32_16x16x32_bf16 v[4:7], v[148:151], v[188:191], v[4:7]
	v_mfma_f32_16x16x32_bf16 v[0:3], v[156:159], v[188:191], v[0:3]
	s_barrier
; #define PG8_STAGE(bufoff, gbase, voff) do { _Pragma("unroll") for (int _i = 0; _i < 2; ++_i) \
;         __builtin_amdgcn_global_load_lds((const unsigned*)((const char*)(gbase) + (voff)[_i]), (PG8_LAS unsigned*)(lds + (bufoff) + ldsw + _i * 8192), 16, 0, 0); } while (0)
; #define PG8_LDA(dst, b, h) do { _Pragma("unroll") for (int m = 0; m < 4; ++m) _Pragma("unroll") for (int k = 0; k < 2; ++k) dst[m][k] = *(const PG8_LAS bf16x8*)(lds + PG8_SA(b, h) + aoff + m * 2048 + k * 1024); } while (0)
; #define PG8_LDB(dst, b, h) do { _Pragma("unroll") for (int n = 0; n < 2; ++n) _Pragma("unroll") for (int k = 0; k < 2; ++k) dst[n][k] = *(const PG8_LAS bf16x8*)(lds + PG8_SB(b, h) + boff + n * 2048 + k * 1024); } while (0)
; #define PG8_MMA(ai, bj, At, Bt) do { __builtin_amdgcn_s_setprio(1); _Pragma("unroll") for (int m = 0; m < 4; ++m) _Pragma("unroll") for (int n = 0; n < 2; ++n) _Pragma("unroll") for (int k = 0; k < 2; ++k) \
;         acc[ai][bj][m][n] = __builtin_amdgcn_mfma_f32_16x16x32_bf16(Bt[n][k], At[m][k], acc[ai][bj][m][n], 0, 0, 0); __builtin_amdgcn_s_setprio(0); } while (0)
; #define PG8_WAIT_V(n) asm volatile("s_waitcnt vmcnt(" #n ")" ::: "memory")
; #define PG8_WAIT_L(n) asm volatile("s_waitcnt lgkmcnt(" #n ")" ::: "memory")
; #define PG8_BAR __builtin_amdgcn_s_barrier()
; #define PG8_SCHED __builtin_amdgcn_sched_barrier(0)
; template <class Epi, class Sched, bool ALIGN_EPI = false, bool SP2 = false>
; __device__ __forceinline__ void gemm_phase(PG8_LAS unsigned char* lds, const Gemm g, const Sched& S, const Epi& E) {
;     ...
;             PG8_LDB(B0, 1, 0); PG8_LDB(B1, 1, 1); PG8_SCHED; PG8_LDA(At, 1, 0); PG8_STAGE(PG8_SA(0, 1), a2 + hstep, voffA);
;             PG8_WAIT_V(8); PG8_WAIT_L(0); PG8_BAR; PG8_MMA(0, 0, At, B0); PG8_MMA(0, 1, At, B1); PG8_BAR; PG8_SCHED;
;             PG8_LDA(At, 1, 1); PG8_STAGE(PG8_SB(1, 0), b3, voffB); PG8_STAGE(PG8_SB(1, 1), b3 + hstep, voffB); PG8_STAGE(PG8_SA(1, 0), a3, voffA);
;             PG8_WAIT_V(8); PG8_WAIT_L(0); PG8_BAR; PG8_MMA(1, 0, At, B0); PG8_MMA(1, 1, At, B1); PG8_BAR; PG8_SCHED;
	s_setprio 0
	s_add_i32 s58, 0, 0x18000
	s_add_i32 s59, 0, 0x1c000
	v_add_u32_e32 v140, s58, v243
	v_add_u32_e32 v156, s59, v243
	ds_read_b128 v[120:123], v140
	ds_read_b128 v[128:131], v140 offset:1024
	ds_read_b128 v[136:139], v140 offset:2048
	ds_read_b128 v[140:143], v140 offset:3072
	ds_read_b128 v[144:147], v156
	ds_read_b128 v[148:151], v156 offset:1024
	ds_read_b128 v[152:155], v156 offset:2048
	ds_read_b128 v[156:159], v156 offset:3072
	s_add_u32 s36, s36, 0x40000
	s_addc_u32 s37, s37, 0
	s_mov_b32 m0, s43
	ds_read_b128 v[160:163], v247 offset:32768
	ds_read_b128 v[164:167], v247 offset:33792
	ds_read_b128 v[168:171], v247 offset:34816
	ds_read_b128 v[172:175], v247 offset:35840
	ds_read_b128 v[176:179], v247 offset:36864
	ds_read_b128 v[180:183], v247 offset:37888
	ds_read_b128 v[184:187], v247 offset:38912
	ds_read_b128 v[188:191], v247 offset:39936
	global_load_lds_dwordx4 v192, s[36:37]
	s_mov_b32 m0, s44
	s_nop 0
	global_load_lds_dwordx4 v196, s[36:37]
	s_waitcnt vmcnt(8)
	s_waitcnt lgkmcnt(0)
	s_setprio 1
	s_barrier
	v_mfma_f32_16x16x32_bf16 v[132:135], v[120:123], v[160:163], v[132:135]
	v_mfma_f32_16x16x32_bf16 v[124:127], v[136:139], v[160:163], v[124:127]
	v_mfma_f32_16x16x32_bf16 v[108:111], v[120:123], v[168:171], v[108:111]
	v_mfma_f32_16x16x32_bf16 v[104:107], v[136:139], v[168:171], v[104:107]
	v_mfma_f32_16x16x32_bf16 v[92:95], v[120:123], v[176:179], v[92:95]
	v_mfma_f32_16x16x32_bf16 v[88:91], v[136:139], v[176:179], v[88:91]
	v_mfma_f32_16x16x32_bf16 v[76:79], v[120:123], v[184:187], v[76:79]
	v_mfma_f32_16x16x32_bf16 v[72:75], v[136:139], v[184:187], v[72:75]
	v_mfma_f32_16x16x32_bf16 v[132:135], v[128:131], v[164:167], v[132:135]
	v_mfma_f32_16x16x32_bf16 v[124:127], v[140:143], v[164:167], v[124:127]
	v_mfma_f32_16x16x32_bf16 v[108:111], v[128:131], v[172:175], v[108:111]
	v_mfma_f32_16x16x32_bf16 v[104:107], v[140:143], v[172:175], v[104:107]
	v_mfma_f32_16x16x32_bf16 v[92:95], v[128:131], v[180:183], v[92:95]
	v_mfma_f32_16x16x32_bf16 v[88:91], v[140:143], v[180:183], v[88:91]
	v_mfma_f32_16x16x32_bf16 v[76:79], v[128:131], v[188:191], v[76:79]
	v_mfma_f32_16x16x32_bf16 v[72:75], v[140:143], v[188:191], v[72:75]
	v_mfma_f32_16x16x32_bf16 v[116:119], v[144:147], v[160:163], v[116:119]
	v_mfma_f32_16x16x32_bf16 v[112:115], v[152:155], v[160:163], v[112:115]
	v_mfma_f32_16x16x32_bf16 v[100:103], v[144:147], v[168:171], v[100:103]
	v_mfma_f32_16x16x32_bf16 v[96:99], v[152:155], v[168:171], v[96:99]
	v_mfma_f32_16x16x32_bf16 v[84:87], v[144:147], v[176:179], v[84:87]
	v_mfma_f32_16x16x32_bf16 v[80:83], v[152:155], v[176:179], v[80:83]
	v_mfma_f32_16x16x32_bf16 v[68:71], v[144:147], v[184:187], v[68:71]
	v_mfma_f32_16x16x32_bf16 v[64:67], v[152:155], v[184:187], v[64:67]
	v_mfma_f32_16x16x32_bf16 v[116:119], v[148:151], v[164:167], v[116:119]
	v_mfma_f32_16x16x32_bf16 v[112:115], v[156:159], v[164:167], v[112:115]
	v_mfma_f32_16x16x32_bf16 v[100:103], v[148:151], v[172:175], v[100:103]
	v_mfma_f32_16x16x32_bf16 v[96:99], v[156:159], v[172:175], v[96:99]
	v_mfma_f32_16x16x32_bf16 v[84:87], v[148:151], v[180:183], v[84:87]
	v_mfma_f32_16x16x32_bf16 v[80:83], v[156:159], v[180:183], v[80:83]
	v_mfma_f32_16x16x32_bf16 v[68:71], v[148:151], v[188:191], v[68:71]
	v_mfma_f32_16x16x32_bf16 v[64:67], v[156:159], v[188:191], v[64:67]
	s_barrier
	s_setprio 0
	s_add_i32 s36, s58, s40
	v_lshl_add_u64 v[204:205], v[204:205], 0, s[16:17]
	s_mov_b32 m0, s36
	ds_read_b128 v[160:163], v247 offset:49152
	ds_read_b128 v[164:167], v247 offset:50176
	ds_read_b128 v[168:171], v247 offset:51200
	ds_read_b128 v[172:175], v247 offset:52224
	ds_read_b128 v[176:179], v247 offset:53248
	ds_read_b128 v[180:183], v247 offset:54272
	ds_read_b128 v[184:187], v247 offset:55296
	ds_read_b128 v[188:191], v247 offset:56320
	global_load_lds_dwordx4 v[204:205], off
	s_add_i32 m0, s36, 0x2000
	s_add_u32 s34, s34, 0x40080
	v_lshl_add_u64 v[204:205], v[206:207], 0, s[16:17]
	s_addc_u32 s35, s35, 0
	s_add_i32 s36, s59, s40
	global_load_lds_dwordx4 v[204:205], off
	s_mov_b32 m0, s36
	s_nop 0
	global_load_lds_dwordx4 v194, s[34:35]
	s_add_i32 m0, s36, 0x2000
	s_nop 0
	global_load_lds_dwordx4 v198, s[34:35]
	v_lshl_add_u64 v[204:205], v[208:209], 0, s[16:17]
	s_mov_b32 m0, s46
	s_nop 0
	global_load_lds_dwordx4 v[204:205], off
	v_lshl_add_u64 v[204:205], v[210:211], 0, s[16:17]
	s_mov_b32 m0, s47
	s_nop 0
	global_load_lds_dwordx4 v[204:205], off
	s_waitcnt vmcnt(8)
	s_waitcnt lgkmcnt(0)
	s_setprio 1
	s_barrier
	v_mfma_f32_16x16x32_bf16 v[60:63], v[120:123], v[160:163], v[60:63]
	v_mfma_f32_16x16x32_bf16 v[56:59], v[136:139], v[160:163], v[56:59]
	v_mfma_f32_16x16x32_bf16 v[44:47], v[120:123], v[168:171], v[44:47]
	v_mfma_f32_16x16x32_bf16 v[40:43], v[136:139], v[168:171], v[40:43]
	v_mfma_f32_16x16x32_bf16 v[28:31], v[120:123], v[176:179], v[28:31]
	v_mfma_f32_16x16x32_bf16 v[24:27], v[136:139], v[176:179], v[24:27]
	v_mfma_f32_16x16x32_bf16 v[12:15], v[120:123], v[184:187], v[12:15]
	v_mfma_f32_16x16x32_bf16 v[8:11], v[136:139], v[184:187], v[8:11]
	v_mfma_f32_16x16x32_bf16 v[60:63], v[128:131], v[164:167], v[60:63]
	v_mfma_f32_16x16x32_bf16 v[56:59], v[140:143], v[164:167], v[56:59]
	v_mfma_f32_16x16x32_bf16 v[44:47], v[128:131], v[172:175], v[44:47]
	v_mfma_f32_16x16x32_bf16 v[40:43], v[140:143], v[172:175], v[40:43]
	v_mfma_f32_16x16x32_bf16 v[28:31], v[128:131], v[180:183], v[28:31]
	v_mfma_f32_16x16x32_bf16 v[24:27], v[140:143], v[180:183], v[24:27]
	v_mfma_f32_16x16x32_bf16 v[12:15], v[128:131], v[188:191], v[12:15]
	v_mfma_f32_16x16x32_bf16 v[8:11], v[140:143], v[188:191], v[8:11]
	v_mfma_f32_16x16x32_bf16 v[52:55], v[144:147], v[160:163], v[52:55]
	v_mfma_f32_16x16x32_bf16 v[48:51], v[152:155], v[160:163], v[48:51]
	v_mfma_f32_16x16x32_bf16 v[36:39], v[144:147], v[168:171], v[36:39]
	v_mfma_f32_16x16x32_bf16 v[32:35], v[152:155], v[168:171], v[32:35]
	v_mfma_f32_16x16x32_bf16 v[20:23], v[144:147], v[176:179], v[20:23]
	v_mfma_f32_16x16x32_bf16 v[16:19], v[152:155], v[176:179], v[16:19]
	v_mfma_f32_16x16x32_bf16 v[4:7], v[144:147], v[184:187], v[4:7]
	v_mfma_f32_16x16x32_bf16 v[0:3], v[152:155], v[184:187], v[0:3]
	v_mfma_f32_16x16x32_bf16 v[52:55], v[148:151], v[164:167], v[52:55]
	v_mfma_f32_16x16x32_bf16 v[48:51], v[156:159], v[164:167], v[48:51]
	v_mfma_f32_16x16x32_bf16 v[36:39], v[148:151], v[172:175], v[36:39]
	v_mfma_f32_16x16x32_bf16 v[32:35], v[156:159], v[172:175], v[32:35]
	v_mfma_f32_16x16x32_bf16 v[20:23], v[148:151], v[180:183], v[20:23]
	v_mfma_f32_16x16x32_bf16 v[16:19], v[156:159], v[180:183], v[16:19]
	v_mfma_f32_16x16x32_bf16 v[4:7], v[148:151], v[188:191], v[4:7]
	v_mfma_f32_16x16x32_bf16 v[0:3], v[156:159], v[188:191], v[0:3]
	s_barrier
	s_setprio 0
	s_add_i32 s57, s57, 2
	s_add_u32 s30, s30, 0x100
	s_addc_u32 s31, s31, 0
	s_add_u32 s55, s55, 0x100
	s_addc_u32 s56, s56, 0
	s_cmp_gt_u32 s57, 13
; #define PG8_STAGE(bufoff, gbase, voff) do { _Pragma("unroll") for (int _i = 0; _i < 2; ++_i) \
;         __builtin_amdgcn_global_load_lds((const unsigned*)((const char*)(gbase) + (voff)[_i]), (PG8_LAS unsigned*)(lds + (bufoff) + ldsw + _i * 8192), 16, 0, 0); } while (0)
; #define PG8_LDA(dst, b, h) do { _Pragma("unroll") for (int m = 0; m < 4; ++m) _Pragma("unroll") for (int k = 0; k < 2; ++k) dst[m][k] = *(const PG8_LAS bf16x8*)(lds + PG8_SA(b, h) + aoff + m * 2048 + k * 1024); } while (0)
; #define PG8_LDB(dst, b, h) do { _Pragma("unroll") for (int n = 0; n < 2; ++n) _Pragma("unroll") for (int k = 0; k < 2; ++k) dst[n][k] = *(const PG8_LAS bf16x8*)(lds + PG8_SB(b, h) + boff + n * 2048 + k * 1024); } while (0)
; #define PG8_MMA(ai, bj, At, Bt) do { __builtin_amdgcn_s_setprio(1); _Pragma("unroll") for (int m = 0; m < 4; ++m) _Pragma("unroll") for (int n = 0; n < 2; ++n) _Pragma("unroll") for (int k = 0; k < 2; ++k) \
;         acc[ai][bj][m][n] = __builtin_amdgcn_mfma_f32_16x16x32_bf16(Bt[n][k], At[m][k], acc[ai][bj][m][n], 0, 0, 0); __builtin_amdgcn_s_setprio(0); } while (0)
; #define PG8_WAIT_V(n) asm volatile("s_waitcnt vmcnt(" #n ")" ::: "memory")
; #define PG8_WAIT_L(n) asm volatile("s_waitcnt lgkmcnt(" #n ")" ::: "memory")
; #define PG8_BAR __builtin_amdgcn_s_barrier()
; #define PG8_SCHED __builtin_amdgcn_sched_barrier(0)
; template <class Epi, class Sched, bool ALIGN_EPI = false, bool SP2 = false>
; __device__ __forceinline__ void gemm_phase(PG8_LAS unsigned char* lds, const Gemm g, const Sched& S, const Epi& E) {
;     ...
;             PG8_LDB(B0, 0, 0); PG8_LDB(B1, 0, 1); PG8_SCHED; PG8_LDA(At, 0, 0); PG8_STAGE(PG8_SA(1, 1), a1 + hstep, voffA);
;             PG8_WAIT_V(8); PG8_WAIT_L(0); PG8_BAR; PG8_MMA(0, 0, At, B0); PG8_MMA(0, 1, At, B1); PG8_BAR; PG8_SCHED;
;             PG8_LDA(At, 0, 1); PG8_STAGE(PG8_SB(0, 0), b2, voffB); PG8_STAGE(PG8_SB(0, 1), b2 + hstep, voffB); PG8_STAGE(PG8_SA(0, 0), a2, voffA);
;             PG8_WAIT_V(8); PG8_WAIT_L(0); PG8_BAR; PG8_MMA(1, 0, At, B0); PG8_MMA(1, 1, At, B1); PG8_BAR; PG8_SCHED;
.LBB0_960:
	ds_read_b128 v[120:123], v245
	ds_read_b128 v[128:131], v245 offset:1024
	ds_read_b128 v[136:139], v245 offset:2048
	ds_read_b128 v[140:143], v245 offset:3072
	ds_read_b128 v[144:147], v246
	ds_read_b128 v[148:151], v246 offset:1024
	ds_read_b128 v[152:155], v246 offset:2048
	ds_read_b128 v[156:159], v246 offset:3072
	s_add_u32 s34, s30, 0xfffc0080
	s_addc_u32 s35, s31, -1
	s_cmp_eq_u32 s57, 12
	s_cselect_b32 s37, s23, s35
	s_cselect_b32 s36, s29, s34
	s_cselect_b32 s35, s21, s56
	s_cselect_b32 s34, s54, s55
	s_add_i32 m0, s41, 0xc000
	ds_read_b128 v[160:163], v247
	ds_read_b128 v[164:167], v247 offset:1024
	ds_read_b128 v[168:171], v247 offset:2048
	ds_read_b128 v[172:175], v247 offset:3072
	ds_read_b128 v[176:179], v247 offset:4096
	ds_read_b128 v[180:183], v247 offset:5120
	ds_read_b128 v[184:187], v247 offset:6144
	ds_read_b128 v[188:191], v247 offset:7168
	global_load_lds_dwordx4 v200, s[30:31]
	s_add_i32 m0, s41, 0xe000
	s_nop 0
	global_load_lds_dwordx4 v202, s[30:31]
	s_waitcnt vmcnt(8)
	s_waitcnt lgkmcnt(0)
	s_setprio 1
	s_barrier
	v_mfma_f32_16x16x32_bf16 v[132:135], v[120:123], v[160:163], v[132:135]
	v_mfma_f32_16x16x32_bf16 v[124:127], v[136:139], v[160:163], v[124:127]
	v_mfma_f32_16x16x32_bf16 v[108:111], v[120:123], v[168:171], v[108:111]
	v_mfma_f32_16x16x32_bf16 v[104:107], v[136:139], v[168:171], v[104:107]
	v_mfma_f32_16x16x32_bf16 v[92:95], v[120:123], v[176:179], v[92:95]
	v_mfma_f32_16x16x32_bf16 v[88:91], v[136:139], v[176:179], v[88:91]
	v_mfma_f32_16x16x32_bf16 v[76:79], v[120:123], v[184:187], v[76:79]
	v_mfma_f32_16x16x32_bf16 v[72:75], v[136:139], v[184:187], v[72:75]
	v_mfma_f32_16x16x32_bf16 v[132:135], v[128:131], v[164:167], v[132:135]
	v_mfma_f32_16x16x32_bf16 v[124:127], v[140:143], v[164:167], v[124:127]
	v_mfma_f32_16x16x32_bf16 v[108:111], v[128:131], v[172:175], v[108:111]
	v_mfma_f32_16x16x32_bf16 v[104:107], v[140:143], v[172:175], v[104:107]
	v_mfma_f32_16x16x32_bf16 v[92:95], v[128:131], v[180:183], v[92:95]
	v_mfma_f32_16x16x32_bf16 v[88:91], v[140:143], v[180:183], v[88:91]
	v_mfma_f32_16x16x32_bf16 v[76:79], v[128:131], v[188:191], v[76:79]
	v_mfma_f32_16x16x32_bf16 v[72:75], v[140:143], v[188:191], v[72:75]
	v_mfma_f32_16x16x32_bf16 v[116:119], v[144:147], v[160:163], v[116:119]
	v_mfma_f32_16x16x32_bf16 v[112:115], v[152:155], v[160:163], v[112:115]
	v_mfma_f32_16x16x32_bf16 v[100:103], v[144:147], v[168:171], v[100:103]
	v_mfma_f32_16x16x32_bf16 v[96:99], v[152:155], v[168:171], v[96:99]
	v_mfma_f32_16x16x32_bf16 v[84:87], v[144:147], v[176:179], v[84:87]
	v_mfma_f32_16x16x32_bf16 v[80:83], v[152:155], v[176:179], v[80:83]
	v_mfma_f32_16x16x32_bf16 v[68:71], v[144:147], v[184:187], v[68:71]
	v_mfma_f32_16x16x32_bf16 v[64:67], v[152:155], v[184:187], v[64:67]
	v_mfma_f32_16x16x32_bf16 v[116:119], v[148:151], v[164:167], v[116:119]
	v_mfma_f32_16x16x32_bf16 v[112:115], v[156:159], v[164:167], v[112:115]
	v_mfma_f32_16x16x32_bf16 v[100:103], v[148:151], v[172:175], v[100:103]
	v_mfma_f32_16x16x32_bf16 v[96:99], v[156:159], v[172:175], v[96:99]
	v_mfma_f32_16x16x32_bf16 v[84:87], v[148:151], v[180:183], v[84:87]
	v_mfma_f32_16x16x32_bf16 v[80:83], v[156:159], v[180:183], v[80:83]
	v_mfma_f32_16x16x32_bf16 v[68:71], v[148:151], v[188:191], v[68:71]
	v_mfma_f32_16x16x32_bf16 v[64:67], v[156:159], v[188:191], v[64:67]
	s_barrier
	s_setprio 0
	s_add_i32 s58, s51, s40
	v_lshl_add_u64 v[204:205], s[34:35], 0, v[194:195]
	s_mov_b32 m0, s58
	ds_read_b128 v[160:163], v247 offset:16384
	ds_read_b128 v[164:167], v247 offset:17408
	ds_read_b128 v[168:171], v247 offset:18432
	ds_read_b128 v[172:175], v247 offset:19456
	ds_read_b128 v[176:179], v247 offset:20480
	ds_read_b128 v[180:183], v247 offset:21504
	ds_read_b128 v[184:187], v247 offset:22528
	ds_read_b128 v[188:191], v247 offset:23552
	global_load_lds_dwordx4 v[204:205], off
	s_add_i32 m0, s58, 0x2000
	s_add_u32 s58, s34, 0x40000
	v_lshl_add_u64 v[206:207], s[34:35], 0, v[198:199]
	s_addc_u32 s59, s35, 0
	s_add_i32 s60, s52, s40
	global_load_lds_dwordx4 v[206:207], off
	s_mov_b32 m0, s60
	v_lshl_add_u64 v[210:211], s[36:37], 0, v[196:197]
	global_load_lds_dwordx4 v194, s[58:59]
	s_add_i32 m0, s60, 0x2000
	s_nop 0
	global_load_lds_dwordx4 v198, s[58:59]
	v_lshl_add_u64 v[208:209], s[36:37], 0, v[192:193]
	s_mov_b32 m0, s41
	s_nop 0
	global_load_lds_dwordx4 v[208:209], off
	s_mov_b32 m0, s42
	s_nop 0
	global_load_lds_dwordx4 v[210:211], off
	s_waitcnt vmcnt(8)
	s_waitcnt lgkmcnt(0)
	s_setprio 1
	s_barrier
	v_mfma_f32_16x16x32_bf16 v[60:63], v[120:123], v[160:163], v[60:63]
	v_mfma_f32_16x16x32_bf16 v[56:59], v[136:139], v[160:163], v[56:59]
	v_mfma_f32_16x16x32_bf16 v[44:47], v[120:123], v[168:171], v[44:47]
	v_mfma_f32_16x16x32_bf16 v[40:43], v[136:139], v[168:171], v[40:43]
	v_mfma_f32_16x16x32_bf16 v[28:31], v[120:123], v[176:179], v[28:31]
	v_mfma_f32_16x16x32_bf16 v[24:27], v[136:139], v[176:179], v[24:27]
	v_mfma_f32_16x16x32_bf16 v[12:15], v[120:123], v[184:187], v[12:15]
	v_mfma_f32_16x16x32_bf16 v[8:11], v[136:139], v[184:187], v[8:11]
	v_mfma_f32_16x16x32_bf16 v[60:63], v[128:131], v[164:167], v[60:63]
	v_mfma_f32_16x16x32_bf16 v[56:59], v[140:143], v[164:167], v[56:59]
	v_mfma_f32_16x16x32_bf16 v[44:47], v[128:131], v[172:175], v[44:47]
	v_mfma_f32_16x16x32_bf16 v[40:43], v[140:143], v[172:175], v[40:43]
	v_mfma_f32_16x16x32_bf16 v[28:31], v[128:131], v[180:183], v[28:31]
	v_mfma_f32_16x16x32_bf16 v[24:27], v[140:143], v[180:183], v[24:27]
	v_mfma_f32_16x16x32_bf16 v[12:15], v[128:131], v[188:191], v[12:15]
	v_mfma_f32_16x16x32_bf16 v[8:11], v[140:143], v[188:191], v[8:11]
	v_mfma_f32_16x16x32_bf16 v[52:55], v[144:147], v[160:163], v[52:55]
	v_mfma_f32_16x16x32_bf16 v[48:51], v[152:155], v[160:163], v[48:51]
	v_mfma_f32_16x16x32_bf16 v[36:39], v[144:147], v[168:171], v[36:39]
	v_mfma_f32_16x16x32_bf16 v[32:35], v[152:155], v[168:171], v[32:35]
	v_mfma_f32_16x16x32_bf16 v[20:23], v[144:147], v[176:179], v[20:23]
	v_mfma_f32_16x16x32_bf16 v[16:19], v[152:155], v[176:179], v[16:19]
	v_mfma_f32_16x16x32_bf16 v[4:7], v[144:147], v[184:187], v[4:7]
	v_mfma_f32_16x16x32_bf16 v[0:3], v[152:155], v[184:187], v[0:3]
	v_mfma_f32_16x16x32_bf16 v[52:55], v[148:151], v[164:167], v[52:55]
	v_mfma_f32_16x16x32_bf16 v[48:51], v[156:159], v[164:167], v[48:51]
	v_mfma_f32_16x16x32_bf16 v[36:39], v[148:151], v[172:175], v[36:39]
	v_mfma_f32_16x16x32_bf16 v[32:35], v[156:159], v[172:175], v[32:35]
	v_mfma_f32_16x16x32_bf16 v[20:23], v[148:151], v[180:183], v[20:23]
	v_mfma_f32_16x16x32_bf16 v[16:19], v[156:159], v[180:183], v[16:19]
	v_mfma_f32_16x16x32_bf16 v[4:7], v[148:151], v[188:191], v[4:7]
	v_mfma_f32_16x16x32_bf16 v[0:3], v[156:159], v[188:191], v[0:3]
	s_barrier
; #define PG8_STAGE(bufoff, gbase, voff) do { _Pragma("unroll") for (int _i = 0; _i < 2; ++_i) \
;         __builtin_amdgcn_global_load_lds((const unsigned*)((const char*)(gbase) + (voff)[_i]), (PG8_LAS unsigned*)(lds + (bufoff) + ldsw + _i * 8192), 16, 0, 0); } while (0)
; #define PG8_LDA(dst, b, h) do { _Pragma("unroll") for (int m = 0; m < 4; ++m) _Pragma("unroll") for (int k = 0; k < 2; ++k) dst[m][k] = *(const PG8_LAS bf16x8*)(lds + PG8_SA(b, h) + aoff + m * 2048 + k * 1024); } while (0)
; #define PG8_LDB(dst, b, h) do { _Pragma("unroll") for (int n = 0; n < 2; ++n) _Pragma("unroll") for (int k = 0; k < 2; ++k) dst[n][k] = *(const PG8_LAS bf16x8*)(lds + PG8_SB(b, h) + boff + n * 2048 + k * 1024); } while (0)
; #define PG8_MMA(ai, bj, At, Bt) do { __builtin_amdgcn_s_setprio(1); _Pragma("unroll") for (int m = 0; m < 4; ++m) _Pragma("unroll") for (int n = 0; n < 2; ++n) _Pragma("unroll") for (int k = 0; k < 2; ++k) \
;         acc[ai][bj][m][n] = __builtin_amdgcn_mfma_f32_16x16x32_bf16(Bt[n][k], At[m][k], acc[ai][bj][m][n], 0, 0, 0); __builtin_amdgcn_s_setprio(0); } while (0)
; #define PG8_WAIT_V(n) asm volatile("s_waitcnt vmcnt(" #n ")" ::: "memory")
; #define PG8_WAIT_L(n) asm volatile("s_waitcnt lgkmcnt(" #n ")" ::: "memory")
; #define PG8_BAR __builtin_amdgcn_s_barrier()
; #define PG8_SCHED __builtin_amdgcn_sched_barrier(0)
; template <class Epi, class Sched, bool ALIGN_EPI = false, bool SP2 = false>
; __device__ __forceinline__ void gemm_phase(PG8_LAS unsigned char* lds, const Gemm g, const Sched& S, const Epi& E) {
;     ...
;             PG8_LDB(B0, 1, 0); PG8_LDB(B1, 1, 1); PG8_SCHED; PG8_LDA(At, 1, 0); PG8_STAGE(PG8_SA(0, 1), a2 + hstep, voffA);
;             PG8_WAIT_V(8); PG8_WAIT_L(0); PG8_BAR; PG8_MMA(0, 0, At, B0); PG8_MMA(0, 1, At, B1); PG8_BAR; PG8_SCHED;
;             PG8_LDA(At, 1, 1); PG8_STAGE(PG8_SB(1, 0), b3, voffB); PG8_STAGE(PG8_SB(1, 1), b3 + hstep, voffB); PG8_STAGE(PG8_SA(1, 0), a3, voffA);
;             PG8_WAIT_V(8); PG8_WAIT_L(0); PG8_BAR; PG8_MMA(1, 0, At, B0); PG8_MMA(1, 1, At, B1); PG8_BAR; PG8_SCHED;
	s_setprio 0
	s_add_i32 s58, 0, 0x18000
	s_add_i32 s59, 0, 0x1c000
	v_add_u32_e32 v140, s58, v243
	v_add_u32_e32 v156, s59, v243
	ds_read_b128 v[120:123], v140
	ds_read_b128 v[128:131], v140 offset:1024
	ds_read_b128 v[136:139], v140 offset:2048
	ds_read_b128 v[140:143], v140 offset:3072
	ds_read_b128 v[144:147], v156
	ds_read_b128 v[148:151], v156 offset:1024
	ds_read_b128 v[152:155], v156 offset:2048
	ds_read_b128 v[156:159], v156 offset:3072
	s_add_u32 s36, s36, 0x40000
	s_addc_u32 s37, s37, 0
	s_mov_b32 m0, s43
	ds_read_b128 v[160:163], v247 offset:32768
	ds_read_b128 v[164:167], v247 offset:33792
	ds_read_b128 v[168:171], v247 offset:34816
	ds_read_b128 v[172:175], v247 offset:35840
	ds_read_b128 v[176:179], v247 offset:36864
	ds_read_b128 v[180:183], v247 offset:37888
	ds_read_b128 v[184:187], v247 offset:38912
	ds_read_b128 v[188:191], v247 offset:39936
	global_load_lds_dwordx4 v192, s[36:37]
	v_lshl_add_u64 v[212:213], s[36:37], 0, v[196:197]
	s_mov_b32 m0, s44
	s_nop 0
	global_load_lds_dwordx4 v[212:213], off
	s_waitcnt vmcnt(8)
	s_waitcnt lgkmcnt(0)
	s_setprio 1
	s_barrier
	v_mfma_f32_16x16x32_bf16 v[132:135], v[120:123], v[160:163], v[132:135]
	v_mfma_f32_16x16x32_bf16 v[124:127], v[136:139], v[160:163], v[124:127]
	v_mfma_f32_16x16x32_bf16 v[108:111], v[120:123], v[168:171], v[108:111]
	v_mfma_f32_16x16x32_bf16 v[104:107], v[136:139], v[168:171], v[104:107]
	v_mfma_f32_16x16x32_bf16 v[92:95], v[120:123], v[176:179], v[92:95]
	v_mfma_f32_16x16x32_bf16 v[88:91], v[136:139], v[176:179], v[88:91]
	v_mfma_f32_16x16x32_bf16 v[76:79], v[120:123], v[184:187], v[76:79]
	v_mfma_f32_16x16x32_bf16 v[72:75], v[136:139], v[184:187], v[72:75]
	v_mfma_f32_16x16x32_bf16 v[132:135], v[128:131], v[164:167], v[132:135]
	v_mfma_f32_16x16x32_bf16 v[124:127], v[140:143], v[164:167], v[124:127]
	v_mfma_f32_16x16x32_bf16 v[108:111], v[128:131], v[172:175], v[108:111]
	v_mfma_f32_16x16x32_bf16 v[104:107], v[140:143], v[172:175], v[104:107]
	v_mfma_f32_16x16x32_bf16 v[92:95], v[128:131], v[180:183], v[92:95]
	v_mfma_f32_16x16x32_bf16 v[88:91], v[140:143], v[180:183], v[88:91]
	v_mfma_f32_16x16x32_bf16 v[76:79], v[128:131], v[188:191], v[76:79]
	v_mfma_f32_16x16x32_bf16 v[72:75], v[140:143], v[188:191], v[72:75]
	v_mfma_f32_16x16x32_bf16 v[116:119], v[144:147], v[160:163], v[116:119]
	v_mfma_f32_16x16x32_bf16 v[112:115], v[152:155], v[160:163], v[112:115]
	v_mfma_f32_16x16x32_bf16 v[100:103], v[144:147], v[168:171], v[100:103]
	v_mfma_f32_16x16x32_bf16 v[96:99], v[152:155], v[168:171], v[96:99]
	v_mfma_f32_16x16x32_bf16 v[84:87], v[144:147], v[176:179], v[84:87]
	v_mfma_f32_16x16x32_bf16 v[80:83], v[152:155], v[176:179], v[80:83]
	v_mfma_f32_16x16x32_bf16 v[68:71], v[144:147], v[184:187], v[68:71]
	v_mfma_f32_16x16x32_bf16 v[64:67], v[152:155], v[184:187], v[64:67]
	v_mfma_f32_16x16x32_bf16 v[116:119], v[148:151], v[164:167], v[116:119]
	v_mfma_f32_16x16x32_bf16 v[112:115], v[156:159], v[164:167], v[112:115]
	v_mfma_f32_16x16x32_bf16 v[100:103], v[148:151], v[172:175], v[100:103]
	v_mfma_f32_16x16x32_bf16 v[96:99], v[156:159], v[172:175], v[96:99]
	v_mfma_f32_16x16x32_bf16 v[84:87], v[148:151], v[180:183], v[84:87]
	v_mfma_f32_16x16x32_bf16 v[80:83], v[156:159], v[180:183], v[80:83]
	v_mfma_f32_16x16x32_bf16 v[68:71], v[148:151], v[188:191], v[68:71]
	v_mfma_f32_16x16x32_bf16 v[64:67], v[156:159], v[188:191], v[64:67]
	s_barrier
	s_setprio 0
	s_add_i32 s36, s58, s40
	v_lshl_add_u64 v[204:205], v[204:205], 0, s[16:17]
	s_mov_b32 m0, s36
	ds_read_b128 v[160:163], v247 offset:49152
	ds_read_b128 v[164:167], v247 offset:50176
	ds_read_b128 v[168:171], v247 offset:51200
	ds_read_b128 v[172:175], v247 offset:52224
	ds_read_b128 v[176:179], v247 offset:53248
	ds_read_b128 v[180:183], v247 offset:54272
	ds_read_b128 v[184:187], v247 offset:55296
	ds_read_b128 v[188:191], v247 offset:56320
	global_load_lds_dwordx4 v[204:205], off
	s_add_i32 m0, s36, 0x2000
	s_add_u32 s34, s34, 0x40080
	v_lshl_add_u64 v[204:205], v[206:207], 0, s[16:17]
	s_addc_u32 s35, s35, 0
	s_add_i32 s36, s59, s40
	global_load_lds_dwordx4 v[204:205], off
	s_mov_b32 m0, s36
	s_nop 0
	global_load_lds_dwordx4 v194, s[34:35]
	s_add_i32 m0, s36, 0x2000
	s_nop 0
	global_load_lds_dwordx4 v198, s[34:35]
	v_lshl_add_u64 v[204:205], v[208:209], 0, s[16:17]
	s_mov_b32 m0, s46
	s_nop 0
	global_load_lds_dwordx4 v[204:205], off
	v_lshl_add_u64 v[204:205], v[210:211], 0, s[16:17]
	s_mov_b32 m0, s47
	s_nop 0
	global_load_lds_dwordx4 v[204:205], off
	s_waitcnt vmcnt(8)
	s_waitcnt lgkmcnt(0)
	s_setprio 1
	s_barrier
	v_mfma_f32_16x16x32_bf16 v[60:63], v[120:123], v[160:163], v[60:63]
	v_mfma_f32_16x16x32_bf16 v[56:59], v[136:139], v[160:163], v[56:59]
	v_mfma_f32_16x16x32_bf16 v[44:47], v[120:123], v[168:171], v[44:47]
	v_mfma_f32_16x16x32_bf16 v[40:43], v[136:139], v[168:171], v[40:43]
	v_mfma_f32_16x16x32_bf16 v[28:31], v[120:123], v[176:179], v[28:31]
	v_mfma_f32_16x16x32_bf16 v[24:27], v[136:139], v[176:179], v[24:27]
	v_mfma_f32_16x16x32_bf16 v[12:15], v[120:123], v[184:187], v[12:15]
	v_mfma_f32_16x16x32_bf16 v[8:11], v[136:139], v[184:187], v[8:11]
	v_mfma_f32_16x16x32_bf16 v[60:63], v[128:131], v[164:167], v[60:63]
	v_mfma_f32_16x16x32_bf16 v[56:59], v[140:143], v[164:167], v[56:59]
	v_mfma_f32_16x16x32_bf16 v[44:47], v[128:131], v[172:175], v[44:47]
	v_mfma_f32_16x16x32_bf16 v[40:43], v[140:143], v[172:175], v[40:43]
	v_mfma_f32_16x16x32_bf16 v[28:31], v[128:131], v[180:183], v[28:31]
	v_mfma_f32_16x16x32_bf16 v[24:27], v[140:143], v[180:183], v[24:27]
	v_mfma_f32_16x16x32_bf16 v[12:15], v[128:131], v[188:191], v[12:15]
	v_mfma_f32_16x16x32_bf16 v[8:11], v[140:143], v[188:191], v[8:11]
	v_mfma_f32_16x16x32_bf16 v[52:55], v[144:147], v[160:163], v[52:55]
	v_mfma_f32_16x16x32_bf16 v[48:51], v[152:155], v[160:163], v[48:51]
	v_mfma_f32_16x16x32_bf16 v[36:39], v[144:147], v[168:171], v[36:39]
	v_mfma_f32_16x16x32_bf16 v[32:35], v[152:155], v[168:171], v[32:35]
	v_mfma_f32_16x16x32_bf16 v[20:23], v[144:147], v[176:179], v[20:23]
	v_mfma_f32_16x16x32_bf16 v[16:19], v[152:155], v[176:179], v[16:19]
	v_mfma_f32_16x16x32_bf16 v[4:7], v[144:147], v[184:187], v[4:7]
	v_mfma_f32_16x16x32_bf16 v[0:3], v[152:155], v[184:187], v[0:3]
	v_mfma_f32_16x16x32_bf16 v[52:55], v[148:151], v[164:167], v[52:55]
	v_mfma_f32_16x16x32_bf16 v[48:51], v[156:159], v[164:167], v[48:51]
	v_mfma_f32_16x16x32_bf16 v[36:39], v[148:151], v[172:175], v[36:39]
	v_mfma_f32_16x16x32_bf16 v[32:35], v[156:159], v[172:175], v[32:35]
	v_mfma_f32_16x16x32_bf16 v[20:23], v[148:151], v[180:183], v[20:23]
	v_mfma_f32_16x16x32_bf16 v[16:19], v[156:159], v[180:183], v[16:19]
	v_mfma_f32_16x16x32_bf16 v[4:7], v[148:151], v[188:191], v[4:7]
	v_mfma_f32_16x16x32_bf16 v[0:3], v[156:159], v[188:191], v[0:3]
	s_barrier
	s_setprio 0
	s_add_i32 s57, s57, 2
	s_add_u32 s30, s30, 0x100
	s_addc_u32 s31, s31, 0
	s_add_u32 s55, s55, 0x100
	s_addc_u32 s56, s56, 0
	s_cmp_gt_u32 s57, 13
	s_cbranch_scc0 .LBB0_960
	s_and_b64 vcc, exec, s[18:19]
	s_cbranch_vccz .LBB0_963
	s_barrier

; #define PG8_STAGE(bufoff, gbase, voff) do { _Pragma("unroll") for (int _i = 0; _i < 2; ++_i) \
;         __builtin_amdgcn_global_load_lds((const unsigned*)((const char*)(gbase) + (voff)[_i]), (PG8_LAS unsigned*)(lds + (bufoff) + ldsw + _i * 8192), 16, 0, 0); } while (0)
; #define PG8_WAIT_V(n) asm volatile("s_waitcnt vmcnt(" #n ")" ::: "memory")
; #define PG8_BAR __builtin_amdgcn_s_barrier()
; template <class Epi, class Sched, bool ALIGN_EPI = false, bool SP2 = false>
; __device__ __forceinline__ void gemm_phase(PG8_LAS unsigned char* lds, const Gemm g, const Sched& S, const Epi& E) {
;     ...
;     for (int i = 0; i < 2; ++i) { int R, C; stage_rc(tid * 16 + i * 8192, R, C); const int Rb = Epi::PERM ? ((R & ~31) + perm32(R & 31)) : R;
;         voffA[i] = (unsigned)(R * K + C) * 2u; voffB[i] = (unsigned)(Rb * K + C) * 2u; }
;     const size_t kstep = (size_t)(BK * 2);
;     const size_t hstep = (size_t)HALF * K * 2;
;     const size_t tstep = 2 * hstep;
;     const unsigned ldsw = (unsigned)wid * 1024u;
;     const int aoff = lds_byte(wr * 64 + fr, fq * 8), boff = lds_byte(wc * 32 + fr, fq * 8);
;     ...
;         PG8_STAGE(PG8_SB(1, 0), cB + kstep, voffB); PG8_STAGE(PG8_SA(1, 0), cA + kstep, voffA); PG8_STAGE(PG8_SB(1, 1), cB + hstep + kstep, voffB);
;         PG8_WAIT_V(6); PG8_BAR;
.LBB0_1043:
	s_add_u32 s6, s90, 0x12500000
	s_addc_u32 s7, s91, 0
	s_lshl_b32 s8, s8, 5
	s_and_b32 s16, s8, 0x60
	s_mov_b64 s[8:9], 0x80
	s_add_i32 m0, s23, 0x18000
	v_lshl_add_u64 v[6:7], v[6:7], 0, s[8:9]
	s_lshl_b32 s13, s1, 13
	s_lshl_b32 s17, s16, 7
	s_waitcnt vmcnt(2)
	s_barrier
	global_load_lds_dwordx4 v[6:7], off
	v_lshl_add_u64 v[4:5], v[4:5], 0, s[8:9]
	s_add_i32 m0, s23, 0x1a000
	s_add_i32 s42, s23, 0x8000
	s_add_i32 s43, s23, 0xa000
	global_load_lds_dwordx4 v[4:5], off
	v_lshl_add_u64 v[0:1], v[0:1], 0, s[8:9]
	s_mov_b32 m0, s42
	s_add_u32 s14, s26, 0x40080
	global_load_lds_dwordx4 v[0:1], off
	v_lshl_add_u64 v[0:1], v[2:3], 0, s[8:9]
	s_mov_b32 m0, s43
	s_addc_u32 s15, s27, 0
	global_load_lds_dwordx4 v[0:1], off
	s_add_i32 m0, s23, 0x1c000
	s_nop 0
	global_load_lds_dwordx4 v132, s[14:15]
	v_lshl_add_u64 v[0:1], s[14:15], 0, v[128:129]
	s_add_i32 m0, s23, 0x1e000
	s_sext_i32_i16 s49, s0
	global_load_lds_dwordx4 v[0:1], off
	v_and_b32_e32 v0, 15, v254
	v_lshlrev_b32_e32 v1, 1, v12
	v_lshl_or_b32 v144, s1, 6, v0
	v_lshl_or_b32 v2, v0, 6, v1
	v_lshlrev_b32_e32 v0, 2, v0
	v_and_b32_e32 v3, 32, v0
	v_bitop3_b32 v2, v2, s13, v3 bitop3:0xde
	v_lshlrev_b32_e32 v3, 6, v254
	s_movk_i32 s0, 0x3c0
	s_cmpk_lt_u32 s12, 0x100
	v_and_or_b32 v1, v3, s0, v1
	s_cselect_b64 s[12:13], -1, 0
	s_lshl_b32 s0, s1, 8
	s_add_i32 s0, s0, 0
	s_add_i32 s0, s0, 0x20000
	v_and_b32_e32 v3, 32, v8
	v_add_u32_e32 v147, s0, v0
	v_lshlrev_b32_e32 v0, 8, v254
	v_bitop3_b32 v145, s17, v1, v3 bitop3:0xf6
	v_and_b32_e32 v0, 0x38000, v0
	v_lshlrev_b32_e32 v1, 11, v13
	v_or3_b32 v0, v10, v0, v1
	v_add_u32_e32 v136, v0, v11
	v_lshlrev_b32_e32 v0, 4, v9
	s_waitcnt vmcnt(6)
	v_and_b32_e32 v0, 0x78000, v0
	v_or3_b32 v0, v10, v0, v1
	s_add_i32 s44, 0, 0x10000
	s_add_i32 s45, 0, 0x14000
	v_or_b32_e32 v146, s16, v12
	v_mov_b32_e32 v137, v133
	v_add_u32_e32 v138, v0, v11
	v_mov_b32_e32 v139, v133
	v_mov_b64_e32 v[140:141], 0xb00
	v_mov_b64_e32 v[142:143], 0xaff
	v_add_u32_e32 v148, s44, v145
	v_add_u32_e32 v149, s45, v145
	v_add_u32_e32 v150, 0, v2
	s_movk_i32 s46, 0x1600
	s_barrier
	s_branch .LBB0_1046

; #define PG8_STAGE(bufoff, gbase, voff) do { _Pragma("unroll") for (int _i = 0; _i < 2; ++_i) \
;         __builtin_amdgcn_global_load_lds((const unsigned*)((const char*)(gbase) + (voff)[_i]), (PG8_LAS unsigned*)(lds + (bufoff) + ldsw + _i * 8192), 16, 0, 0); } while (0)
; #define PG8_LDA(dst, b, h) do { _Pragma("unroll") for (int m = 0; m < 4; ++m) _Pragma("unroll") for (int k = 0; k < 2; ++k) dst[m][k] = *(const PG8_LAS bf16x8*)(lds + PG8_SA(b, h) + aoff + m * 2048 + k * 1024); } while (0)
; #define PG8_LDB(dst, b, h) do { _Pragma("unroll") for (int n = 0; n < 2; ++n) _Pragma("unroll") for (int k = 0; k < 2; ++k) dst[n][k] = *(const PG8_LAS bf16x8*)(lds + PG8_SB(b, h) + boff + n * 2048 + k * 1024); } while (0)
; #define PG8_WAIT_V(n) asm volatile("s_waitcnt vmcnt(" #n ")" ::: "memory")
; #define PG8_WAIT_L(n) asm volatile("s_waitcnt lgkmcnt(" #n ")" ::: "memory")
; #define PG8_BAR __builtin_amdgcn_s_barrier()
; #define PG8_SCHED __builtin_amdgcn_sched_barrier(0)
; template <class Epi, class Sched, bool ALIGN_EPI = false, bool SP2 = false>
; __device__ __forceinline__ void gemm_phase(PG8_LAS unsigned char* lds, const Gemm g, const Sched& S, const Epi& E) {
;     ...
;         const bool has_next = S.next(ui + 1, nxt);
;         const char* nA = has_next ? (const char*)g.A + (size_t)nxt.pm * tstep : cA; const char* nB = has_next ? (const char*)g.Bt + (size_t)nxt.pn * tstep : cB;
;         for (int t = 0; t < nt; t += 2) {
;             const bool last = (t == nt - 2);
;             const char* a1 = cA + (size_t)(t + 1) * kstep;
;             const char* a2 = last ? nA : cA + (size_t)(t + 2) * kstep; const char* b2 = last ? nB : cB + (size_t)(t + 2) * kstep;
;             const char* a3 = a2 + kstep; const char* b3 = b2 + kstep;
;             if (last && has_next) S.a_ready(nxt, ui + 1);
;             if constexpr (SP2) {
;             PG8_LDB(B0, 0, 0); PG8_LDB(B1, 0, 1); PG8_SCHED; PG8_LDA(At, 0, 0); PG8_STAGE(PG8_SA(1, 1), a1 + hstep, voffA);
;             PG8_WAIT_V(8); PG8_WAIT_L(0); PG8_BAR; PG8_MMA(0, 0, At, B0); PG8_MMA(0, 1, At, B1); PG8_BAR; PG8_SCHED;
;             PG8_LDA(At, 0, 1); PG8_STAGE(PG8_SB(0, 0), b2, voffB); PG8_STAGE(PG8_SB(0, 1), b2 + hstep, voffB); PG8_STAGE(PG8_SA(0, 0), a2, voffA);
;             PG8_WAIT_V(8); PG8_WAIT_L(0); PG8_BAR; PG8_MMA(1, 0, At, B0); PG8_MMA(1, 1, At, B1); PG8_BAR; PG8_SCHED;
.LBB0_1048:
	s_ashr_i32 s17, s16, 31
	s_lshl_b64 s[18:19], s[16:17], 19
	s_add_u32 s18, s34, s18
	s_addc_u32 s19, s35, s19
	s_and_b64 s[20:21], s[0:1], exec
	s_cselect_b32 s17, s19, s25
	s_cselect_b32 s50, s18, s24
	s_ashr_i32 s15, s14, 31
	s_lshl_b64 s[20:21], s[14:15], 19
	s_add_u32 s20, s36, s20
	s_addc_u32 s21, s37, s21
	s_and_b64 s[28:29], s[0:1], exec
	s_cselect_b32 s15, s21, s27
	s_cselect_b32 s51, s20, s26
	s_add_u32 s24, s24, 0x40080
	s_addc_u32 s25, s25, 0
	s_add_u32 s52, s26, 0x100
	s_addc_u32 s53, s27, 0
	s_mov_b32 s54, -2
	s_add_u32 s26, s24, 0xfffc0080
	s_addc_u32 s27, s25, -1
	s_cmp_eq_u32 s54, 12
	s_cselect_b32 s29, s17, s27
	s_cselect_b32 s28, s50, s26
	s_cselect_b32 s27, s15, s53
	s_cselect_b32 s26, s51, s52
	s_add_i32 m0, s23, 0xc000
	s_nop 0
	global_load_lds_dwordx4 v136, s[24:25]
	s_add_i32 m0, s23, 0xe000
	s_nop 0
	global_load_lds_dwordx4 v138, s[24:25]
	s_waitcnt vmcnt(8)
	s_waitcnt lgkmcnt(0)
	s_setprio 1
	s_barrier
	v_mfma_f32_16x16x32_bf16 v[124:127], v[152:155], v[184:187], 0
	v_mfma_f32_16x16x32_bf16 v[120:123], v[160:163], v[184:187], 0
	v_mfma_f32_16x16x32_bf16 v[108:111], v[152:155], v[192:195], 0
	v_mfma_f32_16x16x32_bf16 v[104:107], v[160:163], v[192:195], 0
	v_mfma_f32_16x16x32_bf16 v[92:95], v[152:155], v[200:203], 0
	v_mfma_f32_16x16x32_bf16 v[88:91], v[160:163], v[200:203], 0
	v_mfma_f32_16x16x32_bf16 v[76:79], v[152:155], v[208:211], 0
	v_mfma_f32_16x16x32_bf16 v[72:75], v[160:163], v[208:211], 0
	v_mfma_f32_16x16x32_bf16 v[124:127], v[156:159], v[188:191], v[124:127]
	v_mfma_f32_16x16x32_bf16 v[120:123], v[164:167], v[188:191], v[120:123]
	v_mfma_f32_16x16x32_bf16 v[108:111], v[156:159], v[196:199], v[108:111]
	v_mfma_f32_16x16x32_bf16 v[104:107], v[164:167], v[196:199], v[104:107]
	v_mfma_f32_16x16x32_bf16 v[92:95], v[156:159], v[204:207], v[92:95]
	v_mfma_f32_16x16x32_bf16 v[88:91], v[164:167], v[204:207], v[88:91]
	v_mfma_f32_16x16x32_bf16 v[76:79], v[156:159], v[212:215], v[76:79]
	v_mfma_f32_16x16x32_bf16 v[72:75], v[164:167], v[212:215], v[72:75]
	v_mfma_f32_16x16x32_bf16 v[116:119], v[168:171], v[184:187], 0
	v_mfma_f32_16x16x32_bf16 v[112:115], v[176:179], v[184:187], 0
	v_mfma_f32_16x16x32_bf16 v[100:103], v[168:171], v[192:195], 0
	v_mfma_f32_16x16x32_bf16 v[96:99], v[176:179], v[192:195], 0
	v_mfma_f32_16x16x32_bf16 v[84:87], v[168:171], v[200:203], 0
	v_mfma_f32_16x16x32_bf16 v[80:83], v[176:179], v[200:203], 0
	v_mfma_f32_16x16x32_bf16 v[68:71], v[168:171], v[208:211], 0
	v_mfma_f32_16x16x32_bf16 v[64:67], v[176:179], v[208:211], 0
	v_mfma_f32_16x16x32_bf16 v[116:119], v[172:175], v[188:191], v[116:119]
	v_mfma_f32_16x16x32_bf16 v[112:115], v[180:183], v[188:191], v[112:115]
	v_mfma_f32_16x16x32_bf16 v[100:103], v[172:175], v[196:199], v[100:103]
	v_mfma_f32_16x16x32_bf16 v[96:99], v[180:183], v[196:199], v[96:99]
	v_mfma_f32_16x16x32_bf16 v[84:87], v[172:175], v[204:207], v[84:87]
	v_mfma_f32_16x16x32_bf16 v[80:83], v[180:183], v[204:207], v[80:83]
	v_mfma_f32_16x16x32_bf16 v[68:71], v[172:175], v[212:215], v[68:71]
	v_mfma_f32_16x16x32_bf16 v[64:67], v[180:183], v[212:215], v[64:67]
	s_barrier
	s_setprio 0
	s_add_i32 s55, s44, s33
	v_lshl_add_u64 v[216:217], s[26:27], 0, v[132:133]
	s_mov_b32 m0, s55
	ds_read_b128 v[184:187], v150 offset:16384
	ds_read_b128 v[188:191], v150 offset:17408
	ds_read_b128 v[192:195], v150 offset:18432
	ds_read_b128 v[196:199], v150 offset:19456
	ds_read_b128 v[200:203], v150 offset:20480
	ds_read_b128 v[204:207], v150 offset:21504
	ds_read_b128 v[208:211], v150 offset:22528
	ds_read_b128 v[212:215], v150 offset:23552
	global_load_lds_dwordx4 v[216:217], off
	s_add_i32 m0, s55, 0x2000
	s_add_u32 s56, s26, 0x40000
	v_lshl_add_u64 v[218:219], s[26:27], 0, v[128:129]
	s_addc_u32 s57, s27, 0
	s_add_i32 s55, s45, s33
	global_load_lds_dwordx4 v[218:219], off
	s_mov_b32 m0, s55
	v_lshl_add_u64 v[222:223], s[28:29], 0, v[130:131]
	global_load_lds_dwordx4 v132, s[56:57]
	s_add_i32 m0, s55, 0x2000
	s_nop 0
	global_load_lds_dwordx4 v128, s[56:57]
	v_lshl_add_u64 v[220:221], s[28:29], 0, v[134:135]
	s_mov_b32 m0, s23
	s_nop 0
	global_load_lds_dwordx4 v[220:221], off
	s_mov_b32 m0, s39
	s_nop 0
	global_load_lds_dwordx4 v[222:223], off
	s_waitcnt vmcnt(8)
	s_waitcnt lgkmcnt(0)
	s_setprio 1
	s_barrier
	v_mfma_f32_16x16x32_bf16 v[60:63], v[152:155], v[184:187], 0
	v_mfma_f32_16x16x32_bf16 v[56:59], v[160:163], v[184:187], 0
	v_mfma_f32_16x16x32_bf16 v[44:47], v[152:155], v[192:195], 0
	v_mfma_f32_16x16x32_bf16 v[40:43], v[160:163], v[192:195], 0
	v_mfma_f32_16x16x32_bf16 v[28:31], v[152:155], v[200:203], 0
	v_mfma_f32_16x16x32_bf16 v[24:27], v[160:163], v[200:203], 0
	v_mfma_f32_16x16x32_bf16 v[12:15], v[152:155], v[208:211], 0
	v_mfma_f32_16x16x32_bf16 v[8:11], v[160:163], v[208:211], 0
	v_mfma_f32_16x16x32_bf16 v[60:63], v[156:159], v[188:191], v[60:63]
	v_mfma_f32_16x16x32_bf16 v[56:59], v[164:167], v[188:191], v[56:59]
	v_mfma_f32_16x16x32_bf16 v[44:47], v[156:159], v[196:199], v[44:47]
	v_mfma_f32_16x16x32_bf16 v[40:43], v[164:167], v[196:199], v[40:43]
	v_mfma_f32_16x16x32_bf16 v[28:31], v[156:159], v[204:207], v[28:31]
	v_mfma_f32_16x16x32_bf16 v[24:27], v[164:167], v[204:207], v[24:27]
	v_mfma_f32_16x16x32_bf16 v[12:15], v[156:159], v[212:215], v[12:15]
	v_mfma_f32_16x16x32_bf16 v[8:11], v[164:167], v[212:215], v[8:11]
	v_mfma_f32_16x16x32_bf16 v[52:55], v[168:171], v[184:187], 0
	v_mfma_f32_16x16x32_bf16 v[48:51], v[176:179], v[184:187], 0
	v_mfma_f32_16x16x32_bf16 v[36:39], v[168:171], v[192:195], 0
	v_mfma_f32_16x16x32_bf16 v[32:35], v[176:179], v[192:195], 0
	v_mfma_f32_16x16x32_bf16 v[20:23], v[168:171], v[200:203], 0
	v_mfma_f32_16x16x32_bf16 v[16:19], v[176:179], v[200:203], 0
	v_mfma_f32_16x16x32_bf16 v[4:7], v[168:171], v[208:211], 0
	v_mfma_f32_16x16x32_bf16 v[0:3], v[176:179], v[208:211], 0
	v_mfma_f32_16x16x32_bf16 v[52:55], v[172:175], v[188:191], v[52:55]
	v_mfma_f32_16x16x32_bf16 v[48:51], v[180:183], v[188:191], v[48:51]
	v_mfma_f32_16x16x32_bf16 v[36:39], v[172:175], v[196:199], v[36:39]
	v_mfma_f32_16x16x32_bf16 v[32:35], v[180:183], v[196:199], v[32:35]
	v_mfma_f32_16x16x32_bf16 v[20:23], v[172:175], v[204:207], v[20:23]
	v_mfma_f32_16x16x32_bf16 v[16:19], v[180:183], v[204:207], v[16:19]
	v_mfma_f32_16x16x32_bf16 v[4:7], v[172:175], v[212:215], v[4:7]
	v_mfma_f32_16x16x32_bf16 v[0:3], v[180:183], v[212:215], v[0:3]
	s_barrier
; #define PG8_STAGE(bufoff, gbase, voff) do { _Pragma("unroll") for (int _i = 0; _i < 2; ++_i) \
;         __builtin_amdgcn_global_load_lds((const unsigned*)((const char*)(gbase) + (voff)[_i]), (PG8_LAS unsigned*)(lds + (bufoff) + ldsw + _i * 8192), 16, 0, 0); } while (0)
; #define PG8_LDA(dst, b, h) do { _Pragma("unroll") for (int m = 0; m < 4; ++m) _Pragma("unroll") for (int k = 0; k < 2; ++k) dst[m][k] = *(const PG8_LAS bf16x8*)(lds + PG8_SA(b, h) + aoff + m * 2048 + k * 1024); } while (0)
; #define PG8_LDB(dst, b, h) do { _Pragma("unroll") for (int n = 0; n < 2; ++n) _Pragma("unroll") for (int k = 0; k < 2; ++k) dst[n][k] = *(const PG8_LAS bf16x8*)(lds + PG8_SB(b, h) + boff + n * 2048 + k * 1024); } while (0)
; #define PG8_MMA(ai, bj, At, Bt) do { __builtin_amdgcn_s_setprio(1); _Pragma("unroll") for (int m = 0; m < 4; ++m) _Pragma("unroll") for (int n = 0; n < 2; ++n) _Pragma("unroll") for (int k = 0; k < 2; ++k) \
;         acc[ai][bj][m][n] = __builtin_amdgcn_mfma_f32_16x16x32_bf16(Bt[n][k], At[m][k], acc[ai][bj][m][n], 0, 0, 0); __builtin_amdgcn_s_setprio(0); } while (0)
; #define PG8_WAIT_V(n) asm volatile("s_waitcnt vmcnt(" #n ")" ::: "memory")
; #define PG8_WAIT_L(n) asm volatile("s_waitcnt lgkmcnt(" #n ")" ::: "memory")
; #define PG8_BAR __builtin_amdgcn_s_barrier()
; #define PG8_SCHED __builtin_amdgcn_sched_barrier(0)
; template <class Epi, class Sched, bool ALIGN_EPI = false, bool SP2 = false>
; __device__ __forceinline__ void gemm_phase(PG8_LAS unsigned char* lds, const Gemm g, const Sched& S, const Epi& E) {
;     ...
;             PG8_LDB(B0, 1, 0); PG8_LDB(B1, 1, 1); PG8_SCHED; PG8_LDA(At, 1, 0); PG8_STAGE(PG8_SA(0, 1), a2 + hstep, voffA);
;             PG8_WAIT_V(8); PG8_WAIT_L(0); PG8_BAR; PG8_MMA(0, 0, At, B0); PG8_MMA(0, 1, At, B1); PG8_BAR; PG8_SCHED;
;             PG8_LDA(At, 1, 1); PG8_STAGE(PG8_SB(1, 0), b3, voffB); PG8_STAGE(PG8_SB(1, 1), b3 + hstep, voffB); PG8_STAGE(PG8_SA(1, 0), a3, voffA);
;             PG8_WAIT_V(8); PG8_WAIT_L(0); PG8_BAR; PG8_MMA(1, 0, At, B0); PG8_MMA(1, 1, At, B1); PG8_BAR; PG8_SCHED;
	s_setprio 0
	s_add_i32 s55, 0, 0x18000
	v_add_u32_e32 v151, s55, v145
	s_add_i32 s56, 0, 0x1c000
	ds_read_b128 v[152:155], v151
	ds_read_b128 v[156:159], v151 offset:1024
	ds_read_b128 v[160:163], v151 offset:2048
	ds_read_b128 v[164:167], v151 offset:3072
	v_add_u32_e32 v151, s56, v145
	ds_read_b128 v[168:171], v151
	ds_read_b128 v[172:175], v151 offset:1024
	ds_read_b128 v[176:179], v151 offset:2048
	ds_read_b128 v[180:183], v151 offset:3072
	s_add_u32 s28, s28, 0x40000
	s_addc_u32 s29, s29, 0
	s_mov_b32 m0, s40
	ds_read_b128 v[184:187], v150 offset:32768
	ds_read_b128 v[188:191], v150 offset:33792
	ds_read_b128 v[192:195], v150 offset:34816
	ds_read_b128 v[196:199], v150 offset:35840
	ds_read_b128 v[200:203], v150 offset:36864
	ds_read_b128 v[204:207], v150 offset:37888
	ds_read_b128 v[208:211], v150 offset:38912
	ds_read_b128 v[212:215], v150 offset:39936
	global_load_lds_dwordx4 v134, s[28:29]
	s_mov_b32 m0, s41
	s_nop 0
	global_load_lds_dwordx4 v130, s[28:29]
	s_waitcnt vmcnt(8)
	s_waitcnt lgkmcnt(0)
	s_setprio 1
	s_barrier
	v_mfma_f32_16x16x32_bf16 v[124:127], v[152:155], v[184:187], v[124:127]
	v_mfma_f32_16x16x32_bf16 v[120:123], v[160:163], v[184:187], v[120:123]
	v_mfma_f32_16x16x32_bf16 v[108:111], v[152:155], v[192:195], v[108:111]
	v_mfma_f32_16x16x32_bf16 v[104:107], v[160:163], v[192:195], v[104:107]
	v_mfma_f32_16x16x32_bf16 v[92:95], v[152:155], v[200:203], v[92:95]
	v_mfma_f32_16x16x32_bf16 v[88:91], v[160:163], v[200:203], v[88:91]
	v_mfma_f32_16x16x32_bf16 v[76:79], v[152:155], v[208:211], v[76:79]
	v_mfma_f32_16x16x32_bf16 v[72:75], v[160:163], v[208:211], v[72:75]
	v_mfma_f32_16x16x32_bf16 v[124:127], v[156:159], v[188:191], v[124:127]
	v_mfma_f32_16x16x32_bf16 v[120:123], v[164:167], v[188:191], v[120:123]
	v_mfma_f32_16x16x32_bf16 v[108:111], v[156:159], v[196:199], v[108:111]
	v_mfma_f32_16x16x32_bf16 v[104:107], v[164:167], v[196:199], v[104:107]
	v_mfma_f32_16x16x32_bf16 v[92:95], v[156:159], v[204:207], v[92:95]
	v_mfma_f32_16x16x32_bf16 v[88:91], v[164:167], v[204:207], v[88:91]
	v_mfma_f32_16x16x32_bf16 v[76:79], v[156:159], v[212:215], v[76:79]
	v_mfma_f32_16x16x32_bf16 v[72:75], v[164:167], v[212:215], v[72:75]
	v_mfma_f32_16x16x32_bf16 v[116:119], v[168:171], v[184:187], v[116:119]
	v_mfma_f32_16x16x32_bf16 v[112:115], v[176:179], v[184:187], v[112:115]
	v_mfma_f32_16x16x32_bf16 v[100:103], v[168:171], v[192:195], v[100:103]
	v_mfma_f32_16x16x32_bf16 v[96:99], v[176:179], v[192:195], v[96:99]
	v_mfma_f32_16x16x32_bf16 v[84:87], v[168:171], v[200:203], v[84:87]
	v_mfma_f32_16x16x32_bf16 v[80:83], v[176:179], v[200:203], v[80:83]
	v_mfma_f32_16x16x32_bf16 v[68:71], v[168:171], v[208:211], v[68:71]
	v_mfma_f32_16x16x32_bf16 v[64:67], v[176:179], v[208:211], v[64:67]
	v_mfma_f32_16x16x32_bf16 v[116:119], v[172:175], v[188:191], v[116:119]
	v_mfma_f32_16x16x32_bf16 v[112:115], v[180:183], v[188:191], v[112:115]
	v_mfma_f32_16x16x32_bf16 v[100:103], v[172:175], v[196:199], v[100:103]
	v_mfma_f32_16x16x32_bf16 v[96:99], v[180:183], v[196:199], v[96:99]
	v_mfma_f32_16x16x32_bf16 v[84:87], v[172:175], v[204:207], v[84:87]
	v_mfma_f32_16x16x32_bf16 v[80:83], v[180:183], v[204:207], v[80:83]
	v_mfma_f32_16x16x32_bf16 v[68:71], v[172:175], v[212:215], v[68:71]
	v_mfma_f32_16x16x32_bf16 v[64:67], v[180:183], v[212:215], v[64:67]
	s_barrier
	s_setprio 0
	s_add_i32 s28, s55, s33
	v_lshl_add_u64 v[216:217], v[216:217], 0, s[8:9]
	s_mov_b32 m0, s28
	ds_read_b128 v[184:187], v150 offset:49152
	ds_read_b128 v[188:191], v150 offset:50176
	ds_read_b128 v[192:195], v150 offset:51200
	ds_read_b128 v[196:199], v150 offset:52224
	ds_read_b128 v[200:203], v150 offset:53248
	ds_read_b128 v[204:207], v150 offset:54272
	ds_read_b128 v[208:211], v150 offset:55296
	ds_read_b128 v[212:215], v150 offset:56320
	global_load_lds_dwordx4 v[216:217], off
	s_add_i32 m0, s28, 0x2000
	s_add_u32 s26, s26, 0x40080
	v_lshl_add_u64 v[216:217], v[218:219], 0, s[8:9]
	s_addc_u32 s27, s27, 0
	s_add_i32 s28, s56, s33
	global_load_lds_dwordx4 v[216:217], off
	s_mov_b32 m0, s28
	s_nop 0
	global_load_lds_dwordx4 v132, s[26:27]
	s_add_i32 m0, s28, 0x2000
	s_nop 0
	global_load_lds_dwordx4 v128, s[26:27]
	v_lshl_add_u64 v[216:217], v[220:221], 0, s[8:9]
	s_mov_b32 m0, s42
	s_nop 0
	global_load_lds_dwordx4 v[216:217], off
	v_lshl_add_u64 v[216:217], v[222:223], 0, s[8:9]
	s_mov_b32 m0, s43
	s_nop 0
	global_load_lds_dwordx4 v[216:217], off
	s_waitcnt vmcnt(8)
	s_waitcnt lgkmcnt(0)
	s_setprio 1
	s_barrier
	v_mfma_f32_16x16x32_bf16 v[60:63], v[152:155], v[184:187], v[60:63]
	v_mfma_f32_16x16x32_bf16 v[56:59], v[160:163], v[184:187], v[56:59]
	v_mfma_f32_16x16x32_bf16 v[44:47], v[152:155], v[192:195], v[44:47]
	v_mfma_f32_16x16x32_bf16 v[40:43], v[160:163], v[192:195], v[40:43]
	v_mfma_f32_16x16x32_bf16 v[28:31], v[152:155], v[200:203], v[28:31]
	v_mfma_f32_16x16x32_bf16 v[24:27], v[160:163], v[200:203], v[24:27]
	v_mfma_f32_16x16x32_bf16 v[12:15], v[152:155], v[208:211], v[12:15]
	v_mfma_f32_16x16x32_bf16 v[8:11], v[160:163], v[208:211], v[8:11]
	v_mfma_f32_16x16x32_bf16 v[60:63], v[156:159], v[188:191], v[60:63]
	v_mfma_f32_16x16x32_bf16 v[56:59], v[164:167], v[188:191], v[56:59]
	v_mfma_f32_16x16x32_bf16 v[44:47], v[156:159], v[196:199], v[44:47]
	v_mfma_f32_16x16x32_bf16 v[40:43], v[164:167], v[196:199], v[40:43]
	v_mfma_f32_16x16x32_bf16 v[28:31], v[156:159], v[204:207], v[28:31]
	v_mfma_f32_16x16x32_bf16 v[24:27], v[164:167], v[204:207], v[24:27]
	v_mfma_f32_16x16x32_bf16 v[12:15], v[156:159], v[212:215], v[12:15]
	v_mfma_f32_16x16x32_bf16 v[8:11], v[164:167], v[212:215], v[8:11]
	v_mfma_f32_16x16x32_bf16 v[52:55], v[168:171], v[184:187], v[52:55]
	v_mfma_f32_16x16x32_bf16 v[48:51], v[176:179], v[184:187], v[48:51]
	v_mfma_f32_16x16x32_bf16 v[36:39], v[168:171], v[192:195], v[36:39]
	v_mfma_f32_16x16x32_bf16 v[32:35], v[176:179], v[192:195], v[32:35]
	v_mfma_f32_16x16x32_bf16 v[20:23], v[168:171], v[200:203], v[20:23]
	v_mfma_f32_16x16x32_bf16 v[16:19], v[176:179], v[200:203], v[16:19]
	v_mfma_f32_16x16x32_bf16 v[4:7], v[168:171], v[208:211], v[4:7]
	v_mfma_f32_16x16x32_bf16 v[0:3], v[176:179], v[208:211], v[0:3]
	v_mfma_f32_16x16x32_bf16 v[52:55], v[172:175], v[188:191], v[52:55]
	v_mfma_f32_16x16x32_bf16 v[48:51], v[180:183], v[188:191], v[48:51]
	v_mfma_f32_16x16x32_bf16 v[36:39], v[172:175], v[196:199], v[36:39]
	v_mfma_f32_16x16x32_bf16 v[32:35], v[180:183], v[196:199], v[32:35]
	v_mfma_f32_16x16x32_bf16 v[20:23], v[172:175], v[204:207], v[20:23]
	v_mfma_f32_16x16x32_bf16 v[16:19], v[180:183], v[204:207], v[16:19]
	v_mfma_f32_16x16x32_bf16 v[4:7], v[172:175], v[212:215], v[4:7]
	v_mfma_f32_16x16x32_bf16 v[0:3], v[180:183], v[212:215], v[0:3]
	s_barrier
	s_setprio 0
	s_add_i32 s54, s54, 2
	s_add_u32 s24, s24, 0x100
	s_addc_u32 s25, s25, 0
	s_add_u32 s52, s52, 0x100
	s_addc_u32 s53, s53, 0
	s_cmp_gt_u32 s54, 13

; #define PG8_STAGE(bufoff, gbase, voff) do { _Pragma("unroll") for (int _i = 0; _i < 2; ++_i) \
;         __builtin_amdgcn_global_load_lds((const unsigned*)((const char*)(gbase) + (voff)[_i]), (PG8_LAS unsigned*)(lds + (bufoff) + ldsw + _i * 8192), 16, 0, 0); } while (0)
; #define PG8_LDA(dst, b, h) do { _Pragma("unroll") for (int m = 0; m < 4; ++m) _Pragma("unroll") for (int k = 0; k < 2; ++k) dst[m][k] = *(const PG8_LAS bf16x8*)(lds + PG8_SA(b, h) + aoff + m * 2048 + k * 1024); } while (0)
; #define PG8_LDB(dst, b, h) do { _Pragma("unroll") for (int n = 0; n < 2; ++n) _Pragma("unroll") for (int k = 0; k < 2; ++k) dst[n][k] = *(const PG8_LAS bf16x8*)(lds + PG8_SB(b, h) + boff + n * 2048 + k * 1024); } while (0)
; #define PG8_WAIT_V(n) asm volatile("s_waitcnt vmcnt(" #n ")" ::: "memory")
; #define PG8_WAIT_L(n) asm volatile("s_waitcnt lgkmcnt(" #n ")" ::: "memory")
; #define PG8_BAR __builtin_amdgcn_s_barrier()
; #define PG8_SCHED __builtin_amdgcn_sched_barrier(0)
; template <class Epi, class Sched, bool ALIGN_EPI = false, bool SP2 = false>
; __device__ __forceinline__ void gemm_phase(PG8_LAS unsigned char* lds, const Gemm g, const Sched& S, const Epi& E) {
;     ...
;         const bool has_next = S.next(ui + 1, nxt);
;         const char* nA = has_next ? (const char*)g.A + (size_t)nxt.pm * tstep : cA; const char* nB = has_next ? (const char*)g.Bt + (size_t)nxt.pn * tstep : cB;
;         for (int t = 0; t < nt; t += 2) {
;             const bool last = (t == nt - 2);
;             const char* a1 = cA + (size_t)(t + 1) * kstep;
;             const char* a2 = last ? nA : cA + (size_t)(t + 2) * kstep; const char* b2 = last ? nB : cB + (size_t)(t + 2) * kstep;
;             const char* a3 = a2 + kstep; const char* b3 = b2 + kstep;
;             if (last && has_next) S.a_ready(nxt, ui + 1);
;             if constexpr (SP2) {
;             PG8_LDB(B0, 0, 0); PG8_LDB(B1, 0, 1); PG8_SCHED; PG8_LDA(At, 0, 0); PG8_STAGE(PG8_SA(1, 1), a1 + hstep, voffA);
;             PG8_WAIT_V(8); PG8_WAIT_L(0); PG8_BAR; PG8_MMA(0, 0, At, B0); PG8_MMA(0, 1, At, B1); PG8_BAR; PG8_SCHED;
;             PG8_LDA(At, 0, 1); PG8_STAGE(PG8_SB(0, 0), b2, voffB); PG8_STAGE(PG8_SB(0, 1), b2 + hstep, voffB); PG8_STAGE(PG8_SA(0, 0), a2, voffA);
;             PG8_WAIT_V(8); PG8_WAIT_L(0); PG8_BAR; PG8_MMA(1, 0, At, B0); PG8_MMA(1, 1, At, B1); PG8_BAR; PG8_SCHED;
.LBB0_1129:
	s_add_u32 s24, s24, 0xb0080
	s_addc_u32 s25, s25, 0
	s_add_u32 s51, s26, 0x100
	s_addc_u32 s52, s27, 0
	s_mov_b32 s53, -2
	s_add_u32 s26, s24, 0xfff50080
	s_addc_u32 s27, s25, -1
	s_cmp_eq_u32 s53, 40
	s_cselect_b32 s29, s7, s27
	s_cselect_b32 s28, s6, s26
	s_cselect_b32 s27, s23, s52
	s_cselect_b32 s26, s22, s51
	s_add_i32 m0, s35, 0xc000
	s_nop 0
	global_load_lds_dwordx4 v200, s[24:25]
	s_add_i32 m0, s35, 0xe000
	s_nop 0
	global_load_lds_dwordx4 v202, s[24:25]
	s_waitcnt vmcnt(8)
	s_waitcnt lgkmcnt(0)
	s_setprio 1
	s_barrier
	v_mfma_f32_16x16x32_bf16 v[132:135], v[120:123], v[160:163], 0
	v_mfma_f32_16x16x32_bf16 v[124:127], v[136:139], v[160:163], 0
	v_mfma_f32_16x16x32_bf16 v[108:111], v[120:123], v[168:171], 0
	v_mfma_f32_16x16x32_bf16 v[104:107], v[136:139], v[168:171], 0
	v_mfma_f32_16x16x32_bf16 v[92:95], v[120:123], v[176:179], 0
	v_mfma_f32_16x16x32_bf16 v[88:91], v[136:139], v[176:179], 0
	v_mfma_f32_16x16x32_bf16 v[76:79], v[120:123], v[184:187], 0
	v_mfma_f32_16x16x32_bf16 v[72:75], v[136:139], v[184:187], 0
	v_mfma_f32_16x16x32_bf16 v[132:135], v[128:131], v[164:167], v[132:135]
	v_mfma_f32_16x16x32_bf16 v[124:127], v[140:143], v[164:167], v[124:127]
	v_mfma_f32_16x16x32_bf16 v[108:111], v[128:131], v[172:175], v[108:111]
	v_mfma_f32_16x16x32_bf16 v[104:107], v[140:143], v[172:175], v[104:107]
	v_mfma_f32_16x16x32_bf16 v[92:95], v[128:131], v[180:183], v[92:95]
	v_mfma_f32_16x16x32_bf16 v[88:91], v[140:143], v[180:183], v[88:91]
	v_mfma_f32_16x16x32_bf16 v[76:79], v[128:131], v[188:191], v[76:79]
	v_mfma_f32_16x16x32_bf16 v[72:75], v[140:143], v[188:191], v[72:75]
	v_mfma_f32_16x16x32_bf16 v[116:119], v[144:147], v[160:163], 0
	v_mfma_f32_16x16x32_bf16 v[112:115], v[152:155], v[160:163], 0
	v_mfma_f32_16x16x32_bf16 v[100:103], v[144:147], v[168:171], 0
	v_mfma_f32_16x16x32_bf16 v[96:99], v[152:155], v[168:171], 0
	v_mfma_f32_16x16x32_bf16 v[84:87], v[144:147], v[176:179], 0
	v_mfma_f32_16x16x32_bf16 v[80:83], v[152:155], v[176:179], 0
	v_mfma_f32_16x16x32_bf16 v[68:71], v[144:147], v[184:187], 0
	v_mfma_f32_16x16x32_bf16 v[64:67], v[152:155], v[184:187], 0
	v_mfma_f32_16x16x32_bf16 v[116:119], v[148:151], v[164:167], v[116:119]
	v_mfma_f32_16x16x32_bf16 v[112:115], v[156:159], v[164:167], v[112:115]
	v_mfma_f32_16x16x32_bf16 v[100:103], v[148:151], v[172:175], v[100:103]
	v_mfma_f32_16x16x32_bf16 v[96:99], v[156:159], v[172:175], v[96:99]
	v_mfma_f32_16x16x32_bf16 v[84:87], v[148:151], v[180:183], v[84:87]
	v_mfma_f32_16x16x32_bf16 v[80:83], v[156:159], v[180:183], v[80:83]
	v_mfma_f32_16x16x32_bf16 v[68:71], v[148:151], v[188:191], v[68:71]
	v_mfma_f32_16x16x32_bf16 v[64:67], v[156:159], v[188:191], v[64:67]
	s_barrier
	s_setprio 0
	s_add_i32 s54, s45, s34
	v_lshl_add_u64 v[204:205], s[26:27], 0, v[194:195]
	s_mov_b32 m0, s54
	ds_read_b128 v[160:163], v247 offset:16384
	ds_read_b128 v[164:167], v247 offset:17408
	ds_read_b128 v[168:171], v247 offset:18432
	ds_read_b128 v[172:175], v247 offset:19456
	ds_read_b128 v[176:179], v247 offset:20480
	ds_read_b128 v[180:183], v247 offset:21504
	ds_read_b128 v[184:187], v247 offset:22528
	ds_read_b128 v[188:191], v247 offset:23552
	global_load_lds_dwordx4 v[204:205], off
	s_add_i32 m0, s54, 0x2000
	s_add_u32 s54, s26, 0xb0000
	v_lshl_add_u64 v[206:207], s[26:27], 0, v[198:199]
	s_addc_u32 s55, s27, 0
	s_add_i32 s56, s46, s34
	global_load_lds_dwordx4 v[206:207], off
	s_mov_b32 m0, s56
	v_lshl_add_u64 v[210:211], s[28:29], 0, v[196:197]
	global_load_lds_dwordx4 v194, s[54:55]
	s_add_i32 m0, s56, 0x2000
	s_nop 0
	global_load_lds_dwordx4 v198, s[54:55]
	v_lshl_add_u64 v[208:209], s[28:29], 0, v[192:193]
	s_mov_b32 m0, s35
	s_nop 0
	global_load_lds_dwordx4 v[208:209], off
	s_mov_b32 m0, s36
	s_nop 0
	global_load_lds_dwordx4 v[210:211], off
	s_waitcnt vmcnt(8)
	s_waitcnt lgkmcnt(0)
	s_setprio 1
	s_barrier
	v_mfma_f32_16x16x32_bf16 v[60:63], v[120:123], v[160:163], 0
	v_mfma_f32_16x16x32_bf16 v[56:59], v[136:139], v[160:163], 0
	v_mfma_f32_16x16x32_bf16 v[44:47], v[120:123], v[168:171], 0
	v_mfma_f32_16x16x32_bf16 v[40:43], v[136:139], v[168:171], 0
	v_mfma_f32_16x16x32_bf16 v[28:31], v[120:123], v[176:179], 0
	v_mfma_f32_16x16x32_bf16 v[24:27], v[136:139], v[176:179], 0
	v_mfma_f32_16x16x32_bf16 v[12:15], v[120:123], v[184:187], 0
	v_mfma_f32_16x16x32_bf16 v[8:11], v[136:139], v[184:187], 0
	v_mfma_f32_16x16x32_bf16 v[60:63], v[128:131], v[164:167], v[60:63]
	v_mfma_f32_16x16x32_bf16 v[56:59], v[140:143], v[164:167], v[56:59]
	v_mfma_f32_16x16x32_bf16 v[44:47], v[128:131], v[172:175], v[44:47]
	v_mfma_f32_16x16x32_bf16 v[40:43], v[140:143], v[172:175], v[40:43]
	v_mfma_f32_16x16x32_bf16 v[28:31], v[128:131], v[180:183], v[28:31]
	v_mfma_f32_16x16x32_bf16 v[24:27], v[140:143], v[180:183], v[24:27]
	v_mfma_f32_16x16x32_bf16 v[12:15], v[128:131], v[188:191], v[12:15]
	v_mfma_f32_16x16x32_bf16 v[8:11], v[140:143], v[188:191], v[8:11]
	v_mfma_f32_16x16x32_bf16 v[52:55], v[144:147], v[160:163], 0
	v_mfma_f32_16x16x32_bf16 v[48:51], v[152:155], v[160:163], 0
	v_mfma_f32_16x16x32_bf16 v[36:39], v[144:147], v[168:171], 0
	v_mfma_f32_16x16x32_bf16 v[32:35], v[152:155], v[168:171], 0
	v_mfma_f32_16x16x32_bf16 v[20:23], v[144:147], v[176:179], 0
	v_mfma_f32_16x16x32_bf16 v[16:19], v[152:155], v[176:179], 0
	v_mfma_f32_16x16x32_bf16 v[4:7], v[144:147], v[184:187], 0
	v_mfma_f32_16x16x32_bf16 v[0:3], v[152:155], v[184:187], 0
	v_mfma_f32_16x16x32_bf16 v[52:55], v[148:151], v[164:167], v[52:55]
	v_mfma_f32_16x16x32_bf16 v[48:51], v[156:159], v[164:167], v[48:51]
	v_mfma_f32_16x16x32_bf16 v[36:39], v[148:151], v[172:175], v[36:39]
	v_mfma_f32_16x16x32_bf16 v[32:35], v[156:159], v[172:175], v[32:35]
	v_mfma_f32_16x16x32_bf16 v[20:23], v[148:151], v[180:183], v[20:23]
	v_mfma_f32_16x16x32_bf16 v[16:19], v[156:159], v[180:183], v[16:19]
	v_mfma_f32_16x16x32_bf16 v[4:7], v[148:151], v[188:191], v[4:7]
	v_mfma_f32_16x16x32_bf16 v[0:3], v[156:159], v[188:191], v[0:3]
	s_barrier
; #define PG8_STAGE(bufoff, gbase, voff) do { _Pragma("unroll") for (int _i = 0; _i < 2; ++_i) \
;         __builtin_amdgcn_global_load_lds((const unsigned*)((const char*)(gbase) + (voff)[_i]), (PG8_LAS unsigned*)(lds + (bufoff) + ldsw + _i * 8192), 16, 0, 0); } while (0)
; #define PG8_LDA(dst, b, h) do { _Pragma("unroll") for (int m = 0; m < 4; ++m) _Pragma("unroll") for (int k = 0; k < 2; ++k) dst[m][k] = *(const PG8_LAS bf16x8*)(lds + PG8_SA(b, h) + aoff + m * 2048 + k * 1024); } while (0)
; #define PG8_LDB(dst, b, h) do { _Pragma("unroll") for (int n = 0; n < 2; ++n) _Pragma("unroll") for (int k = 0; k < 2; ++k) dst[n][k] = *(const PG8_LAS bf16x8*)(lds + PG8_SB(b, h) + boff + n * 2048 + k * 1024); } while (0)
; #define PG8_MMA(ai, bj, At, Bt) do { __builtin_amdgcn_s_setprio(1); _Pragma("unroll") for (int m = 0; m < 4; ++m) _Pragma("unroll") for (int n = 0; n < 2; ++n) _Pragma("unroll") for (int k = 0; k < 2; ++k) \
;         acc[ai][bj][m][n] = __builtin_amdgcn_mfma_f32_16x16x32_bf16(Bt[n][k], At[m][k], acc[ai][bj][m][n], 0, 0, 0); __builtin_amdgcn_s_setprio(0); } while (0)
; #define PG8_WAIT_V(n) asm volatile("s_waitcnt vmcnt(" #n ")" ::: "memory")
; #define PG8_WAIT_L(n) asm volatile("s_waitcnt lgkmcnt(" #n ")" ::: "memory")
; #define PG8_BAR __builtin_amdgcn_s_barrier()
; #define PG8_SCHED __builtin_amdgcn_sched_barrier(0)
; template <class Epi, class Sched, bool ALIGN_EPI = false, bool SP2 = false>
; __device__ __forceinline__ void gemm_phase(PG8_LAS unsigned char* lds, const Gemm g, const Sched& S, const Epi& E) {
;     ...
;             PG8_LDB(B0, 1, 0); PG8_LDB(B1, 1, 1); PG8_SCHED; PG8_LDA(At, 1, 0); PG8_STAGE(PG8_SA(0, 1), a2 + hstep, voffA);
;             PG8_WAIT_V(8); PG8_WAIT_L(0); PG8_BAR; PG8_MMA(0, 0, At, B0); PG8_MMA(0, 1, At, B1); PG8_BAR; PG8_SCHED;
;             PG8_LDA(At, 1, 1); PG8_STAGE(PG8_SB(1, 0), b3, voffB); PG8_STAGE(PG8_SB(1, 1), b3 + hstep, voffB); PG8_STAGE(PG8_SA(1, 0), a3, voffA);
;             PG8_WAIT_V(8); PG8_WAIT_L(0); PG8_BAR; PG8_MMA(1, 0, At, B0); PG8_MMA(1, 1, At, B1); PG8_BAR; PG8_SCHED;
	s_setprio 0
	s_add_i32 s54, 0, 0x18000
	s_add_i32 s55, 0, 0x1c000
	v_add_u32_e32 v140, s54, v243
	v_add_u32_e32 v156, s55, v243
	ds_read_b128 v[120:123], v140
	ds_read_b128 v[128:131], v140 offset:1024
	ds_read_b128 v[136:139], v140 offset:2048
	ds_read_b128 v[140:143], v140 offset:3072
	ds_read_b128 v[144:147], v156
	ds_read_b128 v[148:151], v156 offset:1024
	ds_read_b128 v[152:155], v156 offset:2048
	ds_read_b128 v[156:159], v156 offset:3072
	s_add_u32 s28, s28, 0xb0000
	s_addc_u32 s29, s29, 0
	s_mov_b32 m0, s37
	ds_read_b128 v[160:163], v247 offset:32768
	ds_read_b128 v[164:167], v247 offset:33792
	ds_read_b128 v[168:171], v247 offset:34816
	ds_read_b128 v[172:175], v247 offset:35840
	ds_read_b128 v[176:179], v247 offset:36864
	ds_read_b128 v[180:183], v247 offset:37888
	ds_read_b128 v[184:187], v247 offset:38912
	ds_read_b128 v[188:191], v247 offset:39936
	global_load_lds_dwordx4 v192, s[28:29]
	s_mov_b32 m0, s38
	s_nop 0
	global_load_lds_dwordx4 v196, s[28:29]
	s_waitcnt vmcnt(8)
	s_waitcnt lgkmcnt(0)
	s_setprio 1
	s_barrier
	v_mfma_f32_16x16x32_bf16 v[132:135], v[120:123], v[160:163], v[132:135]
	v_mfma_f32_16x16x32_bf16 v[124:127], v[136:139], v[160:163], v[124:127]
	v_mfma_f32_16x16x32_bf16 v[108:111], v[120:123], v[168:171], v[108:111]
	v_mfma_f32_16x16x32_bf16 v[104:107], v[136:139], v[168:171], v[104:107]
	v_mfma_f32_16x16x32_bf16 v[92:95], v[120:123], v[176:179], v[92:95]
	v_mfma_f32_16x16x32_bf16 v[88:91], v[136:139], v[176:179], v[88:91]
	v_mfma_f32_16x16x32_bf16 v[76:79], v[120:123], v[184:187], v[76:79]
	v_mfma_f32_16x16x32_bf16 v[72:75], v[136:139], v[184:187], v[72:75]
	v_mfma_f32_16x16x32_bf16 v[132:135], v[128:131], v[164:167], v[132:135]
	v_mfma_f32_16x16x32_bf16 v[124:127], v[140:143], v[164:167], v[124:127]
	v_mfma_f32_16x16x32_bf16 v[108:111], v[128:131], v[172:175], v[108:111]
	v_mfma_f32_16x16x32_bf16 v[104:107], v[140:143], v[172:175], v[104:107]
	v_mfma_f32_16x16x32_bf16 v[92:95], v[128:131], v[180:183], v[92:95]
	v_mfma_f32_16x16x32_bf16 v[88:91], v[140:143], v[180:183], v[88:91]
	v_mfma_f32_16x16x32_bf16 v[76:79], v[128:131], v[188:191], v[76:79]
	v_mfma_f32_16x16x32_bf16 v[72:75], v[140:143], v[188:191], v[72:75]
	v_mfma_f32_16x16x32_bf16 v[116:119], v[144:147], v[160:163], v[116:119]
	v_mfma_f32_16x16x32_bf16 v[112:115], v[152:155], v[160:163], v[112:115]
	v_mfma_f32_16x16x32_bf16 v[100:103], v[144:147], v[168:171], v[100:103]
	v_mfma_f32_16x16x32_bf16 v[96:99], v[152:155], v[168:171], v[96:99]
	v_mfma_f32_16x16x32_bf16 v[84:87], v[144:147], v[176:179], v[84:87]
	v_mfma_f32_16x16x32_bf16 v[80:83], v[152:155], v[176:179], v[80:83]
	v_mfma_f32_16x16x32_bf16 v[68:71], v[144:147], v[184:187], v[68:71]
	v_mfma_f32_16x16x32_bf16 v[64:67], v[152:155], v[184:187], v[64:67]
	v_mfma_f32_16x16x32_bf16 v[116:119], v[148:151], v[164:167], v[116:119]
	v_mfma_f32_16x16x32_bf16 v[112:115], v[156:159], v[164:167], v[112:115]
	v_mfma_f32_16x16x32_bf16 v[100:103], v[148:151], v[172:175], v[100:103]
	v_mfma_f32_16x16x32_bf16 v[96:99], v[156:159], v[172:175], v[96:99]
	v_mfma_f32_16x16x32_bf16 v[84:87], v[148:151], v[180:183], v[84:87]
	v_mfma_f32_16x16x32_bf16 v[80:83], v[156:159], v[180:183], v[80:83]
	v_mfma_f32_16x16x32_bf16 v[68:71], v[148:151], v[188:191], v[68:71]
	v_mfma_f32_16x16x32_bf16 v[64:67], v[156:159], v[188:191], v[64:67]
	s_barrier
	s_setprio 0
	s_add_i32 s28, s54, s34
	v_lshl_add_u64 v[204:205], v[204:205], 0, s[18:19]
	s_mov_b32 m0, s28
	ds_read_b128 v[160:163], v247 offset:49152
	ds_read_b128 v[164:167], v247 offset:50176
	ds_read_b128 v[168:171], v247 offset:51200
	ds_read_b128 v[172:175], v247 offset:52224
	ds_read_b128 v[176:179], v247 offset:53248
	ds_read_b128 v[180:183], v247 offset:54272
	ds_read_b128 v[184:187], v247 offset:55296
	ds_read_b128 v[188:191], v247 offset:56320
	global_load_lds_dwordx4 v[204:205], off
	s_add_i32 m0, s28, 0x2000
	s_add_u32 s26, s26, 0xb0080
	v_lshl_add_u64 v[204:205], v[206:207], 0, s[18:19]
	s_addc_u32 s27, s27, 0
	s_add_i32 s28, s55, s34
	global_load_lds_dwordx4 v[204:205], off
	s_mov_b32 m0, s28
	s_nop 0
	global_load_lds_dwordx4 v194, s[26:27]
	s_add_i32 m0, s28, 0x2000
	s_nop 0
	global_load_lds_dwordx4 v198, s[26:27]
	v_lshl_add_u64 v[204:205], v[208:209], 0, s[18:19]
	s_mov_b32 m0, s40
	s_nop 0
	global_load_lds_dwordx4 v[204:205], off
	v_lshl_add_u64 v[204:205], v[210:211], 0, s[18:19]
	s_mov_b32 m0, s41
	s_nop 0
	global_load_lds_dwordx4 v[204:205], off
	s_waitcnt vmcnt(8)
	s_waitcnt lgkmcnt(0)
	s_setprio 1
	s_barrier
	v_mfma_f32_16x16x32_bf16 v[60:63], v[120:123], v[160:163], v[60:63]
	v_mfma_f32_16x16x32_bf16 v[56:59], v[136:139], v[160:163], v[56:59]
	v_mfma_f32_16x16x32_bf16 v[44:47], v[120:123], v[168:171], v[44:47]
	v_mfma_f32_16x16x32_bf16 v[40:43], v[136:139], v[168:171], v[40:43]
	v_mfma_f32_16x16x32_bf16 v[28:31], v[120:123], v[176:179], v[28:31]
	v_mfma_f32_16x16x32_bf16 v[24:27], v[136:139], v[176:179], v[24:27]
	v_mfma_f32_16x16x32_bf16 v[12:15], v[120:123], v[184:187], v[12:15]
	v_mfma_f32_16x16x32_bf16 v[8:11], v[136:139], v[184:187], v[8:11]
	v_mfma_f32_16x16x32_bf16 v[60:63], v[128:131], v[164:167], v[60:63]
	v_mfma_f32_16x16x32_bf16 v[56:59], v[140:143], v[164:167], v[56:59]
	v_mfma_f32_16x16x32_bf16 v[44:47], v[128:131], v[172:175], v[44:47]
	v_mfma_f32_16x16x32_bf16 v[40:43], v[140:143], v[172:175], v[40:43]
	v_mfma_f32_16x16x32_bf16 v[28:31], v[128:131], v[180:183], v[28:31]
	v_mfma_f32_16x16x32_bf16 v[24:27], v[140:143], v[180:183], v[24:27]
	v_mfma_f32_16x16x32_bf16 v[12:15], v[128:131], v[188:191], v[12:15]
	v_mfma_f32_16x16x32_bf16 v[8:11], v[140:143], v[188:191], v[8:11]
	v_mfma_f32_16x16x32_bf16 v[52:55], v[144:147], v[160:163], v[52:55]
	v_mfma_f32_16x16x32_bf16 v[48:51], v[152:155], v[160:163], v[48:51]
	v_mfma_f32_16x16x32_bf16 v[36:39], v[144:147], v[168:171], v[36:39]
	v_mfma_f32_16x16x32_bf16 v[32:35], v[152:155], v[168:171], v[32:35]
	v_mfma_f32_16x16x32_bf16 v[20:23], v[144:147], v[176:179], v[20:23]
	v_mfma_f32_16x16x32_bf16 v[16:19], v[152:155], v[176:179], v[16:19]
	v_mfma_f32_16x16x32_bf16 v[4:7], v[144:147], v[184:187], v[4:7]
	v_mfma_f32_16x16x32_bf16 v[0:3], v[152:155], v[184:187], v[0:3]
	v_mfma_f32_16x16x32_bf16 v[52:55], v[148:151], v[164:167], v[52:55]
	v_mfma_f32_16x16x32_bf16 v[48:51], v[156:159], v[164:167], v[48:51]
	v_mfma_f32_16x16x32_bf16 v[36:39], v[148:151], v[172:175], v[36:39]
	v_mfma_f32_16x16x32_bf16 v[32:35], v[156:159], v[172:175], v[32:35]
	v_mfma_f32_16x16x32_bf16 v[20:23], v[148:151], v[180:183], v[20:23]
	v_mfma_f32_16x16x32_bf16 v[16:19], v[156:159], v[180:183], v[16:19]
	v_mfma_f32_16x16x32_bf16 v[4:7], v[148:151], v[188:191], v[4:7]
	v_mfma_f32_16x16x32_bf16 v[0:3], v[156:159], v[188:191], v[0:3]
	s_barrier
	s_setprio 0
	s_add_i32 s53, s53, 2
	s_add_u32 s24, s24, 0x100
	s_addc_u32 s25, s25, 0
	s_add_u32 s51, s51, 0x100
	s_addc_u32 s52, s52, 0
	s_cmp_gt_u32 s53, 41

; #define PG8_STAGE(bufoff, gbase, voff) do { _Pragma("unroll") for (int _i = 0; _i < 2; ++_i) \
;         __builtin_amdgcn_global_load_lds((const unsigned*)((const char*)(gbase) + (voff)[_i]), (PG8_LAS unsigned*)(lds + (bufoff) + ldsw + _i * 8192), 16, 0, 0); } while (0)
; #define PG8_WAIT_V(n) asm volatile("s_waitcnt vmcnt(" #n ")" ::: "memory")
; #define PG8_BAR __builtin_amdgcn_s_barrier()
; template <class Epi, class Sched, bool ALIGN_EPI = false, bool SP2 = false>
; __device__ __forceinline__ void gemm_phase(PG8_LAS unsigned char* lds, const Gemm g, const Sched& S, const Epi& E) {
;     ...
;     for (int i = 0; i < 2; ++i) { int R, C; stage_rc(tid * 16 + i * 8192, R, C); const int Rb = Epi::PERM ? ((R & ~31) + perm32(R & 31)) : R;
;         voffA[i] = (unsigned)(R * K + C) * 2u; voffB[i] = (unsigned)(Rb * K + C) * 2u; }
;     const size_t kstep = (size_t)(BK * 2);
;     const size_t hstep = (size_t)HALF * K * 2;
;     const size_t tstep = 2 * hstep;
;     const unsigned ldsw = (unsigned)wid * 1024u;
;     const int aoff = lds_byte(wr * 64 + fr, fq * 8), boff = lds_byte(wc * 32 + fr, fq * 8);
;     ...
;         PG8_STAGE(PG8_SB(1, 0), cB + kstep, voffB); PG8_STAGE(PG8_SA(1, 0), cA + kstep, voffA); PG8_STAGE(PG8_SB(1, 1), cB + hstep + kstep, voffB);
;         PG8_WAIT_V(6); PG8_BAR;
.LBB0_1213:
	s_add_u32 s8, s90, 0x12500000
	s_addc_u32 s9, s91, 0
	s_lshl_b32 s10, s10, 5
	s_and_b32 s16, s10, 0x60
	s_mov_b64 s[10:11], 0x80
	s_add_i32 m0, s23, 0x18000
	v_lshl_add_u64 v[6:7], v[6:7], 0, s[10:11]
	s_lshl_b32 s13, s1, 13
	s_lshl_b32 s17, s16, 7
	s_waitcnt vmcnt(2)
	s_barrier
	global_load_lds_dwordx4 v[6:7], off
	v_lshl_add_u64 v[4:5], v[4:5], 0, s[10:11]
	s_add_i32 m0, s23, 0x1a000
	s_add_i32 s42, s23, 0x8000
	s_add_i32 s43, s23, 0xa000
	global_load_lds_dwordx4 v[4:5], off
	v_lshl_add_u64 v[0:1], v[0:1], 0, s[10:11]
	s_mov_b32 m0, s42
	s_add_u32 s14, s26, 0x40080
	global_load_lds_dwordx4 v[0:1], off
	v_lshl_add_u64 v[0:1], v[2:3], 0, s[10:11]
	s_mov_b32 m0, s43
	s_addc_u32 s15, s27, 0
	global_load_lds_dwordx4 v[0:1], off
	s_add_i32 m0, s23, 0x1c000
	s_nop 0
	global_load_lds_dwordx4 v132, s[14:15]
	v_lshl_add_u64 v[0:1], s[14:15], 0, v[128:129]
	s_add_i32 m0, s23, 0x1e000
	s_sext_i32_i16 s49, s0
	global_load_lds_dwordx4 v[0:1], off
	v_and_b32_e32 v0, 15, v254
	v_lshlrev_b32_e32 v1, 1, v12
	v_lshl_or_b32 v144, s1, 6, v0
	v_lshl_or_b32 v2, v0, 6, v1
	v_lshlrev_b32_e32 v0, 2, v0
	v_and_b32_e32 v3, 32, v0
	v_bitop3_b32 v2, v2, s13, v3 bitop3:0xde
	v_lshlrev_b32_e32 v3, 6, v254
	s_movk_i32 s0, 0x3c0
	s_cmpk_lt_u32 s12, 0x100
	v_and_or_b32 v1, v3, s0, v1
	s_cselect_b64 s[12:13], -1, 0
	s_lshl_b32 s0, s1, 8
	s_add_i32 s0, s0, 0
	s_add_i32 s0, s0, 0x20000
	v_and_b32_e32 v3, 32, v8
	v_add_u32_e32 v147, s0, v0
	v_lshlrev_b32_e32 v0, 8, v254
	v_bitop3_b32 v145, s17, v1, v3 bitop3:0xf6
	v_and_b32_e32 v0, 0x38000, v0
	v_lshlrev_b32_e32 v1, 11, v13
	v_or3_b32 v0, v10, v0, v1
	v_add_u32_e32 v136, v0, v11
	v_lshlrev_b32_e32 v0, 4, v9
	s_waitcnt vmcnt(6)
	v_and_b32_e32 v0, 0x78000, v0
	v_or3_b32 v0, v10, v0, v1
	s_add_i32 s44, 0, 0x10000
	s_add_i32 s45, 0, 0x14000
	v_or_b32_e32 v146, s16, v12
	v_mov_b32_e32 v137, v133
	v_add_u32_e32 v138, v0, v11
	v_mov_b32_e32 v139, v133
	v_mov_b64_e32 v[140:141], 0xb00
	v_mov_b64_e32 v[142:143], 0xaff
	v_add_u32_e32 v148, s44, v145
	v_add_u32_e32 v149, s45, v145
	v_add_u32_e32 v150, 0, v2
	s_movk_i32 s46, 0x1600
	s_barrier
	s_branch .LBB0_1216

; #define PG8_STAGE(bufoff, gbase, voff) do { _Pragma("unroll") for (int _i = 0; _i < 2; ++_i) \
;         __builtin_amdgcn_global_load_lds((const unsigned*)((const char*)(gbase) + (voff)[_i]), (PG8_LAS unsigned*)(lds + (bufoff) + ldsw + _i * 8192), 16, 0, 0); } while (0)
; #define PG8_LDA(dst, b, h) do { _Pragma("unroll") for (int m = 0; m < 4; ++m) _Pragma("unroll") for (int k = 0; k < 2; ++k) dst[m][k] = *(const PG8_LAS bf16x8*)(lds + PG8_SA(b, h) + aoff + m * 2048 + k * 1024); } while (0)
; #define PG8_LDB(dst, b, h) do { _Pragma("unroll") for (int n = 0; n < 2; ++n) _Pragma("unroll") for (int k = 0; k < 2; ++k) dst[n][k] = *(const PG8_LAS bf16x8*)(lds + PG8_SB(b, h) + boff + n * 2048 + k * 1024); } while (0)
; #define PG8_WAIT_V(n) asm volatile("s_waitcnt vmcnt(" #n ")" ::: "memory")
; #define PG8_WAIT_L(n) asm volatile("s_waitcnt lgkmcnt(" #n ")" ::: "memory")
; #define PG8_BAR __builtin_amdgcn_s_barrier()
; #define PG8_SCHED __builtin_amdgcn_sched_barrier(0)
; template <class Epi, class Sched, bool ALIGN_EPI = false, bool SP2 = false>
; __device__ __forceinline__ void gemm_phase(PG8_LAS unsigned char* lds, const Gemm g, const Sched& S, const Epi& E) {
;     ...
;         const bool has_next = S.next(ui + 1, nxt);
;         const char* nA = has_next ? (const char*)g.A + (size_t)nxt.pm * tstep : cA; const char* nB = has_next ? (const char*)g.Bt + (size_t)nxt.pn * tstep : cB;
;         for (int t = 0; t < nt; t += 2) {
;             const bool last = (t == nt - 2);
;             const char* a1 = cA + (size_t)(t + 1) * kstep;
;             const char* a2 = last ? nA : cA + (size_t)(t + 2) * kstep; const char* b2 = last ? nB : cB + (size_t)(t + 2) * kstep;
;             const char* a3 = a2 + kstep; const char* b3 = b2 + kstep;
;             if (last && has_next) S.a_ready(nxt, ui + 1);
;             if constexpr (SP2) {
;             PG8_LDB(B0, 0, 0); PG8_LDB(B1, 0, 1); PG8_SCHED; PG8_LDA(At, 0, 0); PG8_STAGE(PG8_SA(1, 1), a1 + hstep, voffA);
;             PG8_WAIT_V(8); PG8_WAIT_L(0); PG8_BAR; PG8_MMA(0, 0, At, B0); PG8_MMA(0, 1, At, B1); PG8_BAR; PG8_SCHED;
;             PG8_LDA(At, 0, 1); PG8_STAGE(PG8_SB(0, 0), b2, voffB); PG8_STAGE(PG8_SB(0, 1), b2 + hstep, voffB); PG8_STAGE(PG8_SA(0, 0), a2, voffA);
;             PG8_WAIT_V(8); PG8_WAIT_L(0); PG8_BAR; PG8_MMA(1, 0, At, B0); PG8_MMA(1, 1, At, B1); PG8_BAR; PG8_SCHED;
.LBB0_1218:
	s_ashr_i32 s17, s16, 31
	s_lshl_b64 s[18:19], s[16:17], 19
	s_add_u32 s18, s36, s18
	s_addc_u32 s19, s37, s19
	s_and_b64 s[20:21], s[0:1], exec
	s_cselect_b32 s17, s19, s25
	s_cselect_b32 s50, s18, s24
	s_ashr_i32 s15, s14, 31
	s_lshl_b64 s[20:21], s[14:15], 19
	s_add_u32 s20, s34, s20
	s_addc_u32 s21, s35, s21
	s_and_b64 s[28:29], s[0:1], exec
	s_cselect_b32 s15, s21, s27
	s_cselect_b32 s51, s20, s26
	s_add_u32 s24, s24, 0x40080
	s_addc_u32 s25, s25, 0
	s_add_u32 s52, s26, 0x100
	s_addc_u32 s53, s27, 0
	s_mov_b32 s54, -2
	s_add_u32 s26, s24, 0xfffc0080
	s_addc_u32 s27, s25, -1
	s_cmp_eq_u32 s54, 12
	s_cselect_b32 s29, s17, s27
	s_cselect_b32 s28, s50, s26
	s_cselect_b32 s27, s15, s53
	s_cselect_b32 s26, s51, s52
	s_add_i32 m0, s23, 0xc000
	s_nop 0
	global_load_lds_dwordx4 v136, s[24:25]
	s_add_i32 m0, s23, 0xe000
	s_nop 0
	global_load_lds_dwordx4 v138, s[24:25]
	s_waitcnt vmcnt(8)
	s_waitcnt lgkmcnt(0)
	s_setprio 1
	s_barrier
	v_mfma_f32_16x16x32_bf16 v[124:127], v[152:155], v[184:187], 0
	v_mfma_f32_16x16x32_bf16 v[120:123], v[160:163], v[184:187], 0
	v_mfma_f32_16x16x32_bf16 v[108:111], v[152:155], v[192:195], 0
	v_mfma_f32_16x16x32_bf16 v[104:107], v[160:163], v[192:195], 0
	v_mfma_f32_16x16x32_bf16 v[92:95], v[152:155], v[200:203], 0
	v_mfma_f32_16x16x32_bf16 v[88:91], v[160:163], v[200:203], 0
	v_mfma_f32_16x16x32_bf16 v[76:79], v[152:155], v[208:211], 0
	v_mfma_f32_16x16x32_bf16 v[72:75], v[160:163], v[208:211], 0
	v_mfma_f32_16x16x32_bf16 v[124:127], v[156:159], v[188:191], v[124:127]
	v_mfma_f32_16x16x32_bf16 v[120:123], v[164:167], v[188:191], v[120:123]
	v_mfma_f32_16x16x32_bf16 v[108:111], v[156:159], v[196:199], v[108:111]
	v_mfma_f32_16x16x32_bf16 v[104:107], v[164:167], v[196:199], v[104:107]
	v_mfma_f32_16x16x32_bf16 v[92:95], v[156:159], v[204:207], v[92:95]
	v_mfma_f32_16x16x32_bf16 v[88:91], v[164:167], v[204:207], v[88:91]
	v_mfma_f32_16x16x32_bf16 v[76:79], v[156:159], v[212:215], v[76:79]
	v_mfma_f32_16x16x32_bf16 v[72:75], v[164:167], v[212:215], v[72:75]
	v_mfma_f32_16x16x32_bf16 v[116:119], v[168:171], v[184:187], 0
	v_mfma_f32_16x16x32_bf16 v[112:115], v[176:179], v[184:187], 0
	v_mfma_f32_16x16x32_bf16 v[100:103], v[168:171], v[192:195], 0
	v_mfma_f32_16x16x32_bf16 v[96:99], v[176:179], v[192:195], 0
	v_mfma_f32_16x16x32_bf16 v[84:87], v[168:171], v[200:203], 0
	v_mfma_f32_16x16x32_bf16 v[80:83], v[176:179], v[200:203], 0
	v_mfma_f32_16x16x32_bf16 v[68:71], v[168:171], v[208:211], 0
	v_mfma_f32_16x16x32_bf16 v[64:67], v[176:179], v[208:211], 0
	v_mfma_f32_16x16x32_bf16 v[116:119], v[172:175], v[188:191], v[116:119]
	v_mfma_f32_16x16x32_bf16 v[112:115], v[180:183], v[188:191], v[112:115]
	v_mfma_f32_16x16x32_bf16 v[100:103], v[172:175], v[196:199], v[100:103]
	v_mfma_f32_16x16x32_bf16 v[96:99], v[180:183], v[196:199], v[96:99]
	v_mfma_f32_16x16x32_bf16 v[84:87], v[172:175], v[204:207], v[84:87]
	v_mfma_f32_16x16x32_bf16 v[80:83], v[180:183], v[204:207], v[80:83]
	v_mfma_f32_16x16x32_bf16 v[68:71], v[172:175], v[212:215], v[68:71]
	v_mfma_f32_16x16x32_bf16 v[64:67], v[180:183], v[212:215], v[64:67]
	s_barrier
	s_setprio 0
	s_add_i32 s55, s44, s33
	v_lshl_add_u64 v[216:217], s[26:27], 0, v[132:133]
	s_mov_b32 m0, s55
	ds_read_b128 v[184:187], v150 offset:16384
	ds_read_b128 v[188:191], v150 offset:17408
	ds_read_b128 v[192:195], v150 offset:18432
	ds_read_b128 v[196:199], v150 offset:19456
	ds_read_b128 v[200:203], v150 offset:20480
	ds_read_b128 v[204:207], v150 offset:21504
	ds_read_b128 v[208:211], v150 offset:22528
	ds_read_b128 v[212:215], v150 offset:23552
	global_load_lds_dwordx4 v[216:217], off
	s_add_i32 m0, s55, 0x2000
	s_add_u32 s56, s26, 0x40000
	v_lshl_add_u64 v[218:219], s[26:27], 0, v[128:129]
	s_addc_u32 s57, s27, 0
	s_add_i32 s55, s45, s33
	global_load_lds_dwordx4 v[218:219], off
	s_mov_b32 m0, s55
	v_lshl_add_u64 v[222:223], s[28:29], 0, v[130:131]
	global_load_lds_dwordx4 v132, s[56:57]
	s_add_i32 m0, s55, 0x2000
	s_nop 0
	global_load_lds_dwordx4 v128, s[56:57]
	v_lshl_add_u64 v[220:221], s[28:29], 0, v[134:135]
	s_mov_b32 m0, s23
	s_nop 0
	global_load_lds_dwordx4 v[220:221], off
	s_mov_b32 m0, s39
	s_nop 0
	global_load_lds_dwordx4 v[222:223], off
	s_waitcnt vmcnt(8)
	s_waitcnt lgkmcnt(0)
	s_setprio 1
	s_barrier
	v_mfma_f32_16x16x32_bf16 v[60:63], v[152:155], v[184:187], 0
	v_mfma_f32_16x16x32_bf16 v[56:59], v[160:163], v[184:187], 0
	v_mfma_f32_16x16x32_bf16 v[44:47], v[152:155], v[192:195], 0
	v_mfma_f32_16x16x32_bf16 v[40:43], v[160:163], v[192:195], 0
	v_mfma_f32_16x16x32_bf16 v[28:31], v[152:155], v[200:203], 0
	v_mfma_f32_16x16x32_bf16 v[24:27], v[160:163], v[200:203], 0
	v_mfma_f32_16x16x32_bf16 v[12:15], v[152:155], v[208:211], 0
	v_mfma_f32_16x16x32_bf16 v[8:11], v[160:163], v[208:211], 0
	v_mfma_f32_16x16x32_bf16 v[60:63], v[156:159], v[188:191], v[60:63]
	v_mfma_f32_16x16x32_bf16 v[56:59], v[164:167], v[188:191], v[56:59]
	v_mfma_f32_16x16x32_bf16 v[44:47], v[156:159], v[196:199], v[44:47]
	v_mfma_f32_16x16x32_bf16 v[40:43], v[164:167], v[196:199], v[40:43]
	v_mfma_f32_16x16x32_bf16 v[28:31], v[156:159], v[204:207], v[28:31]
	v_mfma_f32_16x16x32_bf16 v[24:27], v[164:167], v[204:207], v[24:27]
	v_mfma_f32_16x16x32_bf16 v[12:15], v[156:159], v[212:215], v[12:15]
	v_mfma_f32_16x16x32_bf16 v[8:11], v[164:167], v[212:215], v[8:11]
	v_mfma_f32_16x16x32_bf16 v[52:55], v[168:171], v[184:187], 0
	v_mfma_f32_16x16x32_bf16 v[48:51], v[176:179], v[184:187], 0
	v_mfma_f32_16x16x32_bf16 v[36:39], v[168:171], v[192:195], 0
	v_mfma_f32_16x16x32_bf16 v[32:35], v[176:179], v[192:195], 0
	v_mfma_f32_16x16x32_bf16 v[20:23], v[168:171], v[200:203], 0
	v_mfma_f32_16x16x32_bf16 v[16:19], v[176:179], v[200:203], 0
	v_mfma_f32_16x16x32_bf16 v[4:7], v[168:171], v[208:211], 0
	v_mfma_f32_16x16x32_bf16 v[0:3], v[176:179], v[208:211], 0
	v_mfma_f32_16x16x32_bf16 v[52:55], v[172:175], v[188:191], v[52:55]
	v_mfma_f32_16x16x32_bf16 v[48:51], v[180:183], v[188:191], v[48:51]
	v_mfma_f32_16x16x32_bf16 v[36:39], v[172:175], v[196:199], v[36:39]
	v_mfma_f32_16x16x32_bf16 v[32:35], v[180:183], v[196:199], v[32:35]
	v_mfma_f32_16x16x32_bf16 v[20:23], v[172:175], v[204:207], v[20:23]
	v_mfma_f32_16x16x32_bf16 v[16:19], v[180:183], v[204:207], v[16:19]
	v_mfma_f32_16x16x32_bf16 v[4:7], v[172:175], v[212:215], v[4:7]
	v_mfma_f32_16x16x32_bf16 v[0:3], v[180:183], v[212:215], v[0:3]
	s_barrier
; #define PG8_STAGE(bufoff, gbase, voff) do { _Pragma("unroll") for (int _i = 0; _i < 2; ++_i) \
;         __builtin_amdgcn_global_load_lds((const unsigned*)((const char*)(gbase) + (voff)[_i]), (PG8_LAS unsigned*)(lds + (bufoff) + ldsw + _i * 8192), 16, 0, 0); } while (0)
; #define PG8_LDA(dst, b, h) do { _Pragma("unroll") for (int m = 0; m < 4; ++m) _Pragma("unroll") for (int k = 0; k < 2; ++k) dst[m][k] = *(const PG8_LAS bf16x8*)(lds + PG8_SA(b, h) + aoff + m * 2048 + k * 1024); } while (0)
; #define PG8_LDB(dst, b, h) do { _Pragma("unroll") for (int n = 0; n < 2; ++n) _Pragma("unroll") for (int k = 0; k < 2; ++k) dst[n][k] = *(const PG8_LAS bf16x8*)(lds + PG8_SB(b, h) + boff + n * 2048 + k * 1024); } while (0)
; #define PG8_MMA(ai, bj, At, Bt) do { __builtin_amdgcn_s_setprio(1); _Pragma("unroll") for (int m = 0; m < 4; ++m) _Pragma("unroll") for (int n = 0; n < 2; ++n) _Pragma("unroll") for (int k = 0; k < 2; ++k) \
;         acc[ai][bj][m][n] = __builtin_amdgcn_mfma_f32_16x16x32_bf16(Bt[n][k], At[m][k], acc[ai][bj][m][n], 0, 0, 0); __builtin_amdgcn_s_setprio(0); } while (0)
; #define PG8_WAIT_V(n) asm volatile("s_waitcnt vmcnt(" #n ")" ::: "memory")
; #define PG8_WAIT_L(n) asm volatile("s_waitcnt lgkmcnt(" #n ")" ::: "memory")
; #define PG8_BAR __builtin_amdgcn_s_barrier()
; #define PG8_SCHED __builtin_amdgcn_sched_barrier(0)
; template <class Epi, class Sched, bool ALIGN_EPI = false, bool SP2 = false>
; __device__ __forceinline__ void gemm_phase(PG8_LAS unsigned char* lds, const Gemm g, const Sched& S, const Epi& E) {
;     ...
;             PG8_LDB(B0, 1, 0); PG8_LDB(B1, 1, 1); PG8_SCHED; PG8_LDA(At, 1, 0); PG8_STAGE(PG8_SA(0, 1), a2 + hstep, voffA);
;             PG8_WAIT_V(8); PG8_WAIT_L(0); PG8_BAR; PG8_MMA(0, 0, At, B0); PG8_MMA(0, 1, At, B1); PG8_BAR; PG8_SCHED;
;             PG8_LDA(At, 1, 1); PG8_STAGE(PG8_SB(1, 0), b3, voffB); PG8_STAGE(PG8_SB(1, 1), b3 + hstep, voffB); PG8_STAGE(PG8_SA(1, 0), a3, voffA);
;             PG8_WAIT_V(8); PG8_WAIT_L(0); PG8_BAR; PG8_MMA(1, 0, At, B0); PG8_MMA(1, 1, At, B1); PG8_BAR; PG8_SCHED;
	s_setprio 0
	s_add_i32 s55, 0, 0x18000
	v_add_u32_e32 v151, s55, v145
	s_add_i32 s56, 0, 0x1c000
	ds_read_b128 v[152:155], v151
	ds_read_b128 v[156:159], v151 offset:1024
	ds_read_b128 v[160:163], v151 offset:2048
	ds_read_b128 v[164:167], v151 offset:3072
	v_add_u32_e32 v151, s56, v145
	ds_read_b128 v[168:171], v151
	ds_read_b128 v[172:175], v151 offset:1024
	ds_read_b128 v[176:179], v151 offset:2048
	ds_read_b128 v[180:183], v151 offset:3072
	s_add_u32 s28, s28, 0x40000
	s_addc_u32 s29, s29, 0
	s_mov_b32 m0, s40
	ds_read_b128 v[184:187], v150 offset:32768
	ds_read_b128 v[188:191], v150 offset:33792
	ds_read_b128 v[192:195], v150 offset:34816
	ds_read_b128 v[196:199], v150 offset:35840
	ds_read_b128 v[200:203], v150 offset:36864
	ds_read_b128 v[204:207], v150 offset:37888
	ds_read_b128 v[208:211], v150 offset:38912
	ds_read_b128 v[212:215], v150 offset:39936
	global_load_lds_dwordx4 v134, s[28:29]
	s_mov_b32 m0, s41
	s_nop 0
	global_load_lds_dwordx4 v130, s[28:29]
	s_waitcnt vmcnt(8)
	s_waitcnt lgkmcnt(0)
	s_setprio 1
	s_barrier
	v_mfma_f32_16x16x32_bf16 v[124:127], v[152:155], v[184:187], v[124:127]
	v_mfma_f32_16x16x32_bf16 v[120:123], v[160:163], v[184:187], v[120:123]
	v_mfma_f32_16x16x32_bf16 v[108:111], v[152:155], v[192:195], v[108:111]
	v_mfma_f32_16x16x32_bf16 v[104:107], v[160:163], v[192:195], v[104:107]
	v_mfma_f32_16x16x32_bf16 v[92:95], v[152:155], v[200:203], v[92:95]
	v_mfma_f32_16x16x32_bf16 v[88:91], v[160:163], v[200:203], v[88:91]
	v_mfma_f32_16x16x32_bf16 v[76:79], v[152:155], v[208:211], v[76:79]
	v_mfma_f32_16x16x32_bf16 v[72:75], v[160:163], v[208:211], v[72:75]
	v_mfma_f32_16x16x32_bf16 v[124:127], v[156:159], v[188:191], v[124:127]
	v_mfma_f32_16x16x32_bf16 v[120:123], v[164:167], v[188:191], v[120:123]
	v_mfma_f32_16x16x32_bf16 v[108:111], v[156:159], v[196:199], v[108:111]
	v_mfma_f32_16x16x32_bf16 v[104:107], v[164:167], v[196:199], v[104:107]
	v_mfma_f32_16x16x32_bf16 v[92:95], v[156:159], v[204:207], v[92:95]
	v_mfma_f32_16x16x32_bf16 v[88:91], v[164:167], v[204:207], v[88:91]
	v_mfma_f32_16x16x32_bf16 v[76:79], v[156:159], v[212:215], v[76:79]
	v_mfma_f32_16x16x32_bf16 v[72:75], v[164:167], v[212:215], v[72:75]
	v_mfma_f32_16x16x32_bf16 v[116:119], v[168:171], v[184:187], v[116:119]
	v_mfma_f32_16x16x32_bf16 v[112:115], v[176:179], v[184:187], v[112:115]
	v_mfma_f32_16x16x32_bf16 v[100:103], v[168:171], v[192:195], v[100:103]
	v_mfma_f32_16x16x32_bf16 v[96:99], v[176:179], v[192:195], v[96:99]
	v_mfma_f32_16x16x32_bf16 v[84:87], v[168:171], v[200:203], v[84:87]
	v_mfma_f32_16x16x32_bf16 v[80:83], v[176:179], v[200:203], v[80:83]
	v_mfma_f32_16x16x32_bf16 v[68:71], v[168:171], v[208:211], v[68:71]
	v_mfma_f32_16x16x32_bf16 v[64:67], v[176:179], v[208:211], v[64:67]
	v_mfma_f32_16x16x32_bf16 v[116:119], v[172:175], v[188:191], v[116:119]
	v_mfma_f32_16x16x32_bf16 v[112:115], v[180:183], v[188:191], v[112:115]
	v_mfma_f32_16x16x32_bf16 v[100:103], v[172:175], v[196:199], v[100:103]
	v_mfma_f32_16x16x32_bf16 v[96:99], v[180:183], v[196:199], v[96:99]
	v_mfma_f32_16x16x32_bf16 v[84:87], v[172:175], v[204:207], v[84:87]
	v_mfma_f32_16x16x32_bf16 v[80:83], v[180:183], v[204:207], v[80:83]
	v_mfma_f32_16x16x32_bf16 v[68:71], v[172:175], v[212:215], v[68:71]
	v_mfma_f32_16x16x32_bf16 v[64:67], v[180:183], v[212:215], v[64:67]
	s_barrier
	s_setprio 0
	s_add_i32 s28, s55, s33
	v_lshl_add_u64 v[216:217], v[216:217], 0, s[10:11]
	s_mov_b32 m0, s28
	ds_read_b128 v[184:187], v150 offset:49152
	ds_read_b128 v[188:191], v150 offset:50176
	ds_read_b128 v[192:195], v150 offset:51200
	ds_read_b128 v[196:199], v150 offset:52224
	ds_read_b128 v[200:203], v150 offset:53248
	ds_read_b128 v[204:207], v150 offset:54272
	ds_read_b128 v[208:211], v150 offset:55296
	ds_read_b128 v[212:215], v150 offset:56320
	global_load_lds_dwordx4 v[216:217], off
	s_add_i32 m0, s28, 0x2000
	s_add_u32 s26, s26, 0x40080
	v_lshl_add_u64 v[216:217], v[218:219], 0, s[10:11]
	s_addc_u32 s27, s27, 0
	s_add_i32 s28, s56, s33
	global_load_lds_dwordx4 v[216:217], off
	s_mov_b32 m0, s28
	s_nop 0
	global_load_lds_dwordx4 v132, s[26:27]
	s_add_i32 m0, s28, 0x2000
	s_nop 0
	global_load_lds_dwordx4 v128, s[26:27]
	v_lshl_add_u64 v[216:217], v[220:221], 0, s[10:11]
	s_mov_b32 m0, s42
	s_nop 0
	global_load_lds_dwordx4 v[216:217], off
	v_lshl_add_u64 v[216:217], v[222:223], 0, s[10:11]
	s_mov_b32 m0, s43
	s_nop 0
	global_load_lds_dwordx4 v[216:217], off
	s_waitcnt vmcnt(8)
	s_waitcnt lgkmcnt(0)
	s_setprio 1
	s_barrier
	v_mfma_f32_16x16x32_bf16 v[60:63], v[152:155], v[184:187], v[60:63]
	v_mfma_f32_16x16x32_bf16 v[56:59], v[160:163], v[184:187], v[56:59]
	v_mfma_f32_16x16x32_bf16 v[44:47], v[152:155], v[192:195], v[44:47]
	v_mfma_f32_16x16x32_bf16 v[40:43], v[160:163], v[192:195], v[40:43]
	v_mfma_f32_16x16x32_bf16 v[28:31], v[152:155], v[200:203], v[28:31]
	v_mfma_f32_16x16x32_bf16 v[24:27], v[160:163], v[200:203], v[24:27]
	v_mfma_f32_16x16x32_bf16 v[12:15], v[152:155], v[208:211], v[12:15]
	v_mfma_f32_16x16x32_bf16 v[8:11], v[160:163], v[208:211], v[8:11]
	v_mfma_f32_16x16x32_bf16 v[60:63], v[156:159], v[188:191], v[60:63]
	v_mfma_f32_16x16x32_bf16 v[56:59], v[164:167], v[188:191], v[56:59]
	v_mfma_f32_16x16x32_bf16 v[44:47], v[156:159], v[196:199], v[44:47]
	v_mfma_f32_16x16x32_bf16 v[40:43], v[164:167], v[196:199], v[40:43]
	v_mfma_f32_16x16x32_bf16 v[28:31], v[156:159], v[204:207], v[28:31]
	v_mfma_f32_16x16x32_bf16 v[24:27], v[164:167], v[204:207], v[24:27]
	v_mfma_f32_16x16x32_bf16 v[12:15], v[156:159], v[212:215], v[12:15]
	v_mfma_f32_16x16x32_bf16 v[8:11], v[164:167], v[212:215], v[8:11]
	v_mfma_f32_16x16x32_bf16 v[52:55], v[168:171], v[184:187], v[52:55]
	v_mfma_f32_16x16x32_bf16 v[48:51], v[176:179], v[184:187], v[48:51]
	v_mfma_f32_16x16x32_bf16 v[36:39], v[168:171], v[192:195], v[36:39]
	v_mfma_f32_16x16x32_bf16 v[32:35], v[176:179], v[192:195], v[32:35]
	v_mfma_f32_16x16x32_bf16 v[20:23], v[168:171], v[200:203], v[20:23]
	v_mfma_f32_16x16x32_bf16 v[16:19], v[176:179], v[200:203], v[16:19]
	v_mfma_f32_16x16x32_bf16 v[4:7], v[168:171], v[208:211], v[4:7]
	v_mfma_f32_16x16x32_bf16 v[0:3], v[176:179], v[208:211], v[0:3]
	v_mfma_f32_16x16x32_bf16 v[52:55], v[172:175], v[188:191], v[52:55]
	v_mfma_f32_16x16x32_bf16 v[48:51], v[180:183], v[188:191], v[48:51]
	v_mfma_f32_16x16x32_bf16 v[36:39], v[172:175], v[196:199], v[36:39]
	v_mfma_f32_16x16x32_bf16 v[32:35], v[180:183], v[196:199], v[32:35]
	v_mfma_f32_16x16x32_bf16 v[20:23], v[172:175], v[204:207], v[20:23]
	v_mfma_f32_16x16x32_bf16 v[16:19], v[180:183], v[204:207], v[16:19]
	v_mfma_f32_16x16x32_bf16 v[4:7], v[172:175], v[212:215], v[4:7]
	v_mfma_f32_16x16x32_bf16 v[0:3], v[180:183], v[212:215], v[0:3]
	s_barrier
	s_setprio 0
	s_add_i32 s54, s54, 2
	s_add_u32 s24, s24, 0x100
	s_addc_u32 s25, s25, 0
	s_add_u32 s52, s52, 0x100
	s_addc_u32 s53, s53, 0
	s_cmp_gt_u32 s54, 13
; #define PG8_STAGE(bufoff, gbase, voff) do { _Pragma("unroll") for (int _i = 0; _i < 2; ++_i) \
;         __builtin_amdgcn_global_load_lds((const unsigned*)((const char*)(gbase) + (voff)[_i]), (PG8_LAS unsigned*)(lds + (bufoff) + ldsw + _i * 8192), 16, 0, 0); } while (0)
; #define PG8_LDA(dst, b, h) do { _Pragma("unroll") for (int m = 0; m < 4; ++m) _Pragma("unroll") for (int k = 0; k < 2; ++k) dst[m][k] = *(const PG8_LAS bf16x8*)(lds + PG8_SA(b, h) + aoff + m * 2048 + k * 1024); } while (0)
; #define PG8_LDB(dst, b, h) do { _Pragma("unroll") for (int n = 0; n < 2; ++n) _Pragma("unroll") for (int k = 0; k < 2; ++k) dst[n][k] = *(const PG8_LAS bf16x8*)(lds + PG8_SB(b, h) + boff + n * 2048 + k * 1024); } while (0)
; #define PG8_MMA(ai, bj, At, Bt) do { __builtin_amdgcn_s_setprio(1); _Pragma("unroll") for (int m = 0; m < 4; ++m) _Pragma("unroll") for (int n = 0; n < 2; ++n) _Pragma("unroll") for (int k = 0; k < 2; ++k) \
;         acc[ai][bj][m][n] = __builtin_amdgcn_mfma_f32_16x16x32_bf16(Bt[n][k], At[m][k], acc[ai][bj][m][n], 0, 0, 0); __builtin_amdgcn_s_setprio(0); } while (0)
; #define PG8_WAIT_V(n) asm volatile("s_waitcnt vmcnt(" #n ")" ::: "memory")
; #define PG8_WAIT_L(n) asm volatile("s_waitcnt lgkmcnt(" #n ")" ::: "memory")
; #define PG8_BAR __builtin_amdgcn_s_barrier()
; #define PG8_SCHED __builtin_amdgcn_sched_barrier(0)
; template <class Epi, class Sched, bool ALIGN_EPI = false, bool SP2 = false>
; __device__ __forceinline__ void gemm_phase(PG8_LAS unsigned char* lds, const Gemm g, const Sched& S, const Epi& E) {
;     ...
;             PG8_LDB(B0, 0, 0); PG8_LDB(B1, 0, 1); PG8_SCHED; PG8_LDA(At, 0, 0); PG8_STAGE(PG8_SA(1, 1), a1 + hstep, voffA);
;             PG8_WAIT_V(8); PG8_WAIT_L(0); PG8_BAR; PG8_MMA(0, 0, At, B0); PG8_MMA(0, 1, At, B1); PG8_BAR; PG8_SCHED;
;             PG8_LDA(At, 0, 1); PG8_STAGE(PG8_SB(0, 0), b2, voffB); PG8_STAGE(PG8_SB(0, 1), b2 + hstep, voffB); PG8_STAGE(PG8_SA(0, 0), a2, voffA);
;             PG8_WAIT_V(8); PG8_WAIT_L(0); PG8_BAR; PG8_MMA(1, 0, At, B0); PG8_MMA(1, 1, At, B1); PG8_BAR; PG8_SCHED;
.LBB0_1219:
	ds_read_b128 v[152:155], v148
	ds_read_b128 v[156:159], v148 offset:1024
	ds_read_b128 v[160:163], v148 offset:2048
	ds_read_b128 v[164:167], v148 offset:3072
	ds_read_b128 v[168:171], v149
	ds_read_b128 v[172:175], v149 offset:1024
	ds_read_b128 v[176:179], v149 offset:2048
	ds_read_b128 v[180:183], v149 offset:3072
	s_add_u32 s26, s24, 0xfffc0080
	s_addc_u32 s27, s25, -1
	s_cmp_eq_u32 s54, 12
	s_cselect_b32 s29, s17, s27
	s_cselect_b32 s28, s50, s26
	s_cselect_b32 s27, s15, s53
	s_cselect_b32 s26, s51, s52
	s_add_i32 m0, s23, 0xc000
	ds_read_b128 v[184:187], v150
	ds_read_b128 v[188:191], v150 offset:1024
	ds_read_b128 v[192:195], v150 offset:2048
	ds_read_b128 v[196:199], v150 offset:3072
	ds_read_b128 v[200:203], v150 offset:4096
	ds_read_b128 v[204:207], v150 offset:5120
	ds_read_b128 v[208:211], v150 offset:6144
	ds_read_b128 v[212:215], v150 offset:7168
	global_load_lds_dwordx4 v136, s[24:25]
	s_add_i32 m0, s23, 0xe000
	s_nop 0
	global_load_lds_dwordx4 v138, s[24:25]
	s_waitcnt vmcnt(8)
	s_waitcnt lgkmcnt(0)
	s_setprio 1
	s_barrier
	v_mfma_f32_16x16x32_bf16 v[124:127], v[152:155], v[184:187], v[124:127]
	v_mfma_f32_16x16x32_bf16 v[120:123], v[160:163], v[184:187], v[120:123]
	v_mfma_f32_16x16x32_bf16 v[108:111], v[152:155], v[192:195], v[108:111]
	v_mfma_f32_16x16x32_bf16 v[104:107], v[160:163], v[192:195], v[104:107]
	v_mfma_f32_16x16x32_bf16 v[92:95], v[152:155], v[200:203], v[92:95]
	v_mfma_f32_16x16x32_bf16 v[88:91], v[160:163], v[200:203], v[88:91]
	v_mfma_f32_16x16x32_bf16 v[76:79], v[152:155], v[208:211], v[76:79]
	v_mfma_f32_16x16x32_bf16 v[72:75], v[160:163], v[208:211], v[72:75]
	v_mfma_f32_16x16x32_bf16 v[124:127], v[156:159], v[188:191], v[124:127]
	v_mfma_f32_16x16x32_bf16 v[120:123], v[164:167], v[188:191], v[120:123]
	v_mfma_f32_16x16x32_bf16 v[108:111], v[156:159], v[196:199], v[108:111]
	v_mfma_f32_16x16x32_bf16 v[104:107], v[164:167], v[196:199], v[104:107]
	v_mfma_f32_16x16x32_bf16 v[92:95], v[156:159], v[204:207], v[92:95]
	v_mfma_f32_16x16x32_bf16 v[88:91], v[164:167], v[204:207], v[88:91]
	v_mfma_f32_16x16x32_bf16 v[76:79], v[156:159], v[212:215], v[76:79]
	v_mfma_f32_16x16x32_bf16 v[72:75], v[164:167], v[212:215], v[72:75]
	v_mfma_f32_16x16x32_bf16 v[116:119], v[168:171], v[184:187], v[116:119]
	v_mfma_f32_16x16x32_bf16 v[112:115], v[176:179], v[184:187], v[112:115]
	v_mfma_f32_16x16x32_bf16 v[100:103], v[168:171], v[192:195], v[100:103]
	v_mfma_f32_16x16x32_bf16 v[96:99], v[176:179], v[192:195], v[96:99]
	v_mfma_f32_16x16x32_bf16 v[84:87], v[168:171], v[200:203], v[84:87]
	v_mfma_f32_16x16x32_bf16 v[80:83], v[176:179], v[200:203], v[80:83]
	v_mfma_f32_16x16x32_bf16 v[68:71], v[168:171], v[208:211], v[68:71]
	v_mfma_f32_16x16x32_bf16 v[64:67], v[176:179], v[208:211], v[64:67]
	v_mfma_f32_16x16x32_bf16 v[116:119], v[172:175], v[188:191], v[116:119]
	v_mfma_f32_16x16x32_bf16 v[112:115], v[180:183], v[188:191], v[112:115]
	v_mfma_f32_16x16x32_bf16 v[100:103], v[172:175], v[196:199], v[100:103]
	v_mfma_f32_16x16x32_bf16 v[96:99], v[180:183], v[196:199], v[96:99]
	v_mfma_f32_16x16x32_bf16 v[84:87], v[172:175], v[204:207], v[84:87]
	v_mfma_f32_16x16x32_bf16 v[80:83], v[180:183], v[204:207], v[80:83]
	v_mfma_f32_16x16x32_bf16 v[68:71], v[172:175], v[212:215], v[68:71]
	v_mfma_f32_16x16x32_bf16 v[64:67], v[180:183], v[212:215], v[64:67]
	s_barrier
	s_setprio 0
	s_add_i32 s55, s44, s33
	v_lshl_add_u64 v[216:217], s[26:27], 0, v[132:133]
	s_mov_b32 m0, s55
	ds_read_b128 v[184:187], v150 offset:16384
	ds_read_b128 v[188:191], v150 offset:17408
	ds_read_b128 v[192:195], v150 offset:18432
	ds_read_b128 v[196:199], v150 offset:19456
	ds_read_b128 v[200:203], v150 offset:20480
	ds_read_b128 v[204:207], v150 offset:21504
	ds_read_b128 v[208:211], v150 offset:22528
	ds_read_b128 v[212:215], v150 offset:23552
	global_load_lds_dwordx4 v[216:217], off
	s_add_i32 m0, s55, 0x2000
	s_add_u32 s56, s26, 0x40000
	v_lshl_add_u64 v[218:219], s[26:27], 0, v[128:129]
	s_addc_u32 s57, s27, 0
	s_add_i32 s55, s45, s33
	global_load_lds_dwordx4 v[218:219], off
	s_mov_b32 m0, s55
	v_lshl_add_u64 v[222:223], s[28:29], 0, v[130:131]
	global_load_lds_dwordx4 v132, s[56:57]
	s_add_i32 m0, s55, 0x2000
	s_nop 0
	global_load_lds_dwordx4 v128, s[56:57]
	v_lshl_add_u64 v[220:221], s[28:29], 0, v[134:135]
	s_mov_b32 m0, s23
	s_nop 0
	global_load_lds_dwordx4 v[220:221], off
	s_mov_b32 m0, s39
	s_nop 0
	global_load_lds_dwordx4 v[222:223], off
	s_waitcnt vmcnt(8)
	s_waitcnt lgkmcnt(0)
	s_setprio 1
	s_barrier
	v_mfma_f32_16x16x32_bf16 v[60:63], v[152:155], v[184:187], v[60:63]
	v_mfma_f32_16x16x32_bf16 v[56:59], v[160:163], v[184:187], v[56:59]
	v_mfma_f32_16x16x32_bf16 v[44:47], v[152:155], v[192:195], v[44:47]
	v_mfma_f32_16x16x32_bf16 v[40:43], v[160:163], v[192:195], v[40:43]
	v_mfma_f32_16x16x32_bf16 v[28:31], v[152:155], v[200:203], v[28:31]
	v_mfma_f32_16x16x32_bf16 v[24:27], v[160:163], v[200:203], v[24:27]
	v_mfma_f32_16x16x32_bf16 v[12:15], v[152:155], v[208:211], v[12:15]
	v_mfma_f32_16x16x32_bf16 v[8:11], v[160:163], v[208:211], v[8:11]
	v_mfma_f32_16x16x32_bf16 v[60:63], v[156:159], v[188:191], v[60:63]
	v_mfma_f32_16x16x32_bf16 v[56:59], v[164:167], v[188:191], v[56:59]
	v_mfma_f32_16x16x32_bf16 v[44:47], v[156:159], v[196:199], v[44:47]
	v_mfma_f32_16x16x32_bf16 v[40:43], v[164:167], v[196:199], v[40:43]
	v_mfma_f32_16x16x32_bf16 v[28:31], v[156:159], v[204:207], v[28:31]
	v_mfma_f32_16x16x32_bf16 v[24:27], v[164:167], v[204:207], v[24:27]
	v_mfma_f32_16x16x32_bf16 v[12:15], v[156:159], v[212:215], v[12:15]
	v_mfma_f32_16x16x32_bf16 v[8:11], v[164:167], v[212:215], v[8:11]
	v_mfma_f32_16x16x32_bf16 v[52:55], v[168:171], v[184:187], v[52:55]
	v_mfma_f32_16x16x32_bf16 v[48:51], v[176:179], v[184:187], v[48:51]
	v_mfma_f32_16x16x32_bf16 v[36:39], v[168:171], v[192:195], v[36:39]
	v_mfma_f32_16x16x32_bf16 v[32:35], v[176:179], v[192:195], v[32:35]
	v_mfma_f32_16x16x32_bf16 v[20:23], v[168:171], v[200:203], v[20:23]
	v_mfma_f32_16x16x32_bf16 v[16:19], v[176:179], v[200:203], v[16:19]
	v_mfma_f32_16x16x32_bf16 v[4:7], v[168:171], v[208:211], v[4:7]
	v_mfma_f32_16x16x32_bf16 v[0:3], v[176:179], v[208:211], v[0:3]
	v_mfma_f32_16x16x32_bf16 v[52:55], v[172:175], v[188:191], v[52:55]
	v_mfma_f32_16x16x32_bf16 v[48:51], v[180:183], v[188:191], v[48:51]
	v_mfma_f32_16x16x32_bf16 v[36:39], v[172:175], v[196:199], v[36:39]
	v_mfma_f32_16x16x32_bf16 v[32:35], v[180:183], v[196:199], v[32:35]
	v_mfma_f32_16x16x32_bf16 v[20:23], v[172:175], v[204:207], v[20:23]
	v_mfma_f32_16x16x32_bf16 v[16:19], v[180:183], v[204:207], v[16:19]
	v_mfma_f32_16x16x32_bf16 v[4:7], v[172:175], v[212:215], v[4:7]
	v_mfma_f32_16x16x32_bf16 v[0:3], v[180:183], v[212:215], v[0:3]
	s_barrier
; #define PG8_STAGE(bufoff, gbase, voff) do { _Pragma("unroll") for (int _i = 0; _i < 2; ++_i) \
;         __builtin_amdgcn_global_load_lds((const unsigned*)((const char*)(gbase) + (voff)[_i]), (PG8_LAS unsigned*)(lds + (bufoff) + ldsw + _i * 8192), 16, 0, 0); } while (0)
; #define PG8_LDA(dst, b, h) do { _Pragma("unroll") for (int m = 0; m < 4; ++m) _Pragma("unroll") for (int k = 0; k < 2; ++k) dst[m][k] = *(const PG8_LAS bf16x8*)(lds + PG8_SA(b, h) + aoff + m * 2048 + k * 1024); } while (0)
; #define PG8_LDB(dst, b, h) do { _Pragma("unroll") for (int n = 0; n < 2; ++n) _Pragma("unroll") for (int k = 0; k < 2; ++k) dst[n][k] = *(const PG8_LAS bf16x8*)(lds + PG8_SB(b, h) + boff + n * 2048 + k * 1024); } while (0)
; #define PG8_MMA(ai, bj, At, Bt) do { __builtin_amdgcn_s_setprio(1); _Pragma("unroll") for (int m = 0; m < 4; ++m) _Pragma("unroll") for (int n = 0; n < 2; ++n) _Pragma("unroll") for (int k = 0; k < 2; ++k) \
;         acc[ai][bj][m][n] = __builtin_amdgcn_mfma_f32_16x16x32_bf16(Bt[n][k], At[m][k], acc[ai][bj][m][n], 0, 0, 0); __builtin_amdgcn_s_setprio(0); } while (0)
; #define PG8_WAIT_V(n) asm volatile("s_waitcnt vmcnt(" #n ")" ::: "memory")
; #define PG8_WAIT_L(n) asm volatile("s_waitcnt lgkmcnt(" #n ")" ::: "memory")
; #define PG8_BAR __builtin_amdgcn_s_barrier()
; #define PG8_SCHED __builtin_amdgcn_sched_barrier(0)
; template <class Epi, class Sched, bool ALIGN_EPI = false, bool SP2 = false>
; __device__ __forceinline__ void gemm_phase(PG8_LAS unsigned char* lds, const Gemm g, const Sched& S, const Epi& E) {
;     ...
;             PG8_LDB(B0, 1, 0); PG8_LDB(B1, 1, 1); PG8_SCHED; PG8_LDA(At, 1, 0); PG8_STAGE(PG8_SA(0, 1), a2 + hstep, voffA);
;             PG8_WAIT_V(8); PG8_WAIT_L(0); PG8_BAR; PG8_MMA(0, 0, At, B0); PG8_MMA(0, 1, At, B1); PG8_BAR; PG8_SCHED;
;             PG8_LDA(At, 1, 1); PG8_STAGE(PG8_SB(1, 0), b3, voffB); PG8_STAGE(PG8_SB(1, 1), b3 + hstep, voffB); PG8_STAGE(PG8_SA(1, 0), a3, voffA);
;             PG8_WAIT_V(8); PG8_WAIT_L(0); PG8_BAR; PG8_MMA(1, 0, At, B0); PG8_MMA(1, 1, At, B1); PG8_BAR; PG8_SCHED;
	s_setprio 0
	s_add_i32 s55, 0, 0x18000
	v_add_u32_e32 v151, s55, v145
	s_add_i32 s56, 0, 0x1c000
	ds_read_b128 v[152:155], v151
	ds_read_b128 v[156:159], v151 offset:1024
	ds_read_b128 v[160:163], v151 offset:2048
	ds_read_b128 v[164:167], v151 offset:3072
	v_add_u32_e32 v151, s56, v145
	ds_read_b128 v[168:171], v151
	ds_read_b128 v[172:175], v151 offset:1024
	ds_read_b128 v[176:179], v151 offset:2048
	ds_read_b128 v[180:183], v151 offset:3072
	s_add_u32 s28, s28, 0x40000
	s_addc_u32 s29, s29, 0
	s_mov_b32 m0, s40
	ds_read_b128 v[184:187], v150 offset:32768
	ds_read_b128 v[188:191], v150 offset:33792
	ds_read_b128 v[192:195], v150 offset:34816
	ds_read_b128 v[196:199], v150 offset:35840
	ds_read_b128 v[200:203], v150 offset:36864
	ds_read_b128 v[204:207], v150 offset:37888
	ds_read_b128 v[208:211], v150 offset:38912
	ds_read_b128 v[212:215], v150 offset:39936
	global_load_lds_dwordx4 v134, s[28:29]
	s_mov_b32 m0, s41
	s_nop 0
	global_load_lds_dwordx4 v130, s[28:29]
	s_waitcnt vmcnt(8)
	s_waitcnt lgkmcnt(0)
	s_setprio 1
	s_barrier
	v_mfma_f32_16x16x32_bf16 v[124:127], v[152:155], v[184:187], v[124:127]
	v_mfma_f32_16x16x32_bf16 v[120:123], v[160:163], v[184:187], v[120:123]
	v_mfma_f32_16x16x32_bf16 v[108:111], v[152:155], v[192:195], v[108:111]
	v_mfma_f32_16x16x32_bf16 v[104:107], v[160:163], v[192:195], v[104:107]
	v_mfma_f32_16x16x32_bf16 v[92:95], v[152:155], v[200:203], v[92:95]
	v_mfma_f32_16x16x32_bf16 v[88:91], v[160:163], v[200:203], v[88:91]
	v_mfma_f32_16x16x32_bf16 v[76:79], v[152:155], v[208:211], v[76:79]
	v_mfma_f32_16x16x32_bf16 v[72:75], v[160:163], v[208:211], v[72:75]
	v_mfma_f32_16x16x32_bf16 v[124:127], v[156:159], v[188:191], v[124:127]
	v_mfma_f32_16x16x32_bf16 v[120:123], v[164:167], v[188:191], v[120:123]
	v_mfma_f32_16x16x32_bf16 v[108:111], v[156:159], v[196:199], v[108:111]
	v_mfma_f32_16x16x32_bf16 v[104:107], v[164:167], v[196:199], v[104:107]
	v_mfma_f32_16x16x32_bf16 v[92:95], v[156:159], v[204:207], v[92:95]
	v_mfma_f32_16x16x32_bf16 v[88:91], v[164:167], v[204:207], v[88:91]
	v_mfma_f32_16x16x32_bf16 v[76:79], v[156:159], v[212:215], v[76:79]
	v_mfma_f32_16x16x32_bf16 v[72:75], v[164:167], v[212:215], v[72:75]
	v_mfma_f32_16x16x32_bf16 v[116:119], v[168:171], v[184:187], v[116:119]
	v_mfma_f32_16x16x32_bf16 v[112:115], v[176:179], v[184:187], v[112:115]
	v_mfma_f32_16x16x32_bf16 v[100:103], v[168:171], v[192:195], v[100:103]
	v_mfma_f32_16x16x32_bf16 v[96:99], v[176:179], v[192:195], v[96:99]
	v_mfma_f32_16x16x32_bf16 v[84:87], v[168:171], v[200:203], v[84:87]
	v_mfma_f32_16x16x32_bf16 v[80:83], v[176:179], v[200:203], v[80:83]
	v_mfma_f32_16x16x32_bf16 v[68:71], v[168:171], v[208:211], v[68:71]
	v_mfma_f32_16x16x32_bf16 v[64:67], v[176:179], v[208:211], v[64:67]
	v_mfma_f32_16x16x32_bf16 v[116:119], v[172:175], v[188:191], v[116:119]
	v_mfma_f32_16x16x32_bf16 v[112:115], v[180:183], v[188:191], v[112:115]
	v_mfma_f32_16x16x32_bf16 v[100:103], v[172:175], v[196:199], v[100:103]
	v_mfma_f32_16x16x32_bf16 v[96:99], v[180:183], v[196:199], v[96:99]
	v_mfma_f32_16x16x32_bf16 v[84:87], v[172:175], v[204:207], v[84:87]
	v_mfma_f32_16x16x32_bf16 v[80:83], v[180:183], v[204:207], v[80:83]
	v_mfma_f32_16x16x32_bf16 v[68:71], v[172:175], v[212:215], v[68:71]
	v_mfma_f32_16x16x32_bf16 v[64:67], v[180:183], v[212:215], v[64:67]
	s_barrier
	s_setprio 0
	s_add_i32 s28, s55, s33
	v_lshl_add_u64 v[216:217], v[216:217], 0, s[10:11]
	s_mov_b32 m0, s28
	ds_read_b128 v[184:187], v150 offset:49152
	ds_read_b128 v[188:191], v150 offset:50176
	ds_read_b128 v[192:195], v150 offset:51200
	ds_read_b128 v[196:199], v150 offset:52224
	ds_read_b128 v[200:203], v150 offset:53248
	ds_read_b128 v[204:207], v150 offset:54272
	ds_read_b128 v[208:211], v150 offset:55296
	ds_read_b128 v[212:215], v150 offset:56320
	global_load_lds_dwordx4 v[216:217], off
	s_add_i32 m0, s28, 0x2000
	s_add_u32 s26, s26, 0x40080
	v_lshl_add_u64 v[216:217], v[218:219], 0, s[10:11]
	s_addc_u32 s27, s27, 0
	s_add_i32 s28, s56, s33
	global_load_lds_dwordx4 v[216:217], off
	s_mov_b32 m0, s28
	s_nop 0
	global_load_lds_dwordx4 v132, s[26:27]
	s_add_i32 m0, s28, 0x2000
	s_nop 0
	global_load_lds_dwordx4 v128, s[26:27]
	v_lshl_add_u64 v[216:217], v[220:221], 0, s[10:11]
	s_mov_b32 m0, s42
	s_nop 0
	global_load_lds_dwordx4 v[216:217], off
	v_lshl_add_u64 v[216:217], v[222:223], 0, s[10:11]
	s_mov_b32 m0, s43
	s_nop 0
	global_load_lds_dwordx4 v[216:217], off
	s_waitcnt vmcnt(8)
	s_waitcnt lgkmcnt(0)
	s_setprio 1
	s_barrier
	v_mfma_f32_16x16x32_bf16 v[60:63], v[152:155], v[184:187], v[60:63]
	v_mfma_f32_16x16x32_bf16 v[56:59], v[160:163], v[184:187], v[56:59]
	v_mfma_f32_16x16x32_bf16 v[44:47], v[152:155], v[192:195], v[44:47]
	v_mfma_f32_16x16x32_bf16 v[40:43], v[160:163], v[192:195], v[40:43]
	v_mfma_f32_16x16x32_bf16 v[28:31], v[152:155], v[200:203], v[28:31]
	v_mfma_f32_16x16x32_bf16 v[24:27], v[160:163], v[200:203], v[24:27]
	v_mfma_f32_16x16x32_bf16 v[12:15], v[152:155], v[208:211], v[12:15]
	v_mfma_f32_16x16x32_bf16 v[8:11], v[160:163], v[208:211], v[8:11]
	v_mfma_f32_16x16x32_bf16 v[60:63], v[156:159], v[188:191], v[60:63]
	v_mfma_f32_16x16x32_bf16 v[56:59], v[164:167], v[188:191], v[56:59]
	v_mfma_f32_16x16x32_bf16 v[44:47], v[156:159], v[196:199], v[44:47]
	v_mfma_f32_16x16x32_bf16 v[40:43], v[164:167], v[196:199], v[40:43]
	v_mfma_f32_16x16x32_bf16 v[28:31], v[156:159], v[204:207], v[28:31]
	v_mfma_f32_16x16x32_bf16 v[24:27], v[164:167], v[204:207], v[24:27]
	v_mfma_f32_16x16x32_bf16 v[12:15], v[156:159], v[212:215], v[12:15]
	v_mfma_f32_16x16x32_bf16 v[8:11], v[164:167], v[212:215], v[8:11]
	v_mfma_f32_16x16x32_bf16 v[52:55], v[168:171], v[184:187], v[52:55]
	v_mfma_f32_16x16x32_bf16 v[48:51], v[176:179], v[184:187], v[48:51]
	v_mfma_f32_16x16x32_bf16 v[36:39], v[168:171], v[192:195], v[36:39]
	v_mfma_f32_16x16x32_bf16 v[32:35], v[176:179], v[192:195], v[32:35]
	v_mfma_f32_16x16x32_bf16 v[20:23], v[168:171], v[200:203], v[20:23]
	v_mfma_f32_16x16x32_bf16 v[16:19], v[176:179], v[200:203], v[16:19]
	v_mfma_f32_16x16x32_bf16 v[4:7], v[168:171], v[208:211], v[4:7]
	v_mfma_f32_16x16x32_bf16 v[0:3], v[176:179], v[208:211], v[0:3]
	v_mfma_f32_16x16x32_bf16 v[52:55], v[172:175], v[188:191], v[52:55]
	v_mfma_f32_16x16x32_bf16 v[48:51], v[180:183], v[188:191], v[48:51]
	v_mfma_f32_16x16x32_bf16 v[36:39], v[172:175], v[196:199], v[36:39]
	v_mfma_f32_16x16x32_bf16 v[32:35], v[180:183], v[196:199], v[32:35]
	v_mfma_f32_16x16x32_bf16 v[20:23], v[172:175], v[204:207], v[20:23]
	v_mfma_f32_16x16x32_bf16 v[16:19], v[180:183], v[204:207], v[16:19]
	v_mfma_f32_16x16x32_bf16 v[4:7], v[172:175], v[212:215], v[4:7]
	v_mfma_f32_16x16x32_bf16 v[0:3], v[180:183], v[212:215], v[0:3]
	s_barrier
	s_setprio 0
	s_add_i32 s54, s54, 2
	s_add_u32 s24, s24, 0x100
	s_addc_u32 s25, s25, 0
	s_add_u32 s52, s52, 0x100
	s_addc_u32 s53, s53, 0
	s_cmp_gt_u32 s54, 13
	s_cbranch_scc0 .LBB0_1219
	s_and_b64 vcc, exec, s[12:13]
	s_cbranch_vccz .LBB0_1222
	s_barrier
